# speedup vs baseline: 1.0173x; 1.0109x over previous
; __device__ __forceinline__ void prologue(const Frame& F, const Args& a) {
;     ...
;         for (int i = F.tid; i < 9 * DM; i += 512) { const float v = (i < 8 * DM) ? a.in[1][i] : a.in[3][i - 8 * DM]; sl[i] = v / (1.f + __expf(-v)); }
.LBB0_21:
	global_load_dword v100, v[2:3], off
	v_lshl_add_u64 v[2:3], v[2:3], 0, s[2:3]
	global_load_dword v101, v[2:3], off
	v_lshl_add_u64 v[2:3], v[2:3], 0, s[2:3]
	global_load_dword v102, v[2:3], off
	v_lshl_add_u64 v[2:3], v[2:3], 0, s[2:3]
	global_load_dword v103, v[2:3], off
	v_lshl_add_u64 v[2:3], v[2:3], 0, s[2:3]
	global_load_dword v104, v[2:3], off
	v_lshl_add_u64 v[2:3], v[2:3], 0, s[2:3]
	global_load_dword v105, v[2:3], off
	v_lshl_add_u64 v[2:3], v[2:3], 0, s[2:3]
	global_load_dword v106, v[2:3], off
	v_lshl_add_u64 v[2:3], v[2:3], 0, s[2:3]
	global_load_dword v107, v[2:3], off
	v_lshl_add_u64 v[2:3], v[2:3], 0, s[2:3]
	global_load_dword v108, v[2:3], off
	v_lshl_add_u64 v[2:3], v[2:3], 0, s[2:3]
	global_load_dword v109, v[2:3], off
	v_lshl_add_u64 v[2:3], v[2:3], 0, s[2:3]
	global_load_dword v110, v[2:3], off
	v_lshl_add_u64 v[2:3], v[2:3], 0, s[2:3]
	global_load_dword v111, v[2:3], off
	v_lshl_add_u64 v[2:3], v[2:3], 0, s[2:3]
	global_load_dword v112, v[2:3], off
	v_lshl_add_u64 v[2:3], v[2:3], 0, s[2:3]
	global_load_dword v113, v[2:3], off
	v_lshl_add_u64 v[2:3], v[2:3], 0, s[2:3]
	global_load_dword v114, v[2:3], off
	v_lshl_add_u64 v[2:3], v[2:3], 0, s[2:3]
	global_load_dword v115, v[2:3], off
	v_lshl_add_u64 v[2:3], v[2:3], 0, s[2:3]
	global_load_dword v116, v[2:3], off
	v_lshl_add_u64 v[2:3], v[2:3], 0, s[2:3]
	global_load_dword v117, v[2:3], off
	v_lshl_add_u64 v[2:3], v[2:3], 0, s[2:3]
	global_load_dword v118, v[2:3], off
	v_lshl_add_u64 v[2:3], v[2:3], 0, s[2:3]
	global_load_dword v119, v[2:3], off
	v_lshl_add_u64 v[2:3], v[2:3], 0, s[2:3]
	global_load_dword v120, v[2:3], off
	v_lshl_add_u64 v[2:3], v[2:3], 0, s[2:3]
	global_load_dword v121, v[2:3], off
	v_lshl_add_u64 v[2:3], v[2:3], 0, s[2:3]
	global_load_dword v122, v[2:3], off
	v_lshl_add_u64 v[2:3], v[2:3], 0, s[2:3]
	global_load_dword v123, v[2:3], off
	v_lshl_add_u64 v[2:3], v[2:3], 0, s[2:3]
	global_load_dword v124, v[2:3], off
	v_lshl_add_u64 v[2:3], v[2:3], 0, s[2:3]
	global_load_dword v125, v[2:3], off
	v_lshl_add_u64 v[2:3], v[2:3], 0, s[2:3]
	global_load_dword v126, v[2:3], off
	v_lshl_add_u64 v[2:3], v[2:3], 0, s[2:3]
	global_load_dword v127, v[2:3], off
	v_lshl_add_u64 v[2:3], v[2:3], 0, s[2:3]
	global_load_dword v128, v[2:3], off
	v_lshl_add_u64 v[2:3], v[2:3], 0, s[2:3]
	global_load_dword v129, v[2:3], off
	v_lshl_add_u64 v[2:3], v[2:3], 0, s[2:3]
	global_load_dword v130, v[2:3], off
	v_lshl_add_u64 v[2:3], v[2:3], 0, s[2:3]
	global_load_dword v131, v[2:3], off
	v_lshl_add_u64 v[2:3], v[2:3], 0, s[2:3]
	s_mov_b64 s[6:7], 0x10000
	v_lshl_add_u64 v[0:1], v[0:1], 0, s[6:7]
	global_load_dword v132, v[0:1], off
	v_lshl_add_u64 v[0:1], v[0:1], 0, s[2:3]
	global_load_dword v133, v[0:1], off
	v_lshl_add_u64 v[0:1], v[0:1], 0, s[2:3]
	global_load_dword v134, v[0:1], off
	v_lshl_add_u64 v[0:1], v[0:1], 0, s[2:3]
	global_load_dword v135, v[0:1], off
	v_lshl_add_u64 v[0:1], v[0:1], 0, s[2:3]
	s_waitcnt vmcnt(35)
	v_mov_b32_e32 v6, v100
	v_mul_f32_e32 v7, 0xbfb8aa3b, v6
	v_exp_f32_e32 v7, v7
	s_nop 0
	v_add_f32_e32 v7, 1.0, v7
	v_div_scale_f32 v8, s[54:55], v7, v7, v6
	v_rcp_f32_e32 v9, v8
	v_div_scale_f32 v10, vcc, v6, v7, v6
	v_fma_f32 v11, -v8, v9, 1.0
	v_fmac_f32_e32 v9, v11, v9
	v_mul_f32_e32 v11, v10, v9
	v_fma_f32 v12, -v8, v11, v10
	v_fmac_f32_e32 v11, v12, v9
	v_fma_f32 v8, -v8, v11, v10
	v_div_fmas_f32 v8, v8, v9, v11
	v_div_fixup_f32 v6, v8, v7, v6
	ds_write_b32 v4, v6
	v_add_u32_e32 v4, 0x800, v4
	s_waitcnt vmcnt(34)
	v_mov_b32_e32 v6, v101
	v_mul_f32_e32 v7, 0xbfb8aa3b, v6
	v_exp_f32_e32 v7, v7
	s_nop 0
	v_add_f32_e32 v7, 1.0, v7
	v_div_scale_f32 v8, s[54:55], v7, v7, v6
	v_rcp_f32_e32 v9, v8
	v_div_scale_f32 v10, vcc, v6, v7, v6
	v_fma_f32 v11, -v8, v9, 1.0
	v_fmac_f32_e32 v9, v11, v9
	v_mul_f32_e32 v11, v10, v9
	v_fma_f32 v12, -v8, v11, v10
	v_fmac_f32_e32 v11, v12, v9
	v_fma_f32 v8, -v8, v11, v10
	v_div_fmas_f32 v8, v8, v9, v11
	v_div_fixup_f32 v6, v8, v7, v6
	ds_write_b32 v4, v6
	v_add_u32_e32 v4, 0x800, v4
	s_waitcnt vmcnt(33)
	v_mov_b32_e32 v6, v102
	v_mul_f32_e32 v7, 0xbfb8aa3b, v6
	v_exp_f32_e32 v7, v7
	s_nop 0
	v_add_f32_e32 v7, 1.0, v7
	v_div_scale_f32 v8, s[54:55], v7, v7, v6
	v_rcp_f32_e32 v9, v8
	v_div_scale_f32 v10, vcc, v6, v7, v6
	v_fma_f32 v11, -v8, v9, 1.0
	v_fmac_f32_e32 v9, v11, v9
	v_mul_f32_e32 v11, v10, v9
	v_fma_f32 v12, -v8, v11, v10
	v_fmac_f32_e32 v11, v12, v9
	v_fma_f32 v8, -v8, v11, v10
	v_div_fmas_f32 v8, v8, v9, v11
	v_div_fixup_f32 v6, v8, v7, v6
	ds_write_b32 v4, v6
	v_add_u32_e32 v4, 0x800, v4
	s_waitcnt vmcnt(32)
	v_mov_b32_e32 v6, v103
	v_mul_f32_e32 v7, 0xbfb8aa3b, v6
	v_exp_f32_e32 v7, v7
	s_nop 0
	v_add_f32_e32 v7, 1.0, v7
	v_div_scale_f32 v8, s[54:55], v7, v7, v6
	v_rcp_f32_e32 v9, v8
	v_div_scale_f32 v10, vcc, v6, v7, v6
	v_fma_f32 v11, -v8, v9, 1.0
	v_fmac_f32_e32 v9, v11, v9
	v_mul_f32_e32 v11, v10, v9
	v_fma_f32 v12, -v8, v11, v10
	v_fmac_f32_e32 v11, v12, v9
	v_fma_f32 v8, -v8, v11, v10
	v_div_fmas_f32 v8, v8, v9, v11
	v_div_fixup_f32 v6, v8, v7, v6
	ds_write_b32 v4, v6
	v_add_u32_e32 v4, 0x800, v4
	s_waitcnt vmcnt(31)
	v_mov_b32_e32 v6, v104
	v_mul_f32_e32 v7, 0xbfb8aa3b, v6
	v_exp_f32_e32 v7, v7
	s_nop 0
	v_add_f32_e32 v7, 1.0, v7
	v_div_scale_f32 v8, s[54:55], v7, v7, v6
	v_rcp_f32_e32 v9, v8
	v_div_scale_f32 v10, vcc, v6, v7, v6
	v_fma_f32 v11, -v8, v9, 1.0
	v_fmac_f32_e32 v9, v11, v9
	v_mul_f32_e32 v11, v10, v9
	v_fma_f32 v12, -v8, v11, v10
	v_fmac_f32_e32 v11, v12, v9
	v_fma_f32 v8, -v8, v11, v10
	v_div_fmas_f32 v8, v8, v9, v11
	v_div_fixup_f32 v6, v8, v7, v6
	ds_write_b32 v4, v6
	v_add_u32_e32 v4, 0x800, v4
	s_waitcnt vmcnt(30)
; __device__ __forceinline__ void prologue(const Frame& F, const Args& a) {
;     ...
;         for (int i = F.tid; i < 9 * DM; i += 512) { const float v = (i < 8 * DM) ? a.in[1][i] : a.in[3][i - 8 * DM]; sl[i] = v / (1.f + __expf(-v)); }
	v_mov_b32_e32 v6, v105
	v_mul_f32_e32 v7, 0xbfb8aa3b, v6
	v_exp_f32_e32 v7, v7
	s_nop 0
	v_add_f32_e32 v7, 1.0, v7
	v_div_scale_f32 v8, s[54:55], v7, v7, v6
	v_rcp_f32_e32 v9, v8
	v_div_scale_f32 v10, vcc, v6, v7, v6
	v_fma_f32 v11, -v8, v9, 1.0
	v_fmac_f32_e32 v9, v11, v9
	v_mul_f32_e32 v11, v10, v9
	v_fma_f32 v12, -v8, v11, v10
	v_fmac_f32_e32 v11, v12, v9
	v_fma_f32 v8, -v8, v11, v10
	v_div_fmas_f32 v8, v8, v9, v11
	v_div_fixup_f32 v6, v8, v7, v6
	ds_write_b32 v4, v6
	v_add_u32_e32 v4, 0x800, v4
	s_waitcnt vmcnt(29)
	v_mov_b32_e32 v6, v106
	v_mul_f32_e32 v7, 0xbfb8aa3b, v6
	v_exp_f32_e32 v7, v7
	s_nop 0
	v_add_f32_e32 v7, 1.0, v7
	v_div_scale_f32 v8, s[54:55], v7, v7, v6
	v_rcp_f32_e32 v9, v8
	v_div_scale_f32 v10, vcc, v6, v7, v6
	v_fma_f32 v11, -v8, v9, 1.0
	v_fmac_f32_e32 v9, v11, v9
	v_mul_f32_e32 v11, v10, v9
	v_fma_f32 v12, -v8, v11, v10
	v_fmac_f32_e32 v11, v12, v9
	v_fma_f32 v8, -v8, v11, v10
	v_div_fmas_f32 v8, v8, v9, v11
	v_div_fixup_f32 v6, v8, v7, v6
	ds_write_b32 v4, v6
	v_add_u32_e32 v4, 0x800, v4
	s_waitcnt vmcnt(28)
	v_mov_b32_e32 v6, v107
	v_mul_f32_e32 v7, 0xbfb8aa3b, v6
	v_exp_f32_e32 v7, v7
	s_nop 0
	v_add_f32_e32 v7, 1.0, v7
	v_div_scale_f32 v8, s[54:55], v7, v7, v6
	v_rcp_f32_e32 v9, v8
	v_div_scale_f32 v10, vcc, v6, v7, v6
	v_fma_f32 v11, -v8, v9, 1.0
	v_fmac_f32_e32 v9, v11, v9
	v_mul_f32_e32 v11, v10, v9
	v_fma_f32 v12, -v8, v11, v10
	v_fmac_f32_e32 v11, v12, v9
	v_fma_f32 v8, -v8, v11, v10
	v_div_fmas_f32 v8, v8, v9, v11
	v_div_fixup_f32 v6, v8, v7, v6
	ds_write_b32 v4, v6
	v_add_u32_e32 v4, 0x800, v4
	s_waitcnt vmcnt(27)
	v_mov_b32_e32 v6, v108
	v_mul_f32_e32 v7, 0xbfb8aa3b, v6
	v_exp_f32_e32 v7, v7
	s_nop 0
	v_add_f32_e32 v7, 1.0, v7
	v_div_scale_f32 v8, s[54:55], v7, v7, v6
	v_rcp_f32_e32 v9, v8
	v_div_scale_f32 v10, vcc, v6, v7, v6
	v_fma_f32 v11, -v8, v9, 1.0
	v_fmac_f32_e32 v9, v11, v9
	v_mul_f32_e32 v11, v10, v9
	v_fma_f32 v12, -v8, v11, v10
	v_fmac_f32_e32 v11, v12, v9
	v_fma_f32 v8, -v8, v11, v10
	v_div_fmas_f32 v8, v8, v9, v11
	v_div_fixup_f32 v6, v8, v7, v6
	ds_write_b32 v4, v6
	v_add_u32_e32 v4, 0x800, v4
	s_waitcnt vmcnt(26)
	v_mov_b32_e32 v6, v109
	v_mul_f32_e32 v7, 0xbfb8aa3b, v6
	v_exp_f32_e32 v7, v7
	s_nop 0
	v_add_f32_e32 v7, 1.0, v7
	v_div_scale_f32 v8, s[54:55], v7, v7, v6
	v_rcp_f32_e32 v9, v8
	v_div_scale_f32 v10, vcc, v6, v7, v6
	v_fma_f32 v11, -v8, v9, 1.0
	v_fmac_f32_e32 v9, v11, v9
	v_mul_f32_e32 v11, v10, v9
	v_fma_f32 v12, -v8, v11, v10
	v_fmac_f32_e32 v11, v12, v9
	v_fma_f32 v8, -v8, v11, v10
	v_div_fmas_f32 v8, v8, v9, v11
	v_div_fixup_f32 v6, v8, v7, v6
	ds_write_b32 v4, v6
	v_add_u32_e32 v4, 0x800, v4
	s_waitcnt vmcnt(25)
	v_mov_b32_e32 v6, v110
	v_mul_f32_e32 v7, 0xbfb8aa3b, v6
	v_exp_f32_e32 v7, v7
	s_nop 0
	v_add_f32_e32 v7, 1.0, v7
	v_div_scale_f32 v8, s[54:55], v7, v7, v6
	v_rcp_f32_e32 v9, v8
	v_div_scale_f32 v10, vcc, v6, v7, v6
	v_fma_f32 v11, -v8, v9, 1.0
	v_fmac_f32_e32 v9, v11, v9
	v_mul_f32_e32 v11, v10, v9
	v_fma_f32 v12, -v8, v11, v10
	v_fmac_f32_e32 v11, v12, v9
	v_fma_f32 v8, -v8, v11, v10
	v_div_fmas_f32 v8, v8, v9, v11
	v_div_fixup_f32 v6, v8, v7, v6
	ds_write_b32 v4, v6
	v_add_u32_e32 v4, 0x800, v4
	s_waitcnt vmcnt(24)
	v_mov_b32_e32 v6, v111
	v_mul_f32_e32 v7, 0xbfb8aa3b, v6
	v_exp_f32_e32 v7, v7
	s_nop 0
	v_add_f32_e32 v7, 1.0, v7
	v_div_scale_f32 v8, s[54:55], v7, v7, v6
	v_rcp_f32_e32 v9, v8
	v_div_scale_f32 v10, vcc, v6, v7, v6
	v_fma_f32 v11, -v8, v9, 1.0
	v_fmac_f32_e32 v9, v11, v9
	v_mul_f32_e32 v11, v10, v9
	v_fma_f32 v12, -v8, v11, v10
	v_fmac_f32_e32 v11, v12, v9
	v_fma_f32 v8, -v8, v11, v10
	v_div_fmas_f32 v8, v8, v9, v11
	v_div_fixup_f32 v6, v8, v7, v6
	ds_write_b32 v4, v6
	v_add_u32_e32 v4, 0x800, v4
	s_waitcnt vmcnt(23)
	v_mov_b32_e32 v6, v112
	v_mul_f32_e32 v7, 0xbfb8aa3b, v6
	v_exp_f32_e32 v7, v7
	s_nop 0
	v_add_f32_e32 v7, 1.0, v7
	v_div_scale_f32 v8, s[54:55], v7, v7, v6
	v_rcp_f32_e32 v9, v8
	v_div_scale_f32 v10, vcc, v6, v7, v6
	v_fma_f32 v11, -v8, v9, 1.0
	v_fmac_f32_e32 v9, v11, v9
	v_mul_f32_e32 v11, v10, v9
	v_fma_f32 v12, -v8, v11, v10
	v_fmac_f32_e32 v11, v12, v9
	v_fma_f32 v8, -v8, v11, v10
	v_div_fmas_f32 v8, v8, v9, v11
	v_div_fixup_f32 v6, v8, v7, v6
	ds_write_b32 v4, v6
	v_add_u32_e32 v4, 0x800, v4
	s_waitcnt vmcnt(22)
	v_mov_b32_e32 v6, v113
	v_mul_f32_e32 v7, 0xbfb8aa3b, v6
	v_exp_f32_e32 v7, v7
	s_nop 0
	v_add_f32_e32 v7, 1.0, v7
	v_div_scale_f32 v8, s[54:55], v7, v7, v6
	v_rcp_f32_e32 v9, v8
	v_div_scale_f32 v10, vcc, v6, v7, v6
	v_fma_f32 v11, -v8, v9, 1.0
	v_fmac_f32_e32 v9, v11, v9
	v_mul_f32_e32 v11, v10, v9
	v_fma_f32 v12, -v8, v11, v10
	v_fmac_f32_e32 v11, v12, v9
	v_fma_f32 v8, -v8, v11, v10
	v_div_fmas_f32 v8, v8, v9, v11
	v_div_fixup_f32 v6, v8, v7, v6
	ds_write_b32 v4, v6
	v_add_u32_e32 v4, 0x800, v4
	s_waitcnt vmcnt(21)
	v_mov_b32_e32 v6, v114
	v_mul_f32_e32 v7, 0xbfb8aa3b, v6
	v_exp_f32_e32 v7, v7
	s_nop 0
	v_add_f32_e32 v7, 1.0, v7
	v_div_scale_f32 v8, s[54:55], v7, v7, v6
	v_rcp_f32_e32 v9, v8
	v_div_scale_f32 v10, vcc, v6, v7, v6
	v_fma_f32 v11, -v8, v9, 1.0
	v_fmac_f32_e32 v9, v11, v9
	v_mul_f32_e32 v11, v10, v9
	v_fma_f32 v12, -v8, v11, v10
	v_fmac_f32_e32 v11, v12, v9
	v_fma_f32 v8, -v8, v11, v10
	v_div_fmas_f32 v8, v8, v9, v11
	v_div_fixup_f32 v6, v8, v7, v6
	ds_write_b32 v4, v6
	v_add_u32_e32 v4, 0x800, v4
	s_waitcnt vmcnt(20)
	v_mov_b32_e32 v6, v115
	v_mul_f32_e32 v7, 0xbfb8aa3b, v6
	v_exp_f32_e32 v7, v7
	s_nop 0
	v_add_f32_e32 v7, 1.0, v7
	v_div_scale_f32 v8, s[54:55], v7, v7, v6
	v_rcp_f32_e32 v9, v8
	v_div_scale_f32 v10, vcc, v6, v7, v6
	v_fma_f32 v11, -v8, v9, 1.0
	v_fmac_f32_e32 v9, v11, v9
	v_mul_f32_e32 v11, v10, v9
	v_fma_f32 v12, -v8, v11, v10
	v_fmac_f32_e32 v11, v12, v9
	v_fma_f32 v8, -v8, v11, v10
	v_div_fmas_f32 v8, v8, v9, v11
	v_div_fixup_f32 v6, v8, v7, v6
	ds_write_b32 v4, v6
	v_add_u32_e32 v4, 0x800, v4
	s_waitcnt vmcnt(19)
; __device__ __forceinline__ void prologue(const Frame& F, const Args& a) {
;     ...
;         for (int i = F.tid; i < 9 * DM; i += 512) { const float v = (i < 8 * DM) ? a.in[1][i] : a.in[3][i - 8 * DM]; sl[i] = v / (1.f + __expf(-v)); }
	v_mov_b32_e32 v6, v116
	v_mul_f32_e32 v7, 0xbfb8aa3b, v6
	v_exp_f32_e32 v7, v7
	s_nop 0
	v_add_f32_e32 v7, 1.0, v7
	v_div_scale_f32 v8, s[54:55], v7, v7, v6
	v_rcp_f32_e32 v9, v8
	v_div_scale_f32 v10, vcc, v6, v7, v6
	v_fma_f32 v11, -v8, v9, 1.0
	v_fmac_f32_e32 v9, v11, v9
	v_mul_f32_e32 v11, v10, v9
	v_fma_f32 v12, -v8, v11, v10
	v_fmac_f32_e32 v11, v12, v9
	v_fma_f32 v8, -v8, v11, v10
	v_div_fmas_f32 v8, v8, v9, v11
	v_div_fixup_f32 v6, v8, v7, v6
	ds_write_b32 v4, v6
	v_add_u32_e32 v4, 0x800, v4
	s_waitcnt vmcnt(18)
	v_mov_b32_e32 v6, v117
	v_mul_f32_e32 v7, 0xbfb8aa3b, v6
	v_exp_f32_e32 v7, v7
	s_nop 0
	v_add_f32_e32 v7, 1.0, v7
	v_div_scale_f32 v8, s[54:55], v7, v7, v6
	v_rcp_f32_e32 v9, v8
	v_div_scale_f32 v10, vcc, v6, v7, v6
	v_fma_f32 v11, -v8, v9, 1.0
	v_fmac_f32_e32 v9, v11, v9
	v_mul_f32_e32 v11, v10, v9
	v_fma_f32 v12, -v8, v11, v10
	v_fmac_f32_e32 v11, v12, v9
	v_fma_f32 v8, -v8, v11, v10
	v_div_fmas_f32 v8, v8, v9, v11
	v_div_fixup_f32 v6, v8, v7, v6
	ds_write_b32 v4, v6
	v_add_u32_e32 v4, 0x800, v4
	s_waitcnt vmcnt(17)
	v_mov_b32_e32 v6, v118
	v_mul_f32_e32 v7, 0xbfb8aa3b, v6
	v_exp_f32_e32 v7, v7
	s_nop 0
	v_add_f32_e32 v7, 1.0, v7
	v_div_scale_f32 v8, s[54:55], v7, v7, v6
	v_rcp_f32_e32 v9, v8
	v_div_scale_f32 v10, vcc, v6, v7, v6
	v_fma_f32 v11, -v8, v9, 1.0
	v_fmac_f32_e32 v9, v11, v9
	v_mul_f32_e32 v11, v10, v9
	v_fma_f32 v12, -v8, v11, v10
	v_fmac_f32_e32 v11, v12, v9
	v_fma_f32 v8, -v8, v11, v10
	v_div_fmas_f32 v8, v8, v9, v11
	v_div_fixup_f32 v6, v8, v7, v6
	ds_write_b32 v4, v6
	v_add_u32_e32 v4, 0x800, v4
	s_waitcnt vmcnt(16)
	v_mov_b32_e32 v6, v119
	v_mul_f32_e32 v7, 0xbfb8aa3b, v6
	v_exp_f32_e32 v7, v7
	s_nop 0
	v_add_f32_e32 v7, 1.0, v7
	v_div_scale_f32 v8, s[54:55], v7, v7, v6
	v_rcp_f32_e32 v9, v8
	v_div_scale_f32 v10, vcc, v6, v7, v6
	v_fma_f32 v11, -v8, v9, 1.0
	v_fmac_f32_e32 v9, v11, v9
	v_mul_f32_e32 v11, v10, v9
	v_fma_f32 v12, -v8, v11, v10
	v_fmac_f32_e32 v11, v12, v9
	v_fma_f32 v8, -v8, v11, v10
	v_div_fmas_f32 v8, v8, v9, v11
	v_div_fixup_f32 v6, v8, v7, v6
	ds_write_b32 v4, v6
	v_add_u32_e32 v4, 0x800, v4
	s_waitcnt vmcnt(15)
	v_mov_b32_e32 v6, v120
	v_mul_f32_e32 v7, 0xbfb8aa3b, v6
	v_exp_f32_e32 v7, v7
	s_nop 0
	v_add_f32_e32 v7, 1.0, v7
	v_div_scale_f32 v8, s[54:55], v7, v7, v6
	v_rcp_f32_e32 v9, v8
	v_div_scale_f32 v10, vcc, v6, v7, v6
	v_fma_f32 v11, -v8, v9, 1.0
	v_fmac_f32_e32 v9, v11, v9
	v_mul_f32_e32 v11, v10, v9
	v_fma_f32 v12, -v8, v11, v10
	v_fmac_f32_e32 v11, v12, v9
	v_fma_f32 v8, -v8, v11, v10
	v_div_fmas_f32 v8, v8, v9, v11
	v_div_fixup_f32 v6, v8, v7, v6
	ds_write_b32 v4, v6
	v_add_u32_e32 v4, 0x800, v4
	s_waitcnt vmcnt(14)
	v_mov_b32_e32 v6, v121
	v_mul_f32_e32 v7, 0xbfb8aa3b, v6
	v_exp_f32_e32 v7, v7
	s_nop 0
	v_add_f32_e32 v7, 1.0, v7
	v_div_scale_f32 v8, s[54:55], v7, v7, v6
	v_rcp_f32_e32 v9, v8
	v_div_scale_f32 v10, vcc, v6, v7, v6
	v_fma_f32 v11, -v8, v9, 1.0
	v_fmac_f32_e32 v9, v11, v9
	v_mul_f32_e32 v11, v10, v9
	v_fma_f32 v12, -v8, v11, v10
	v_fmac_f32_e32 v11, v12, v9
	v_fma_f32 v8, -v8, v11, v10
	v_div_fmas_f32 v8, v8, v9, v11
	v_div_fixup_f32 v6, v8, v7, v6
	ds_write_b32 v4, v6
	v_add_u32_e32 v4, 0x800, v4
	s_waitcnt vmcnt(13)
	v_mov_b32_e32 v6, v122
	v_mul_f32_e32 v7, 0xbfb8aa3b, v6
	v_exp_f32_e32 v7, v7
	s_nop 0
	v_add_f32_e32 v7, 1.0, v7
	v_div_scale_f32 v8, s[54:55], v7, v7, v6
	v_rcp_f32_e32 v9, v8
	v_div_scale_f32 v10, vcc, v6, v7, v6
	v_fma_f32 v11, -v8, v9, 1.0
	v_fmac_f32_e32 v9, v11, v9
	v_mul_f32_e32 v11, v10, v9
	v_fma_f32 v12, -v8, v11, v10
	v_fmac_f32_e32 v11, v12, v9
	v_fma_f32 v8, -v8, v11, v10
	v_div_fmas_f32 v8, v8, v9, v11
	v_div_fixup_f32 v6, v8, v7, v6
	ds_write_b32 v4, v6
	v_add_u32_e32 v4, 0x800, v4
	s_waitcnt vmcnt(12)
	v_mov_b32_e32 v6, v123
	v_mul_f32_e32 v7, 0xbfb8aa3b, v6
	v_exp_f32_e32 v7, v7
	s_nop 0
	v_add_f32_e32 v7, 1.0, v7
	v_div_scale_f32 v8, s[54:55], v7, v7, v6
	v_rcp_f32_e32 v9, v8
	v_div_scale_f32 v10, vcc, v6, v7, v6
	v_fma_f32 v11, -v8, v9, 1.0
	v_fmac_f32_e32 v9, v11, v9
	v_mul_f32_e32 v11, v10, v9
	v_fma_f32 v12, -v8, v11, v10
	v_fmac_f32_e32 v11, v12, v9
	v_fma_f32 v8, -v8, v11, v10
	v_div_fmas_f32 v8, v8, v9, v11
	v_div_fixup_f32 v6, v8, v7, v6
	ds_write_b32 v4, v6
	v_add_u32_e32 v4, 0x800, v4
	s_waitcnt vmcnt(11)
	v_mov_b32_e32 v6, v124
	v_mul_f32_e32 v7, 0xbfb8aa3b, v6
	v_exp_f32_e32 v7, v7
	s_nop 0
	v_add_f32_e32 v7, 1.0, v7
	v_div_scale_f32 v8, s[54:55], v7, v7, v6
	v_rcp_f32_e32 v9, v8
	v_div_scale_f32 v10, vcc, v6, v7, v6
	v_fma_f32 v11, -v8, v9, 1.0
	v_fmac_f32_e32 v9, v11, v9
	v_mul_f32_e32 v11, v10, v9
	v_fma_f32 v12, -v8, v11, v10
	v_fmac_f32_e32 v11, v12, v9
	v_fma_f32 v8, -v8, v11, v10
	v_div_fmas_f32 v8, v8, v9, v11
	v_div_fixup_f32 v6, v8, v7, v6
	ds_write_b32 v4, v6
	v_add_u32_e32 v4, 0x800, v4
	s_waitcnt vmcnt(10)
	v_mov_b32_e32 v6, v125
	v_mul_f32_e32 v7, 0xbfb8aa3b, v6
	v_exp_f32_e32 v7, v7
	s_nop 0
	v_add_f32_e32 v7, 1.0, v7
	v_div_scale_f32 v8, s[54:55], v7, v7, v6
	v_rcp_f32_e32 v9, v8
	v_div_scale_f32 v10, vcc, v6, v7, v6
	v_fma_f32 v11, -v8, v9, 1.0
	v_fmac_f32_e32 v9, v11, v9
	v_mul_f32_e32 v11, v10, v9
	v_fma_f32 v12, -v8, v11, v10
	v_fmac_f32_e32 v11, v12, v9
	v_fma_f32 v8, -v8, v11, v10
	v_div_fmas_f32 v8, v8, v9, v11
	v_div_fixup_f32 v6, v8, v7, v6
	ds_write_b32 v4, v6
	v_add_u32_e32 v4, 0x800, v4
	s_waitcnt vmcnt(9)
; __device__ __forceinline__ void prologue(const Frame& F, const Args& a) {
;     ...
;         for (int i = F.tid; i < 9 * DM; i += 512) { const float v = (i < 8 * DM) ? a.in[1][i] : a.in[3][i - 8 * DM]; sl[i] = v / (1.f + __expf(-v)); }
;         __syncthreads();
;         unsigned long long* modi = (unsigned long long*)(ws + WS_MODI);
;         for (int item = gw; item < 1536; item += NGW) {
	v_mov_b32_e32 v6, v126
	v_mul_f32_e32 v7, 0xbfb8aa3b, v6
	v_exp_f32_e32 v7, v7
	s_nop 0
	v_add_f32_e32 v7, 1.0, v7
	v_div_scale_f32 v8, s[54:55], v7, v7, v6
	v_rcp_f32_e32 v9, v8
	v_div_scale_f32 v10, vcc, v6, v7, v6
	v_fma_f32 v11, -v8, v9, 1.0
	v_fmac_f32_e32 v9, v11, v9
	v_mul_f32_e32 v11, v10, v9
	v_fma_f32 v12, -v8, v11, v10
	v_fmac_f32_e32 v11, v12, v9
	v_fma_f32 v8, -v8, v11, v10
	v_div_fmas_f32 v8, v8, v9, v11
	v_div_fixup_f32 v6, v8, v7, v6
	ds_write_b32 v4, v6
	v_add_u32_e32 v4, 0x800, v4
	s_waitcnt vmcnt(8)
	v_mov_b32_e32 v6, v127
	v_mul_f32_e32 v7, 0xbfb8aa3b, v6
	v_exp_f32_e32 v7, v7
	s_nop 0
	v_add_f32_e32 v7, 1.0, v7
	v_div_scale_f32 v8, s[54:55], v7, v7, v6
	v_rcp_f32_e32 v9, v8
	v_div_scale_f32 v10, vcc, v6, v7, v6
	v_fma_f32 v11, -v8, v9, 1.0
	v_fmac_f32_e32 v9, v11, v9
	v_mul_f32_e32 v11, v10, v9
	v_fma_f32 v12, -v8, v11, v10
	v_fmac_f32_e32 v11, v12, v9
	v_fma_f32 v8, -v8, v11, v10
	v_div_fmas_f32 v8, v8, v9, v11
	v_div_fixup_f32 v6, v8, v7, v6
	ds_write_b32 v4, v6
	v_add_u32_e32 v4, 0x800, v4
	s_waitcnt vmcnt(7)
	v_mov_b32_e32 v6, v128
	v_mul_f32_e32 v7, 0xbfb8aa3b, v6
	v_exp_f32_e32 v7, v7
	s_nop 0
	v_add_f32_e32 v7, 1.0, v7
	v_div_scale_f32 v8, s[54:55], v7, v7, v6
	v_rcp_f32_e32 v9, v8
	v_div_scale_f32 v10, vcc, v6, v7, v6
	v_fma_f32 v11, -v8, v9, 1.0
	v_fmac_f32_e32 v9, v11, v9
	v_mul_f32_e32 v11, v10, v9
	v_fma_f32 v12, -v8, v11, v10
	v_fmac_f32_e32 v11, v12, v9
	v_fma_f32 v8, -v8, v11, v10
	v_div_fmas_f32 v8, v8, v9, v11
	v_div_fixup_f32 v6, v8, v7, v6
	ds_write_b32 v4, v6
	v_add_u32_e32 v4, 0x800, v4
	s_waitcnt vmcnt(6)
	v_mov_b32_e32 v6, v129
	v_mul_f32_e32 v7, 0xbfb8aa3b, v6
	v_exp_f32_e32 v7, v7
	s_nop 0
	v_add_f32_e32 v7, 1.0, v7
	v_div_scale_f32 v8, s[54:55], v7, v7, v6
	v_rcp_f32_e32 v9, v8
	v_div_scale_f32 v10, vcc, v6, v7, v6
	v_fma_f32 v11, -v8, v9, 1.0
	v_fmac_f32_e32 v9, v11, v9
	v_mul_f32_e32 v11, v10, v9
	v_fma_f32 v12, -v8, v11, v10
	v_fmac_f32_e32 v11, v12, v9
	v_fma_f32 v8, -v8, v11, v10
	v_div_fmas_f32 v8, v8, v9, v11
	v_div_fixup_f32 v6, v8, v7, v6
	ds_write_b32 v4, v6
	v_add_u32_e32 v4, 0x800, v4
	s_waitcnt vmcnt(5)
	v_mov_b32_e32 v6, v130
	v_mul_f32_e32 v7, 0xbfb8aa3b, v6
	v_exp_f32_e32 v7, v7
	s_nop 0
	v_add_f32_e32 v7, 1.0, v7
	v_div_scale_f32 v8, s[54:55], v7, v7, v6
	v_rcp_f32_e32 v9, v8
	v_div_scale_f32 v10, vcc, v6, v7, v6
	v_fma_f32 v11, -v8, v9, 1.0
	v_fmac_f32_e32 v9, v11, v9
	v_mul_f32_e32 v11, v10, v9
	v_fma_f32 v12, -v8, v11, v10
	v_fmac_f32_e32 v11, v12, v9
	v_fma_f32 v8, -v8, v11, v10
	v_div_fmas_f32 v8, v8, v9, v11
	v_div_fixup_f32 v6, v8, v7, v6
	ds_write_b32 v4, v6
	v_add_u32_e32 v4, 0x800, v4
	s_waitcnt vmcnt(4)
	v_mov_b32_e32 v6, v131
	v_mul_f32_e32 v7, 0xbfb8aa3b, v6
	v_exp_f32_e32 v7, v7
	s_nop 0
	v_add_f32_e32 v7, 1.0, v7
	v_div_scale_f32 v8, s[54:55], v7, v7, v6
	v_rcp_f32_e32 v9, v8
	v_div_scale_f32 v10, vcc, v6, v7, v6
	v_fma_f32 v11, -v8, v9, 1.0
	v_fmac_f32_e32 v9, v11, v9
	v_mul_f32_e32 v11, v10, v9
	v_fma_f32 v12, -v8, v11, v10
	v_fmac_f32_e32 v11, v12, v9
	v_fma_f32 v8, -v8, v11, v10
	v_div_fmas_f32 v8, v8, v9, v11
	v_div_fixup_f32 v6, v8, v7, v6
	ds_write_b32 v4, v6
	v_add_u32_e32 v4, 0x800, v4
	s_waitcnt vmcnt(3)
	v_mov_b32_e32 v6, v132
	v_mul_f32_e32 v7, 0xbfb8aa3b, v6
	v_exp_f32_e32 v7, v7
	s_nop 0
	v_add_f32_e32 v7, 1.0, v7
	v_div_scale_f32 v8, s[54:55], v7, v7, v6
	v_rcp_f32_e32 v9, v8
	v_div_scale_f32 v10, vcc, v6, v7, v6
	v_fma_f32 v11, -v8, v9, 1.0
	v_fmac_f32_e32 v9, v11, v9
	v_mul_f32_e32 v11, v10, v9
	v_fma_f32 v12, -v8, v11, v10
	v_fmac_f32_e32 v11, v12, v9
	v_fma_f32 v8, -v8, v11, v10
	v_div_fmas_f32 v8, v8, v9, v11
	v_div_fixup_f32 v6, v8, v7, v6
	ds_write_b32 v4, v6
	v_add_u32_e32 v4, 0x800, v4
	s_waitcnt vmcnt(2)
	v_mov_b32_e32 v6, v133
	v_mul_f32_e32 v7, 0xbfb8aa3b, v6
	v_exp_f32_e32 v7, v7
	s_nop 0
	v_add_f32_e32 v7, 1.0, v7
	v_div_scale_f32 v8, s[54:55], v7, v7, v6
	v_rcp_f32_e32 v9, v8
	v_div_scale_f32 v10, vcc, v6, v7, v6
	v_fma_f32 v11, -v8, v9, 1.0
	v_fmac_f32_e32 v9, v11, v9
	v_mul_f32_e32 v11, v10, v9
	v_fma_f32 v12, -v8, v11, v10
	v_fmac_f32_e32 v11, v12, v9
	v_fma_f32 v8, -v8, v11, v10
	v_div_fmas_f32 v8, v8, v9, v11
	v_div_fixup_f32 v6, v8, v7, v6
	ds_write_b32 v4, v6
	v_add_u32_e32 v4, 0x800, v4
	s_waitcnt vmcnt(1)
	v_mov_b32_e32 v6, v134
	v_mul_f32_e32 v7, 0xbfb8aa3b, v6
	v_exp_f32_e32 v7, v7
	s_nop 0
	v_add_f32_e32 v7, 1.0, v7
	v_div_scale_f32 v8, s[54:55], v7, v7, v6
	v_rcp_f32_e32 v9, v8
	v_div_scale_f32 v10, vcc, v6, v7, v6
	v_fma_f32 v11, -v8, v9, 1.0
	v_fmac_f32_e32 v9, v11, v9
	v_mul_f32_e32 v11, v10, v9
	v_fma_f32 v12, -v8, v11, v10
	v_fmac_f32_e32 v11, v12, v9
	v_fma_f32 v8, -v8, v11, v10
	v_div_fmas_f32 v8, v8, v9, v11
	v_div_fixup_f32 v6, v8, v7, v6
	ds_write_b32 v4, v6
	v_add_u32_e32 v4, 0x800, v4
	s_waitcnt vmcnt(0)
	v_mov_b32_e32 v6, v135
	v_mul_f32_e32 v7, 0xbfb8aa3b, v6
	v_exp_f32_e32 v7, v7
	s_nop 0
	v_add_f32_e32 v7, 1.0, v7
	v_div_scale_f32 v8, s[54:55], v7, v7, v6
	v_rcp_f32_e32 v9, v8
	v_div_scale_f32 v10, vcc, v6, v7, v6
	v_fma_f32 v11, -v8, v9, 1.0
	v_fmac_f32_e32 v9, v11, v9
	v_mul_f32_e32 v11, v10, v9
	v_fma_f32 v12, -v8, v11, v10
	v_fmac_f32_e32 v11, v12, v9
	v_fma_f32 v8, -v8, v11, v10
	v_div_fmas_f32 v8, v8, v9, v11
	v_div_fixup_f32 v6, v8, v7, v6
	ds_write_b32 v4, v6
	v_add_u32_e32 v4, 0x800, v4
	s_or_b64 exec, exec, s[0:1]
	s_lshl_b32 s0, s33, 3
	s_add_i32 s74, s0, s84
	s_lshl_b32 s75, s28, 3
	s_cmpk_gt_i32 s74, 0x5ff
	s_waitcnt lgkmcnt(0)
	s_barrier
	s_cbranch_scc1 .LBB0_29
	s_add_u32 s0, s50, 0x200000
	s_addc_u32 s1, s51, 0
	s_mov_b64 s[2:3], 0x60000
	s_mov_b32 s9, 0x2f800000
	s_mov_b32 s10, 0xcf800000
	v_mov_b32_e32 v12, 0x18000
	s_mov_b32 s11, s74
	s_branch .LBB0_25

; __device__ __forceinline__ unsigned pk_bf16(float lo, float hi) { f32x2 v = {lo, hi}; bf16x2_t b = __builtin_convertvector(v, bf16x2_t); return __builtin_bit_cast(unsigned, b); }
; __device__ __forceinline__ f32x4 unpack4(u32x2 w) { return (f32x4){bf_lo(w.x), bf_hi(w.x), bf_lo(w.y), bf_hi(w.y)}; }
;     __device__ __forceinline__ void operator()(const f32x4 (&acc)[2][2][4][2], const Unit& u, int wr, int wc, int fr, int fq) const {
;         const int rowl = u.pm * BM + wr * 64 + fr, b = u.pm >> 3;
;         const int c0 = u.pn * BM + wc * 32 + 4 * fq;
;         f32x4 gv[2][2];
; #pragma unroll
;         for (int bj = 0; bj < 2; ++bj)
; #pragma unroll
;             for (int n = 0; n < 2; ++n) gv[bj][n] = *(const f32x4*)(gate + (size_t)b * NMOD + c0 + bj * HALF + n * 16);
; #pragma unroll
;         for (int ai = 0; ai < 2; ++ai)
; #pragma unroll
;             for (int m = 0; m < 4; ++m) { const int rr = rowl + ai * HALF + m * 16;
; #pragma unroll
;                 for (int bj = 0; bj < 2; ++bj)
; #pragma unroll
;                     for (int n = 0; n < 2; ++n) { const int c = c0 + bj * HALF + n * 16; char* xp = (char*)xr + blk_off(rr, c, DM / 64);
;                         const f32x4 bs = base_f32 ? *(const f32x4*)(base_f32 + (size_t)rr * DM + c) : unpack4(*(const u32x2*)xp);
;                         const f32x4 o = bs + gv[bj][n] * acc[ai][bj][m][n];
;                         u32x2 w; w.x = pk_bf16(o[0], o[1]); w.y = pk_bf16(o[2], o[3]);
;                         *(u32x2*)xp = w; } }
.LBB0_1100:
	s_lshl_b32 s9, s24, 8
	s_add_i32 s9, s9, s86
	v_or_b32_e32 v184, s9, v177
	s_ashr_i32 s6, s24, 3
	v_lshl_or_b32 v172, s95, 8, v180
	v_lshlrev_b32_e32 v88, 6, v184
	s_mul_hi_i32 s7, s6, 0xc000
	s_mul_i32 s6, s6, 0xc000
	v_and_b32_e32 v194, 0x3c0, v88
	v_ashrrev_i32_e32 v88, 6, v172
	s_add_u32 s6, s82, s6
	v_ashrrev_i32_e32 v89, 31, v88
	s_addc_u32 s7, s83, s7
	s_ashr_i32 s34, s9, 7
	v_lshlrev_b64 v[88:89], 14, v[88:89]
	s_ashr_i32 s35, s34, 31
	v_lshl_add_u64 v[158:159], s[10:11], 0, v[88:89]
	v_lshlrev_b32_e32 v88, 2, v184
	s_lshl_b64 s[64:65], s[34:35], 19
	v_lshlrev_b32_e32 v90, 1, v172
	v_and_b32_e32 v195, 32, v88
	v_and_b32_e32 v185, 16, v90
	v_lshl_add_u64 v[160:161], v[158:159], 0, s[64:65]
	v_or_b32_e32 v190, v195, v194
	v_lshl_add_u64 v[168:169], v[160:161], 0, s[52:53]
	v_or_b32_e32 v162, v190, v185
	v_mov_b32_e32 v163, v153
	v_and_b32_e32 v152, 8, v90
	v_lshl_add_u64 v[88:89], v[168:169], 0, v[162:163]
	v_lshl_add_u64 v[170:171], v[88:89], 0, v[152:153]
	v_ashrrev_i32_e32 v173, 31, v172
	v_mov_b32_e32 v240, v172
	v_mov_b32_e32 v241, v173
	v_mov_b32_e32 v238, v190
	v_mov_b32_e32 v239, v191
	v_mov_b32_e32 v236, v194
	v_mov_b32_e32 v237, v195
	global_load_dwordx2 v[198:199], v[170:171], off
	v_or_b32_e32 v202, 32, v185
	v_mov_b32_e32 v205, v153
	v_bitop3_b32 v204, v194, v195, v202 bitop3:0x36
	v_lshl_add_u64 v[206:207], v[168:169], 0, v[204:205]
	v_lshl_add_u64 v[208:209], v[206:207], 0, v[152:153]
	global_load_dwordx2 v[200:201], v[208:209], off
	s_waitcnt vmcnt(0)
	v_mov_b32_e32 v174, v198
	v_mov_b32_e32 v175, v199
	v_lshl_add_u64 v[88:89], v[172:173], 2, s[6:7]
	global_load_dwordx4 v[112:115], v[88:89], off
	v_or_b32_e32 v186, 32, v185
	v_mov_b32_e32 v167, v153
	v_bitop3_b32 v166, v194, v195, v186 bitop3:0x36
	v_lshl_add_u64 v[168:169], v[168:169], 0, v[166:167]
	v_lshl_add_u64 v[188:189], v[168:169], 0, v[152:153]
	global_load_dwordx4 v[108:111], v[88:89], off offset:64
	global_load_dwordx4 v[96:99], v[88:89], off offset:512
	s_nop 0
	global_load_dwordx4 v[88:91], v[88:89], off offset:576
	v_mov_b32_e32 v173, v153
	s_or_b32 s6, s9, 16
	s_lshr_b32 s6, s6, 3
	s_and_b32 s6, s6, 10
	s_or_b32 s6, s6, s89
	s_lshl_b32 s24, s6, 10
	s_or_b32 s6, s9, 32
	s_lshr_b32 s6, s6, 3
	s_and_b32 s6, s6, 12
	s_or_b32 s6, s6, s89
	s_andn2_b64 vcc, exec, s[2:3]
	s_mov_b64 s[2:3], -1
	s_waitcnt vmcnt(0)
	v_lshlrev_b32_e32 v168, 16, v174
	v_and_b32_e32 v169, 0xffff0000, v174
	v_lshlrev_b32_e32 v174, 16, v175
	v_and_b32_e32 v175, 0xffff0000, v175
	v_pk_fma_f32 v[142:143], v[142:143], v[114:115], v[174:175]
	v_pk_fma_f32 v[140:141], v[140:141], v[112:113], v[168:169]
	v_mov_b32_e32 v169, v153
	v_cvt_pk_bf16_f32 v140, v140, v141
	v_cvt_pk_bf16_f32 v141, v142, v143
	global_store_dwordx2 v[170:171], v[140:141], off
	v_mov_b32_e32 v174, v200
	v_mov_b32_e32 v175, v201
	v_or_b32_e32 v140, 0x80, v172
	v_ashrrev_i32_e32 v142, 6, v140
	v_ashrrev_i32_e32 v143, 31, v142
	v_lshlrev_b64 v[142:143], 14, v[142:143]
	v_lshlrev_b32_e32 v168, 1, v140
	v_lshl_add_u64 v[142:143], s[10:11], 0, v[142:143]
	v_and_b32_e32 v187, 16, v168
	v_lshl_add_u64 v[170:171], v[142:143], 0, s[64:65]
	v_and_b32_e32 v140, 8, v168
	v_or_b32_e32 v168, v190, v187
	v_lshl_add_u64 v[190:191], v[170:171], 0, s[52:53]
	v_mov_b32_e32 v141, v153
	v_lshl_add_u64 v[190:191], v[190:191], 0, v[168:169]
	v_lshl_add_u64 v[190:191], v[190:191], 0, v[140:141]
	v_lshlrev_b32_e32 v192, 16, v174
	v_and_b32_e32 v193, 0xffff0000, v174
	v_lshlrev_b32_e32 v174, 16, v175
	v_and_b32_e32 v175, 0xffff0000, v175
	v_pk_fma_f32 v[138:139], v[138:139], v[110:111], v[174:175]
	v_pk_fma_f32 v[136:137], v[136:137], v[108:109], v[192:193]
	s_nop 0
	v_cvt_pk_bf16_f32 v136, v136, v137
	v_cvt_pk_bf16_f32 v137, v138, v139
	global_store_dwordx2 v[188:189], v[136:137], off
	v_mov_b32_e32 v203, v153
	v_mov_b32_e32 v205, v153
	v_or_b32_e32 v206, 0x80, v240
	v_ashrrev_i32_e32 v208, 6, v206
	v_ashrrev_i32_e32 v209, 31, v208
	v_lshlrev_b64 v[208:209], 14, v[208:209]
	v_lshlrev_b32_e32 v204, 1, v206
	v_lshl_add_u64 v[208:209], s[10:11], 0, v[208:209]
	v_and_b32_e32 v215, 16, v204
	v_lshl_add_u64 v[216:217], v[208:209], 0, s[64:65]
	v_and_b32_e32 v206, 8, v204
	v_or_b32_e32 v204, v238, v215
	v_lshl_add_u64 v[218:219], v[216:217], 0, s[52:53]
	v_mov_b32_e32 v207, v153
	v_lshl_add_u64 v[218:219], v[218:219], 0, v[204:205]
	v_lshl_add_u64 v[218:219], v[218:219], 0, v[206:207]
	global_load_dwordx2 v[198:199], v[218:219], off
	v_or_b32_e32 v224, 0x90, v240
	v_ashrrev_i32_e32 v226, 6, v224
	v_ashrrev_i32_e32 v227, 31, v226
	v_lshlrev_b64 v[226:227], 14, v[226:227]
	v_lshlrev_b32_e32 v202, 1, v224
	v_lshl_add_u64 v[226:227], s[10:11], 0, v[226:227]
	v_and_b32_e32 v228, 48, v202
	v_lshl_add_u64 v[230:231], v[226:227], 0, s[64:65]
	v_and_b32_e32 v224, 8, v202
	v_bitop3_b32 v202, v236, v237, v228 bitop3:0x36
	v_lshl_add_u64 v[232:233], v[230:231], 0, s[52:53]
	v_mov_b32_e32 v225, v153
	v_lshl_add_u64 v[232:233], v[232:233], 0, v[202:203]
	v_lshl_add_u64 v[232:233], v[232:233], 0, v[224:225]
	global_load_dwordx2 v[200:201], v[232:233], off
	s_waitcnt vmcnt(0)
; __device__ __forceinline__ unsigned pk_bf16(float lo, float hi) { f32x2 v = {lo, hi}; bf16x2_t b = __builtin_convertvector(v, bf16x2_t); return __builtin_bit_cast(unsigned, b); }
; __device__ __forceinline__ f32x4 unpack4(u32x2 w) { return (f32x4){bf_lo(w.x), bf_hi(w.x), bf_lo(w.y), bf_hi(w.y)}; }
;     __device__ __forceinline__ void operator()(const f32x4 (&acc)[2][2][4][2], const Unit& u, int wr, int wc, int fr, int fq) const {
;     ...
;             for (int m = 0; m < 4; ++m) { const int rr = rowl + ai * HALF + m * 16;
; #pragma unroll
;                 for (int bj = 0; bj < 2; ++bj)
; #pragma unroll
;                     for (int n = 0; n < 2; ++n) { const int c = c0 + bj * HALF + n * 16; char* xp = (char*)xr + blk_off(rr, c, DM / 64);
;                         const f32x4 bs = base_f32 ? *(const f32x4*)(base_f32 + (size_t)rr * DM + c) : unpack4(*(const u32x2*)xp);
;                         const f32x4 o = bs + gv[bj][n] * acc[ai][bj][m][n];
;                         u32x2 w; w.x = pk_bf16(o[0], o[1]); w.y = pk_bf16(o[2], o[3]);
;                         *(u32x2*)xp = w; } }
	v_mov_b32_e32 v192, v198
	v_mov_b32_e32 v193, v199
	v_or_b32_e32 v136, 0x90, v172
	v_ashrrev_i32_e32 v138, 6, v136
	v_ashrrev_i32_e32 v139, 31, v138
	v_lshlrev_b64 v[138:139], 14, v[138:139]
	v_lshlrev_b32_e32 v172, 1, v136
	v_lshl_add_u64 v[138:139], s[10:11], 0, v[138:139]
	v_and_b32_e32 v188, 48, v172
	v_lshl_add_u64 v[174:175], v[138:139], 0, s[64:65]
	v_and_b32_e32 v136, 8, v172
	v_bitop3_b32 v172, v194, v195, v188 bitop3:0x36
	v_lshl_add_u64 v[194:195], v[174:175], 0, s[52:53]
	v_mov_b32_e32 v137, v153
	v_lshl_add_u64 v[194:195], v[194:195], 0, v[172:173]
	v_lshl_add_u64 v[194:195], v[194:195], 0, v[136:137]
	v_lshlrev_b32_e32 v196, 16, v192
	v_and_b32_e32 v197, 0xffff0000, v192
	v_lshlrev_b32_e32 v192, 16, v193
	v_and_b32_e32 v193, 0xffff0000, v193
	v_pk_fma_f32 v[134:135], v[134:135], v[98:99], v[192:193]
	v_pk_fma_f32 v[132:133], v[132:133], v[96:97], v[196:197]
	s_nop 0
	v_cvt_pk_bf16_f32 v132, v132, v133
	v_cvt_pk_bf16_f32 v133, v134, v135
	global_store_dwordx2 v[190:191], v[132:133], off
	v_mov_b32_e32 v132, v200
	v_mov_b32_e32 v133, v201
	v_lshl_add_u64 v[134:135], v[160:161], 0, s[24:25]
	v_lshl_add_u64 v[190:191], v[134:135], 0, v[162:163]
	v_lshl_add_u64 v[190:191], v[190:191], 0, v[152:153]
	v_lshlrev_b32_e32 v192, 16, v132
	v_and_b32_e32 v193, 0xffff0000, v132
	v_lshlrev_b32_e32 v132, 16, v133
	v_and_b32_e32 v133, 0xffff0000, v133
	v_pk_fma_f32 v[130:131], v[130:131], v[90:91], v[132:133]
	v_pk_fma_f32 v[128:129], v[128:129], v[88:89], v[192:193]
	s_nop 0
	v_cvt_pk_bf16_f32 v128, v128, v129
	v_cvt_pk_bf16_f32 v129, v130, v131
	global_store_dwordx2 v[194:195], v[128:129], off
	s_mov_b32 s101, s25
	v_or_b32_e32 v202, 32, v185
	v_mov_b32_e32 v205, v153
	v_bitop3_b32 v204, v236, v237, v202 bitop3:0x36
	s_or_b32 s98, s9, 16
	s_lshr_b32 s98, s98, 3
	s_and_b32 s98, s98, 10
	s_or_b32 s98, s98, s89
	s_lshl_b32 s100, s98, 10
	v_lshl_add_u64 v[206:207], v[160:161], 0, s[100:101]
	v_lshl_add_u64 v[208:209], v[206:207], 0, v[162:163]
	v_lshl_add_u64 v[208:209], v[208:209], 0, v[152:153]
	global_load_dwordx2 v[198:199], v[208:209], off
	v_lshl_add_u64 v[214:215], v[206:207], 0, v[204:205]
	v_lshl_add_u64 v[214:215], v[214:215], 0, v[152:153]
	global_load_dwordx2 v[200:201], v[214:215], off
	s_waitcnt vmcnt(0)
	v_mov_b32_e32 v128, v198
	v_mov_b32_e32 v129, v199
	v_lshl_add_u64 v[130:131], v[134:135], 0, v[166:167]
	v_lshl_add_u64 v[130:131], v[130:131], 0, v[152:153]
	v_lshlrev_b32_e32 v132, 16, v128
	v_and_b32_e32 v133, 0xffff0000, v128
	v_lshlrev_b32_e32 v128, 16, v129
	v_and_b32_e32 v129, 0xffff0000, v129
	v_pk_fma_f32 v[126:127], v[126:127], v[114:115], v[128:129]
	v_pk_fma_f32 v[124:125], v[124:125], v[112:113], v[132:133]
	s_nop 0
	v_cvt_pk_bf16_f32 v124, v124, v125
	v_cvt_pk_bf16_f32 v125, v126, v127
	global_store_dwordx2 v[190:191], v[124:125], off
	v_mov_b32_e32 v124, v200
	v_mov_b32_e32 v125, v201
	v_lshl_add_u64 v[126:127], v[170:171], 0, s[24:25]
	v_lshl_add_u64 v[126:127], v[126:127], 0, v[168:169]
	v_lshl_add_u64 v[126:127], v[126:127], 0, v[140:141]
	v_lshlrev_b32_e32 v128, 16, v124
	v_and_b32_e32 v129, 0xffff0000, v124
	v_lshlrev_b32_e32 v124, 16, v125
	v_and_b32_e32 v125, 0xffff0000, v125
	v_pk_fma_f32 v[122:123], v[122:123], v[110:111], v[124:125]
	v_pk_fma_f32 v[120:121], v[120:121], v[108:109], v[128:129]
	s_nop 0
	v_cvt_pk_bf16_f32 v120, v120, v121
	v_cvt_pk_bf16_f32 v121, v122, v123
	global_store_dwordx2 v[130:131], v[120:121], off
	s_mov_b32 s101, s25
	v_mov_b32_e32 v203, v153
	s_or_b32 s98, s9, 16
	s_lshr_b32 s98, s98, 3
	s_and_b32 s98, s98, 10
	s_or_b32 s98, s98, s89
	s_lshl_b32 s100, s98, 10
	v_mov_b32_e32 v205, v153
	v_or_b32_e32 v206, 0x80, v240
	v_ashrrev_i32_e32 v208, 6, v206
	v_ashrrev_i32_e32 v209, 31, v208
	v_lshlrev_b64 v[208:209], 14, v[208:209]
	v_lshlrev_b32_e32 v204, 1, v206
	v_lshl_add_u64 v[208:209], s[10:11], 0, v[208:209]
	v_and_b32_e32 v215, 16, v204
	v_lshl_add_u64 v[216:217], v[208:209], 0, s[64:65]
	v_and_b32_e32 v206, 8, v204
	v_or_b32_e32 v204, v238, v215
	v_mov_b32_e32 v207, v153
	v_or_b32_e32 v218, 0x90, v240
	v_ashrrev_i32_e32 v224, 6, v218
	v_ashrrev_i32_e32 v225, 31, v224
	v_lshlrev_b64 v[224:225], 14, v[224:225]
	v_lshlrev_b32_e32 v202, 1, v218
	v_lshl_add_u64 v[224:225], s[10:11], 0, v[224:225]
	v_and_b32_e32 v226, 48, v202
	v_lshl_add_u64 v[228:229], v[224:225], 0, s[64:65]
	v_and_b32_e32 v218, 8, v202
	v_bitop3_b32 v202, v236, v237, v226 bitop3:0x36
	v_mov_b32_e32 v219, v153
	v_lshl_add_u64 v[230:231], v[216:217], 0, s[100:101]
	v_lshl_add_u64 v[230:231], v[230:231], 0, v[204:205]
	v_lshl_add_u64 v[230:231], v[230:231], 0, v[206:207]
	global_load_dwordx2 v[198:199], v[230:231], off
	v_lshl_add_u64 v[232:233], v[228:229], 0, s[100:101]
	v_lshl_add_u64 v[232:233], v[232:233], 0, v[202:203]
	v_lshl_add_u64 v[232:233], v[232:233], 0, v[218:219]
	global_load_dwordx2 v[200:201], v[232:233], off
	s_waitcnt vmcnt(0)
; __device__ __forceinline__ unsigned pk_bf16(float lo, float hi) { f32x2 v = {lo, hi}; bf16x2_t b = __builtin_convertvector(v, bf16x2_t); return __builtin_bit_cast(unsigned, b); }
; __device__ __forceinline__ f32x4 unpack4(u32x2 w) { return (f32x4){bf_lo(w.x), bf_hi(w.x), bf_lo(w.y), bf_hi(w.y)}; }
;     __device__ __forceinline__ void operator()(const f32x4 (&acc)[2][2][4][2], const Unit& u, int wr, int wc, int fr, int fq) const {
;     ...
;             for (int m = 0; m < 4; ++m) { const int rr = rowl + ai * HALF + m * 16;
; #pragma unroll
;                 for (int bj = 0; bj < 2; ++bj)
; #pragma unroll
;                     for (int n = 0; n < 2; ++n) { const int c = c0 + bj * HALF + n * 16; char* xp = (char*)xr + blk_off(rr, c, DM / 64);
;                         const f32x4 bs = base_f32 ? *(const f32x4*)(base_f32 + (size_t)rr * DM + c) : unpack4(*(const u32x2*)xp);
;                         const f32x4 o = bs + gv[bj][n] * acc[ai][bj][m][n];
;                         u32x2 w; w.x = pk_bf16(o[0], o[1]); w.y = pk_bf16(o[2], o[3]);
;                         *(u32x2*)xp = w; } }
	v_mov_b32_e32 v120, v198
	v_mov_b32_e32 v121, v199
	v_lshl_add_u64 v[122:123], v[174:175], 0, s[24:25]
	v_lshl_add_u64 v[122:123], v[122:123], 0, v[172:173]
	v_lshl_add_u64 v[122:123], v[122:123], 0, v[136:137]
	s_lshl_b32 s24, s6, 10
	s_or_b32 s6, s9, 48
	s_lshr_b32 s6, s6, 3
	s_and_b32 s6, s6, 14
	s_or_b32 s6, s6, s89
	v_lshlrev_b32_e32 v124, 16, v120
	v_and_b32_e32 v125, 0xffff0000, v120
	v_lshlrev_b32_e32 v120, 16, v121
	v_and_b32_e32 v121, 0xffff0000, v121
	v_pk_fma_f32 v[118:119], v[118:119], v[98:99], v[120:121]
	v_pk_fma_f32 v[116:117], v[116:117], v[96:97], v[124:125]
	s_nop 0
	v_cvt_pk_bf16_f32 v116, v116, v117
	v_cvt_pk_bf16_f32 v117, v118, v119
	global_store_dwordx2 v[126:127], v[116:117], off
	v_mov_b32_e32 v116, v200
	v_mov_b32_e32 v117, v201
	v_lshl_add_u64 v[118:119], v[160:161], 0, s[24:25]
	v_lshl_add_u64 v[120:121], v[118:119], 0, v[162:163]
	v_lshl_add_u64 v[120:121], v[120:121], 0, v[152:153]
	v_lshlrev_b32_e32 v124, 16, v116
	v_and_b32_e32 v125, 0xffff0000, v116
	v_lshlrev_b32_e32 v116, 16, v117
	v_and_b32_e32 v117, 0xffff0000, v117
	v_pk_fma_f32 v[106:107], v[106:107], v[90:91], v[116:117]
	v_pk_fma_f32 v[104:105], v[104:105], v[88:89], v[124:125]
	s_nop 0
	v_cvt_pk_bf16_f32 v104, v104, v105
	v_cvt_pk_bf16_f32 v105, v106, v107
	global_store_dwordx2 v[122:123], v[104:105], off
	s_mov_b32 s101, s25
	v_or_b32_e32 v202, 32, v185
	v_mov_b32_e32 v205, v153
	v_bitop3_b32 v204, v236, v237, v202 bitop3:0x36
	s_or_b32 s98, s9, 32
	s_lshr_b32 s98, s98, 3
	s_and_b32 s98, s98, 12
	s_or_b32 s98, s98, s89
	s_lshl_b32 s100, s98, 10
	v_lshl_add_u64 v[206:207], v[160:161], 0, s[100:101]
	v_lshl_add_u64 v[208:209], v[206:207], 0, v[162:163]
	v_lshl_add_u64 v[208:209], v[208:209], 0, v[152:153]
	global_load_dwordx2 v[198:199], v[208:209], off
	v_lshl_add_u64 v[214:215], v[206:207], 0, v[204:205]
	v_lshl_add_u64 v[214:215], v[214:215], 0, v[152:153]
	global_load_dwordx2 v[200:201], v[214:215], off
	s_waitcnt vmcnt(0)
	v_mov_b32_e32 v104, v198
	v_mov_b32_e32 v105, v199
	v_lshl_add_u64 v[106:107], v[118:119], 0, v[166:167]
	v_lshl_add_u64 v[106:107], v[106:107], 0, v[152:153]
	v_lshlrev_b32_e32 v116, 16, v104
	v_and_b32_e32 v117, 0xffff0000, v104
	v_lshlrev_b32_e32 v104, 16, v105
	v_and_b32_e32 v105, 0xffff0000, v105
	v_pk_fma_f32 v[102:103], v[102:103], v[114:115], v[104:105]
	v_pk_fma_f32 v[100:101], v[100:101], v[112:113], v[116:117]
	s_nop 0
	v_cvt_pk_bf16_f32 v100, v100, v101
	v_cvt_pk_bf16_f32 v101, v102, v103
	global_store_dwordx2 v[120:121], v[100:101], off
	v_mov_b32_e32 v100, v200
	v_mov_b32_e32 v101, v201
	v_lshl_add_u64 v[102:103], v[170:171], 0, s[24:25]
	v_lshl_add_u64 v[102:103], v[102:103], 0, v[168:169]
	v_lshl_add_u64 v[102:103], v[102:103], 0, v[140:141]
	v_lshlrev_b32_e32 v104, 16, v100
	v_and_b32_e32 v105, 0xffff0000, v100
	v_lshlrev_b32_e32 v100, 16, v101
	v_and_b32_e32 v101, 0xffff0000, v101
	v_pk_fma_f32 v[94:95], v[94:95], v[110:111], v[100:101]
	v_pk_fma_f32 v[92:93], v[92:93], v[108:109], v[104:105]
	s_nop 0
	v_cvt_pk_bf16_f32 v92, v92, v93
	v_cvt_pk_bf16_f32 v93, v94, v95
	global_store_dwordx2 v[106:107], v[92:93], off
	s_mov_b32 s101, s25
	v_mov_b32_e32 v203, v153
	s_or_b32 s98, s9, 32
	s_lshr_b32 s98, s98, 3
	s_and_b32 s98, s98, 12
	s_or_b32 s98, s98, s89
	v_mov_b32_e32 v205, v153
	v_or_b32_e32 v206, 0x80, v240
	v_ashrrev_i32_e32 v208, 6, v206
	v_ashrrev_i32_e32 v209, 31, v208
	v_lshlrev_b64 v[208:209], 14, v[208:209]
	v_lshlrev_b32_e32 v204, 1, v206
	v_lshl_add_u64 v[208:209], s[10:11], 0, v[208:209]
	v_and_b32_e32 v215, 16, v204
	v_lshl_add_u64 v[216:217], v[208:209], 0, s[64:65]
	v_and_b32_e32 v206, 8, v204
	v_or_b32_e32 v204, v238, v215
	v_mov_b32_e32 v207, v153
	v_or_b32_e32 v218, 0x90, v240
	v_ashrrev_i32_e32 v224, 6, v218
	v_ashrrev_i32_e32 v225, 31, v224
	v_lshlrev_b64 v[224:225], 14, v[224:225]
	v_lshlrev_b32_e32 v202, 1, v218
	v_lshl_add_u64 v[224:225], s[10:11], 0, v[224:225]
	v_and_b32_e32 v226, 48, v202
	v_lshl_add_u64 v[228:229], v[224:225], 0, s[64:65]
	v_and_b32_e32 v218, 8, v202
	v_bitop3_b32 v202, v236, v237, v226 bitop3:0x36
	v_mov_b32_e32 v219, v153
	s_lshl_b32 s100, s98, 10
	v_lshl_add_u64 v[230:231], v[216:217], 0, s[100:101]
	v_lshl_add_u64 v[230:231], v[230:231], 0, v[204:205]
	v_lshl_add_u64 v[230:231], v[230:231], 0, v[206:207]
	global_load_dwordx2 v[198:199], v[230:231], off
	v_lshl_add_u64 v[232:233], v[228:229], 0, s[100:101]
	v_lshl_add_u64 v[232:233], v[232:233], 0, v[202:203]
	v_lshl_add_u64 v[232:233], v[232:233], 0, v[218:219]
	global_load_dwordx2 v[200:201], v[232:233], off
	s_waitcnt vmcnt(0)
	v_mov_b32_e32 v92, v198
	v_mov_b32_e32 v93, v199
	v_lshl_add_u64 v[94:95], v[174:175], 0, s[24:25]
	v_lshl_add_u64 v[94:95], v[94:95], 0, v[172:173]
	v_lshl_add_u64 v[94:95], v[94:95], 0, v[136:137]
	s_lshl_b32 s24, s6, 10
	v_lshlrev_b32_e32 v100, 16, v92
	v_and_b32_e32 v101, 0xffff0000, v92
	v_lshlrev_b32_e32 v92, 16, v93
	v_and_b32_e32 v93, 0xffff0000, v93
	v_pk_fma_f32 v[86:87], v[86:87], v[98:99], v[92:93]
	v_pk_fma_f32 v[84:85], v[84:85], v[96:97], v[100:101]
	s_nop 0
	v_cvt_pk_bf16_f32 v84, v84, v85
	v_cvt_pk_bf16_f32 v85, v86, v87
	global_store_dwordx2 v[102:103], v[84:85], off
	v_mov_b32_e32 v84, v200
	v_mov_b32_e32 v85, v201
	v_lshl_add_u64 v[86:87], v[160:161], 0, s[24:25]
	v_lshl_add_u64 v[92:93], v[86:87], 0, v[162:163]
	v_lshl_add_u64 v[92:93], v[92:93], 0, v[152:153]
	v_lshlrev_b32_e32 v100, 16, v84
	v_and_b32_e32 v101, 0xffff0000, v84
	v_lshlrev_b32_e32 v84, 16, v85
	v_and_b32_e32 v85, 0xffff0000, v85
	v_pk_fma_f32 v[82:83], v[82:83], v[90:91], v[84:85]
	v_pk_fma_f32 v[80:81], v[80:81], v[88:89], v[100:101]
	s_nop 0
	v_cvt_pk_bf16_f32 v80, v80, v81
	v_cvt_pk_bf16_f32 v81, v82, v83
	global_store_dwordx2 v[94:95], v[80:81], off
	s_mov_b32 s101, s25
	v_or_b32_e32 v202, 32, v185
	v_mov_b32_e32 v205, v153
	v_bitop3_b32 v204, v236, v237, v202 bitop3:0x36
	s_or_b32 s98, s9, 48
	s_lshr_b32 s98, s98, 3
	s_and_b32 s98, s98, 14
	s_or_b32 s98, s98, s89
	s_lshl_b32 s100, s98, 10
	v_lshl_add_u64 v[206:207], v[160:161], 0, s[100:101]
	v_lshl_add_u64 v[208:209], v[206:207], 0, v[162:163]
	v_lshl_add_u64 v[208:209], v[208:209], 0, v[152:153]
	global_load_dwordx2 v[198:199], v[208:209], off
	v_lshl_add_u64 v[214:215], v[206:207], 0, v[204:205]
	v_lshl_add_u64 v[214:215], v[214:215], 0, v[152:153]
	global_load_dwordx2 v[200:201], v[214:215], off
	s_waitcnt vmcnt(0)
; __device__ __forceinline__ unsigned pk_bf16(float lo, float hi) { f32x2 v = {lo, hi}; bf16x2_t b = __builtin_convertvector(v, bf16x2_t); return __builtin_bit_cast(unsigned, b); }
; __device__ __forceinline__ f32x4 unpack4(u32x2 w) { return (f32x4){bf_lo(w.x), bf_hi(w.x), bf_lo(w.y), bf_hi(w.y)}; }
;     __device__ __forceinline__ void operator()(const f32x4 (&acc)[2][2][4][2], const Unit& u, int wr, int wc, int fr, int fq) const {
;     ...
;             for (int m = 0; m < 4; ++m) { const int rr = rowl + ai * HALF + m * 16;
; #pragma unroll
;                 for (int bj = 0; bj < 2; ++bj)
; #pragma unroll
;                     for (int n = 0; n < 2; ++n) { const int c = c0 + bj * HALF + n * 16; char* xp = (char*)xr + blk_off(rr, c, DM / 64);
;                         const f32x4 bs = base_f32 ? *(const f32x4*)(base_f32 + (size_t)rr * DM + c) : unpack4(*(const u32x2*)xp);
;                         const f32x4 o = bs + gv[bj][n] * acc[ai][bj][m][n];
;                         u32x2 w; w.x = pk_bf16(o[0], o[1]); w.y = pk_bf16(o[2], o[3]);
;                         *(u32x2*)xp = w; } }
	v_mov_b32_e32 v80, v198
	v_mov_b32_e32 v81, v199
	v_lshl_add_u64 v[82:83], v[86:87], 0, v[166:167]
	v_lshl_add_u64 v[82:83], v[82:83], 0, v[152:153]
	v_lshlrev_b32_e32 v84, 16, v80
	v_and_b32_e32 v85, 0xffff0000, v80
	v_lshlrev_b32_e32 v80, 16, v81
	v_and_b32_e32 v81, 0xffff0000, v81
	v_pk_fma_f32 v[78:79], v[78:79], v[114:115], v[80:81]
	v_pk_fma_f32 v[76:77], v[76:77], v[112:113], v[84:85]
	s_nop 0
	v_cvt_pk_bf16_f32 v76, v76, v77
	v_cvt_pk_bf16_f32 v77, v78, v79
	global_store_dwordx2 v[92:93], v[76:77], off
	v_mov_b32_e32 v76, v200
	v_mov_b32_e32 v77, v201
	v_lshl_add_u64 v[78:79], v[170:171], 0, s[24:25]
	v_lshl_add_u64 v[78:79], v[78:79], 0, v[168:169]
	v_lshl_add_u64 v[78:79], v[78:79], 0, v[140:141]
	v_lshlrev_b32_e32 v80, 16, v76
	v_and_b32_e32 v81, 0xffff0000, v76
	v_lshlrev_b32_e32 v76, 16, v77
	v_and_b32_e32 v77, 0xffff0000, v77
	v_pk_fma_f32 v[74:75], v[74:75], v[110:111], v[76:77]
	v_pk_fma_f32 v[72:73], v[72:73], v[108:109], v[80:81]
	s_nop 0
	v_cvt_pk_bf16_f32 v72, v72, v73
	v_cvt_pk_bf16_f32 v73, v74, v75
	global_store_dwordx2 v[82:83], v[72:73], off
	s_mov_b32 s101, s25
	v_mov_b32_e32 v203, v153
	v_mov_b32_e32 v205, v153
	v_or_b32_e32 v206, 0x80, v240
	v_ashrrev_i32_e32 v208, 6, v206
	v_ashrrev_i32_e32 v209, 31, v208
	v_lshlrev_b64 v[208:209], 14, v[208:209]
	v_lshlrev_b32_e32 v204, 1, v206
	v_lshl_add_u64 v[208:209], s[10:11], 0, v[208:209]
	v_and_b32_e32 v215, 16, v204
	v_lshl_add_u64 v[216:217], v[208:209], 0, s[64:65]
	v_and_b32_e32 v206, 8, v204
	v_or_b32_e32 v204, v238, v215
	v_mov_b32_e32 v207, v153
	v_or_b32_e32 v218, 0x90, v240
	v_ashrrev_i32_e32 v224, 6, v218
	v_ashrrev_i32_e32 v225, 31, v224
	v_lshlrev_b64 v[224:225], 14, v[224:225]
	v_lshlrev_b32_e32 v202, 1, v218
	v_lshl_add_u64 v[224:225], s[10:11], 0, v[224:225]
	v_and_b32_e32 v226, 48, v202
	v_lshl_add_u64 v[228:229], v[224:225], 0, s[64:65]
	v_and_b32_e32 v218, 8, v202
	v_bitop3_b32 v202, v236, v237, v226 bitop3:0x36
	v_mov_b32_e32 v219, v153
	s_or_b32 s98, s9, 48
	s_lshr_b32 s98, s98, 3
	s_and_b32 s98, s98, 14
	s_or_b32 s98, s98, s89
	s_lshl_b32 s100, s98, 10
	v_lshl_add_u64 v[230:231], v[216:217], 0, s[100:101]
	v_lshl_add_u64 v[230:231], v[230:231], 0, v[204:205]
	v_lshl_add_u64 v[230:231], v[230:231], 0, v[206:207]
	global_load_dwordx2 v[198:199], v[230:231], off
	v_lshl_add_u64 v[232:233], v[228:229], 0, s[100:101]
	v_lshl_add_u64 v[232:233], v[232:233], 0, v[202:203]
	v_lshl_add_u64 v[232:233], v[232:233], 0, v[218:219]
	global_load_dwordx2 v[200:201], v[232:233], off
	s_waitcnt vmcnt(0)
	v_mov_b32_e32 v72, v198
	v_mov_b32_e32 v73, v199
	v_lshl_add_u64 v[74:75], v[174:175], 0, s[24:25]
	v_lshl_add_u64 v[74:75], v[74:75], 0, v[172:173]
	v_lshl_add_u64 v[74:75], v[74:75], 0, v[136:137]
	v_lshlrev_b32_e32 v76, 16, v72
	v_and_b32_e32 v77, 0xffff0000, v72
	v_lshlrev_b32_e32 v72, 16, v73
	v_and_b32_e32 v73, 0xffff0000, v73
	v_pk_fma_f32 v[70:71], v[70:71], v[98:99], v[72:73]
	v_pk_fma_f32 v[68:69], v[68:69], v[96:97], v[76:77]
	v_mov_b32_e32 v73, v153
	v_cvt_pk_bf16_f32 v68, v68, v69
	v_cvt_pk_bf16_f32 v69, v70, v71
	global_store_dwordx2 v[78:79], v[68:69], off
	v_mov_b32_e32 v70, v200
	v_mov_b32_e32 v71, v201
	v_add_u32_e32 v69, 0x80, v184
	v_ashrrev_i32_e32 v68, 7, v69
	v_lshlrev_b32_e32 v72, 6, v69
	v_lshlrev_b32_e32 v76, 2, v69
	v_ashrrev_i32_e32 v69, 31, v68
	v_and_b32_e32 v82, 0x3c0, v72
	v_and_b32_e32 v83, 32, v76
	v_lshlrev_b64 v[76:77], 19, v[68:69]
	v_or_b32_e32 v84, v83, v82
	v_lshl_add_u64 v[68:69], v[158:159], 0, v[76:77]
	v_or_b32_e32 v72, v84, v185
	v_lshl_add_u64 v[78:79], v[68:69], 0, s[52:53]
	v_lshl_add_u64 v[72:73], v[78:79], 0, v[72:73]
	v_lshl_add_u64 v[72:73], v[72:73], 0, v[152:153]
	v_lshlrev_b32_e32 v80, 16, v70
	v_and_b32_e32 v81, 0xffff0000, v70
	v_lshlrev_b32_e32 v70, 16, v71
	v_and_b32_e32 v71, 0xffff0000, v71
	v_pk_fma_f32 v[66:67], v[66:67], v[90:91], v[70:71]
	v_pk_fma_f32 v[64:65], v[64:65], v[88:89], v[80:81]
	s_nop 0
	v_cvt_pk_bf16_f32 v64, v64, v65
	v_cvt_pk_bf16_f32 v65, v66, v67
	global_store_dwordx2 v[74:75], v[64:65], off
	v_or_b32_e32 v202, 32, v185
	v_mov_b32_e32 v205, v153
	v_add_u32_e32 v207, 0x80, v184
	v_ashrrev_i32_e32 v206, 7, v207
	v_lshlrev_b32_e32 v204, 6, v207
	v_lshlrev_b32_e32 v208, 2, v207
	v_ashrrev_i32_e32 v207, 31, v206
	v_and_b32_e32 v214, 0x3c0, v204
	v_and_b32_e32 v215, 32, v208
	v_lshlrev_b64 v[208:209], 19, v[206:207]
	v_or_b32_e32 v216, v215, v214
	v_lshl_add_u64 v[206:207], v[158:159], 0, v[208:209]
	v_or_b32_e32 v204, v216, v185
	v_lshl_add_u64 v[218:219], v[206:207], 0, s[52:53]
	v_lshl_add_u64 v[204:205], v[218:219], 0, v[204:205]
	v_lshl_add_u64 v[204:205], v[204:205], 0, v[152:153]
	global_load_dwordx2 v[198:199], v[204:205], off
	v_mov_b32_e32 v225, v153
	v_bitop3_b32 v224, v214, v215, v202 bitop3:0x36
	v_lshl_add_u64 v[224:225], v[218:219], 0, v[224:225]
	v_lshl_add_u64 v[224:225], v[224:225], 0, v[152:153]
	global_load_dwordx2 v[200:201], v[224:225], off
	s_waitcnt vmcnt(0)
; __device__ __forceinline__ unsigned pk_bf16(float lo, float hi) { f32x2 v = {lo, hi}; bf16x2_t b = __builtin_convertvector(v, bf16x2_t); return __builtin_bit_cast(unsigned, b); }
; __device__ __forceinline__ f32x4 unpack4(u32x2 w) { return (f32x4){bf_lo(w.x), bf_hi(w.x), bf_lo(w.y), bf_hi(w.y)}; }
;     __device__ __forceinline__ void operator()(const f32x4 (&acc)[2][2][4][2], const Unit& u, int wr, int wc, int fr, int fq) const {
;     ...
;             for (int m = 0; m < 4; ++m) { const int rr = rowl + ai * HALF + m * 16;
; #pragma unroll
;                 for (int bj = 0; bj < 2; ++bj)
; #pragma unroll
;                     for (int n = 0; n < 2; ++n) { const int c = c0 + bj * HALF + n * 16; char* xp = (char*)xr + blk_off(rr, c, DM / 64);
;                         const f32x4 bs = base_f32 ? *(const f32x4*)(base_f32 + (size_t)rr * DM + c) : unpack4(*(const u32x2*)xp);
;                         const f32x4 o = bs + gv[bj][n] * acc[ai][bj][m][n];
;                         u32x2 w; w.x = pk_bf16(o[0], o[1]); w.y = pk_bf16(o[2], o[3]);
;                         *(u32x2*)xp = w; } }
	v_mov_b32_e32 v64, v198
	v_mov_b32_e32 v65, v199
	v_mov_b32_e32 v67, v153
	v_bitop3_b32 v66, v82, v83, v186 bitop3:0x36
	v_lshl_add_u64 v[66:67], v[78:79], 0, v[66:67]
	v_lshl_add_u64 v[66:67], v[66:67], 0, v[152:153]
	v_lshlrev_b32_e32 v70, 16, v64
	v_and_b32_e32 v71, 0xffff0000, v64
	v_lshlrev_b32_e32 v64, 16, v65
	v_and_b32_e32 v65, 0xffff0000, v65
	v_pk_fma_f32 v[62:63], v[62:63], v[114:115], v[64:65]
	v_pk_fma_f32 v[60:61], v[60:61], v[112:113], v[70:71]
	v_mov_b32_e32 v65, v153
	v_cvt_pk_bf16_f32 v60, v60, v61
	v_cvt_pk_bf16_f32 v61, v62, v63
	global_store_dwordx2 v[72:73], v[60:61], off
	v_mov_b32_e32 v62, v200
	v_mov_b32_e32 v63, v201
	v_lshl_add_u64 v[60:61], v[142:143], 0, v[76:77]
	v_or_b32_e32 v64, v84, v187
	v_lshl_add_u64 v[70:71], v[60:61], 0, s[52:53]
	v_lshl_add_u64 v[64:65], v[70:71], 0, v[64:65]
	v_lshl_add_u64 v[64:65], v[64:65], 0, v[140:141]
	v_lshlrev_b32_e32 v70, 16, v62
	v_and_b32_e32 v71, 0xffff0000, v62
	v_lshlrev_b32_e32 v62, 16, v63
	v_and_b32_e32 v63, 0xffff0000, v63
	v_pk_fma_f32 v[58:59], v[58:59], v[110:111], v[62:63]
	v_pk_fma_f32 v[56:57], v[56:57], v[108:109], v[70:71]
	v_mov_b32_e32 v63, v153
	v_cvt_pk_bf16_f32 v56, v56, v57
	v_cvt_pk_bf16_f32 v57, v58, v59
	global_store_dwordx2 v[66:67], v[56:57], off
	v_or_b32_e32 v202, 0x80, v240
	v_ashrrev_i32_e32 v204, 6, v202
	v_ashrrev_i32_e32 v205, 31, v204
	v_lshlrev_b64 v[204:205], 14, v[204:205]
	v_lshlrev_b32_e32 v206, 1, v202
	v_lshl_add_u64 v[204:205], s[10:11], 0, v[204:205]
	v_and_b32_e32 v209, 16, v206
	v_and_b32_e32 v202, 8, v206
	v_mov_b32_e32 v203, v153
	v_or_b32_e32 v214, 0x90, v240
	v_ashrrev_i32_e32 v216, 6, v214
	v_ashrrev_i32_e32 v217, 31, v216
	v_lshlrev_b64 v[216:217], 14, v[216:217]
	v_lshlrev_b32_e32 v218, 1, v214
	v_lshl_add_u64 v[216:217], s[10:11], 0, v[216:217]
	v_and_b32_e32 v224, 48, v218
	v_and_b32_e32 v214, 8, v218
	v_mov_b32_e32 v215, v153
	v_add_u32_e32 v227, 0x80, v184
	v_ashrrev_i32_e32 v226, 7, v227
	v_lshlrev_b32_e32 v228, 6, v227
	v_lshlrev_b32_e32 v230, 2, v227
	v_ashrrev_i32_e32 v227, 31, v226
	v_and_b32_e32 v232, 0x3c0, v228
	v_and_b32_e32 v233, 32, v230
	v_lshlrev_b64 v[230:231], 19, v[226:227]
	v_or_b32_e32 v234, v233, v232
	v_mov_b32_e32 v207, v153
	v_lshl_add_u64 v[218:219], v[204:205], 0, v[230:231]
	v_or_b32_e32 v206, v234, v209
	v_lshl_add_u64 v[228:229], v[218:219], 0, s[52:53]
	v_lshl_add_u64 v[206:207], v[228:229], 0, v[206:207]
	v_lshl_add_u64 v[206:207], v[206:207], 0, v[202:203]
	v_mov_b32_e32 v227, v153
	global_load_dwordx2 v[198:199], v[206:207], off
	v_lshl_add_u64 v[204:205], v[216:217], 0, v[230:231]
	v_bitop3_b32 v226, v232, v233, v224 bitop3:0x36
	v_lshl_add_u64 v[208:209], v[204:205], 0, s[52:53]
	v_lshl_add_u64 v[226:227], v[208:209], 0, v[226:227]
	v_lshl_add_u64 v[226:227], v[226:227], 0, v[214:215]
	global_load_dwordx2 v[200:201], v[226:227], off
	s_waitcnt vmcnt(0)
	v_mov_b32_e32 v58, v198
	v_mov_b32_e32 v59, v199
	v_lshl_add_u64 v[56:57], v[138:139], 0, v[76:77]
	v_bitop3_b32 v62, v82, v83, v188 bitop3:0x36
	v_lshl_add_u64 v[66:67], v[56:57], 0, s[52:53]
	v_lshl_add_u64 v[62:63], v[66:67], 0, v[62:63]
	v_lshl_add_u64 v[62:63], v[62:63], 0, v[136:137]
	v_lshlrev_b32_e32 v66, 16, v58
	v_and_b32_e32 v67, 0xffff0000, v58
	v_lshlrev_b32_e32 v58, 16, v59
	v_and_b32_e32 v59, 0xffff0000, v59
	v_pk_fma_f32 v[54:55], v[54:55], v[98:99], v[58:59]
	v_pk_fma_f32 v[52:53], v[52:53], v[96:97], v[66:67]
	v_mov_b32_e32 v59, v153
	v_cvt_pk_bf16_f32 v52, v52, v53
	v_cvt_pk_bf16_f32 v53, v54, v55
	global_store_dwordx2 v[64:65], v[52:53], off
	v_mov_b32_e32 v52, v200
	v_mov_b32_e32 v53, v201
	v_add_u32_e32 v54, 0x90, v184
	v_lshrrev_b32_e32 v58, 3, v54
	v_lshlrev_b32_e32 v64, 6, v54
	v_lshlrev_b32_e32 v54, 2, v54
	v_and_or_b32 v58, v58, 10, s89
	v_and_b32_e32 v70, 0x3c0, v64
	v_and_b32_e32 v71, 32, v54
	v_mov_b32_e32 v55, v153
	v_lshlrev_b32_e32 v54, 10, v58
	v_or_b32_e32 v72, v71, v70
	v_or_b32_e32 v58, v72, v185
	v_lshl_add_u64 v[64:65], v[68:69], 0, v[54:55]
	v_lshl_add_u64 v[58:59], v[64:65], 0, v[58:59]
	v_lshl_add_u64 v[58:59], v[58:59], 0, v[152:153]
	v_lshlrev_b32_e32 v66, 16, v52
	v_and_b32_e32 v67, 0xffff0000, v52
	v_lshlrev_b32_e32 v52, 16, v53
	v_and_b32_e32 v53, 0xffff0000, v53
	v_pk_fma_f32 v[50:51], v[50:51], v[90:91], v[52:53]
	v_pk_fma_f32 v[48:49], v[48:49], v[88:89], v[66:67]
	s_nop 0
	v_cvt_pk_bf16_f32 v48, v48, v49
	v_cvt_pk_bf16_f32 v49, v50, v51
	global_store_dwordx2 v[62:63], v[48:49], off
	v_or_b32_e32 v202, 32, v185
	v_add_u32_e32 v205, 0x80, v184
	v_ashrrev_i32_e32 v204, 7, v205
	v_ashrrev_i32_e32 v205, 31, v204
	v_lshlrev_b64 v[206:207], 19, v[204:205]
	v_lshl_add_u64 v[204:205], v[158:159], 0, v[206:207]
	v_mov_b32_e32 v209, v153
	v_add_u32_e32 v214, 0x90, v184
	v_lshrrev_b32_e32 v208, 3, v214
	v_lshlrev_b32_e32 v216, 6, v214
	v_lshlrev_b32_e32 v214, 2, v214
	v_and_or_b32 v208, v208, 10, s89
	v_and_b32_e32 v218, 0x3c0, v216
	v_and_b32_e32 v219, 32, v214
	v_mov_b32_e32 v215, v153
	v_lshlrev_b32_e32 v214, 10, v208
	v_or_b32_e32 v224, v219, v218
	v_or_b32_e32 v208, v224, v185
	v_lshl_add_u64 v[216:217], v[204:205], 0, v[214:215]
	v_lshl_add_u64 v[208:209], v[216:217], 0, v[208:209]
	v_lshl_add_u64 v[208:209], v[208:209], 0, v[152:153]
	global_load_dwordx2 v[198:199], v[208:209], off
	v_mov_b32_e32 v227, v153
	v_bitop3_b32 v226, v218, v219, v202 bitop3:0x36
	v_lshl_add_u64 v[226:227], v[216:217], 0, v[226:227]
	v_lshl_add_u64 v[226:227], v[226:227], 0, v[152:153]
	global_load_dwordx2 v[200:201], v[226:227], off
	s_waitcnt vmcnt(0)
; __device__ __forceinline__ unsigned pk_bf16(float lo, float hi) { f32x2 v = {lo, hi}; bf16x2_t b = __builtin_convertvector(v, bf16x2_t); return __builtin_bit_cast(unsigned, b); }
; __device__ __forceinline__ f32x4 unpack4(u32x2 w) { return (f32x4){bf_lo(w.x), bf_hi(w.x), bf_lo(w.y), bf_hi(w.y)}; }
;     __device__ __forceinline__ void operator()(const f32x4 (&acc)[2][2][4][2], const Unit& u, int wr, int wc, int fr, int fq) const {
;     ...
;             for (int m = 0; m < 4; ++m) { const int rr = rowl + ai * HALF + m * 16;
; #pragma unroll
;                 for (int bj = 0; bj < 2; ++bj)
; #pragma unroll
;                     for (int n = 0; n < 2; ++n) { const int c = c0 + bj * HALF + n * 16; char* xp = (char*)xr + blk_off(rr, c, DM / 64);
;                         const f32x4 bs = base_f32 ? *(const f32x4*)(base_f32 + (size_t)rr * DM + c) : unpack4(*(const u32x2*)xp);
;                         const f32x4 o = bs + gv[bj][n] * acc[ai][bj][m][n];
;                         u32x2 w; w.x = pk_bf16(o[0], o[1]); w.y = pk_bf16(o[2], o[3]);
;                         *(u32x2*)xp = w; } }
	v_mov_b32_e32 v48, v198
	v_mov_b32_e32 v49, v199
	v_mov_b32_e32 v51, v153
	v_bitop3_b32 v50, v70, v71, v186 bitop3:0x36
	v_lshl_add_u64 v[50:51], v[64:65], 0, v[50:51]
	v_lshl_add_u64 v[50:51], v[50:51], 0, v[152:153]
	v_lshlrev_b32_e32 v52, 16, v48
	v_and_b32_e32 v53, 0xffff0000, v48
	v_lshlrev_b32_e32 v48, 16, v49
	v_and_b32_e32 v49, 0xffff0000, v49
	v_pk_fma_f32 v[46:47], v[46:47], v[114:115], v[48:49]
	v_pk_fma_f32 v[44:45], v[44:45], v[112:113], v[52:53]
	v_lshl_add_u64 v[48:49], v[60:61], 0, v[54:55]
	v_cvt_pk_bf16_f32 v44, v44, v45
	v_cvt_pk_bf16_f32 v45, v46, v47
	global_store_dwordx2 v[58:59], v[44:45], off
	v_mov_b32_e32 v44, v200
	v_mov_b32_e32 v45, v201
	v_mov_b32_e32 v47, v153
	v_or_b32_e32 v46, v72, v187
	v_lshl_add_u64 v[46:47], v[48:49], 0, v[46:47]
	v_lshl_add_u64 v[46:47], v[46:47], 0, v[140:141]
	v_lshlrev_b32_e32 v48, 16, v44
	v_and_b32_e32 v49, 0xffff0000, v44
	v_lshlrev_b32_e32 v44, 16, v45
	v_and_b32_e32 v45, 0xffff0000, v45
	v_pk_fma_f32 v[42:43], v[42:43], v[110:111], v[44:45]
	v_pk_fma_f32 v[40:41], v[40:41], v[108:109], v[48:49]
	v_lshl_add_u64 v[44:45], v[56:57], 0, v[54:55]
	v_cvt_pk_bf16_f32 v40, v40, v41
	v_cvt_pk_bf16_f32 v41, v42, v43
	global_store_dwordx2 v[50:51], v[40:41], off
	v_or_b32_e32 v202, 0x80, v240
	v_ashrrev_i32_e32 v204, 6, v202
	v_ashrrev_i32_e32 v205, 31, v204
	v_lshlrev_b64 v[204:205], 14, v[204:205]
	v_lshlrev_b32_e32 v206, 1, v202
	v_lshl_add_u64 v[204:205], s[10:11], 0, v[204:205]
	v_and_b32_e32 v209, 16, v206
	v_and_b32_e32 v202, 8, v206
	v_mov_b32_e32 v203, v153
	v_or_b32_e32 v214, 0x90, v240
	v_ashrrev_i32_e32 v216, 6, v214
	v_ashrrev_i32_e32 v217, 31, v216
	v_lshlrev_b64 v[216:217], 14, v[216:217]
	v_lshlrev_b32_e32 v218, 1, v214
	v_lshl_add_u64 v[216:217], s[10:11], 0, v[216:217]
	v_and_b32_e32 v224, 48, v218
	v_and_b32_e32 v214, 8, v218
	v_mov_b32_e32 v215, v153
	v_add_u32_e32 v227, 0x80, v184
	v_ashrrev_i32_e32 v226, 7, v227
	v_ashrrev_i32_e32 v227, 31, v226
	v_lshlrev_b64 v[228:229], 19, v[226:227]
	v_lshl_add_u64 v[230:231], v[204:205], 0, v[228:229]
	v_lshl_add_u64 v[232:233], v[216:217], 0, v[228:229]
	v_add_u32_e32 v234, 0x90, v184
	v_lshrrev_b32_e32 v206, 3, v234
	v_lshlrev_b32_e32 v218, 6, v234
	v_lshlrev_b32_e32 v234, 2, v234
	v_and_or_b32 v206, v206, 10, s89
	v_and_b32_e32 v226, 0x3c0, v218
	v_and_b32_e32 v227, 32, v234
	v_mov_b32_e32 v235, v153
	v_lshlrev_b32_e32 v234, 10, v206
	v_or_b32_e32 v204, v227, v226
	v_lshl_add_u64 v[216:217], v[230:231], 0, v[234:235]
	v_mov_b32_e32 v229, v153
	v_or_b32_e32 v228, v204, v209
	v_lshl_add_u64 v[228:229], v[216:217], 0, v[228:229]
	v_lshl_add_u64 v[228:229], v[228:229], 0, v[202:203]
	v_lshl_add_u64 v[218:219], v[232:233], 0, v[234:235]
	global_load_dwordx2 v[198:199], v[228:229], off
	v_mov_b32_e32 v207, v153
	v_bitop3_b32 v206, v226, v227, v224 bitop3:0x36
	v_lshl_add_u64 v[206:207], v[218:219], 0, v[206:207]
	v_lshl_add_u64 v[206:207], v[206:207], 0, v[214:215]
	global_load_dwordx2 v[200:201], v[206:207], off
	s_waitcnt vmcnt(0)
	v_mov_b32_e32 v40, v198
	v_mov_b32_e32 v41, v199
	v_mov_b32_e32 v43, v153
	v_bitop3_b32 v42, v70, v71, v188 bitop3:0x36
	v_lshl_add_u64 v[42:43], v[44:45], 0, v[42:43]
	v_lshl_add_u64 v[42:43], v[42:43], 0, v[136:137]
	v_lshlrev_b32_e32 v44, 16, v40
	v_and_b32_e32 v45, 0xffff0000, v40
	v_lshlrev_b32_e32 v40, 16, v41
	v_and_b32_e32 v41, 0xffff0000, v41
	v_pk_fma_f32 v[38:39], v[38:39], v[98:99], v[40:41]
	v_pk_fma_f32 v[36:37], v[36:37], v[96:97], v[44:45]
	v_mov_b32_e32 v41, v153
	v_cvt_pk_bf16_f32 v36, v36, v37
	v_cvt_pk_bf16_f32 v37, v38, v39
	global_store_dwordx2 v[46:47], v[36:37], off
	v_mov_b32_e32 v36, v200
	v_mov_b32_e32 v37, v201
	v_add_u32_e32 v38, 0xa0, v184
	v_lshrrev_b32_e32 v40, 3, v38
	v_lshlrev_b32_e32 v44, 6, v38
	v_lshlrev_b32_e32 v38, 2, v38
	v_and_or_b32 v40, v40, 12, s89
	v_and_b32_e32 v48, 0x3c0, v44
	v_and_b32_e32 v49, 32, v38
	v_mov_b32_e32 v39, v153
	v_lshlrev_b32_e32 v38, 10, v40
	v_or_b32_e32 v50, v49, v48
	v_or_b32_e32 v40, v50, v185
	v_lshl_add_u64 v[44:45], v[68:69], 0, v[38:39]
	v_lshl_add_u64 v[40:41], v[44:45], 0, v[40:41]
	v_lshl_add_u64 v[40:41], v[40:41], 0, v[152:153]
	v_lshlrev_b32_e32 v46, 16, v36
	v_and_b32_e32 v47, 0xffff0000, v36
	v_lshlrev_b32_e32 v36, 16, v37
	v_and_b32_e32 v37, 0xffff0000, v37
	v_pk_fma_f32 v[34:35], v[34:35], v[90:91], v[36:37]
	v_pk_fma_f32 v[32:33], v[32:33], v[88:89], v[46:47]
	s_nop 0
	v_cvt_pk_bf16_f32 v32, v32, v33
	v_cvt_pk_bf16_f32 v33, v34, v35
	global_store_dwordx2 v[42:43], v[32:33], off
	v_or_b32_e32 v202, 32, v185
	v_add_u32_e32 v205, 0x80, v184
	v_ashrrev_i32_e32 v204, 7, v205
	v_ashrrev_i32_e32 v205, 31, v204
	v_lshlrev_b64 v[206:207], 19, v[204:205]
	v_lshl_add_u64 v[204:205], v[158:159], 0, v[206:207]
	v_mov_b32_e32 v209, v153
	v_add_u32_e32 v214, 0xa0, v184
	v_lshrrev_b32_e32 v208, 3, v214
	v_lshlrev_b32_e32 v216, 6, v214
	v_lshlrev_b32_e32 v214, 2, v214
	v_and_or_b32 v208, v208, 12, s89
	v_and_b32_e32 v218, 0x3c0, v216
	v_and_b32_e32 v219, 32, v214
	v_mov_b32_e32 v215, v153
	v_lshlrev_b32_e32 v214, 10, v208
	v_or_b32_e32 v224, v219, v218
	v_or_b32_e32 v208, v224, v185
	v_lshl_add_u64 v[216:217], v[204:205], 0, v[214:215]
	v_lshl_add_u64 v[208:209], v[216:217], 0, v[208:209]
	v_lshl_add_u64 v[208:209], v[208:209], 0, v[152:153]
	global_load_dwordx2 v[198:199], v[208:209], off
	v_mov_b32_e32 v227, v153
	v_bitop3_b32 v226, v218, v219, v202 bitop3:0x36
	v_lshl_add_u64 v[226:227], v[216:217], 0, v[226:227]
	v_lshl_add_u64 v[226:227], v[226:227], 0, v[152:153]
	global_load_dwordx2 v[200:201], v[226:227], off
	s_waitcnt vmcnt(0)
; __device__ __forceinline__ unsigned pk_bf16(float lo, float hi) { f32x2 v = {lo, hi}; bf16x2_t b = __builtin_convertvector(v, bf16x2_t); return __builtin_bit_cast(unsigned, b); }
; __device__ __forceinline__ f32x4 unpack4(u32x2 w) { return (f32x4){bf_lo(w.x), bf_hi(w.x), bf_lo(w.y), bf_hi(w.y)}; }
;     __device__ __forceinline__ void operator()(const f32x4 (&acc)[2][2][4][2], const Unit& u, int wr, int wc, int fr, int fq) const {
;     ...
;             for (int m = 0; m < 4; ++m) { const int rr = rowl + ai * HALF + m * 16;
; #pragma unroll
;                 for (int bj = 0; bj < 2; ++bj)
; #pragma unroll
;                     for (int n = 0; n < 2; ++n) { const int c = c0 + bj * HALF + n * 16; char* xp = (char*)xr + blk_off(rr, c, DM / 64);
;                         const f32x4 bs = base_f32 ? *(const f32x4*)(base_f32 + (size_t)rr * DM + c) : unpack4(*(const u32x2*)xp);
;                         const f32x4 o = bs + gv[bj][n] * acc[ai][bj][m][n];
;                         u32x2 w; w.x = pk_bf16(o[0], o[1]); w.y = pk_bf16(o[2], o[3]);
;                         *(u32x2*)xp = w; } }
	v_mov_b32_e32 v32, v198
	v_mov_b32_e32 v33, v199
	v_mov_b32_e32 v35, v153
	v_bitop3_b32 v34, v48, v49, v186 bitop3:0x36
	v_lshl_add_u64 v[34:35], v[44:45], 0, v[34:35]
	v_lshl_add_u64 v[34:35], v[34:35], 0, v[152:153]
	v_lshlrev_b32_e32 v36, 16, v32
	v_and_b32_e32 v37, 0xffff0000, v32
	v_lshlrev_b32_e32 v32, 16, v33
	v_and_b32_e32 v33, 0xffff0000, v33
	v_pk_fma_f32 v[30:31], v[30:31], v[114:115], v[32:33]
	v_pk_fma_f32 v[28:29], v[28:29], v[112:113], v[36:37]
	v_lshl_add_u64 v[32:33], v[60:61], 0, v[38:39]
	v_cvt_pk_bf16_f32 v28, v28, v29
	v_cvt_pk_bf16_f32 v29, v30, v31
	global_store_dwordx2 v[40:41], v[28:29], off
	v_mov_b32_e32 v28, v200
	v_mov_b32_e32 v29, v201
	v_mov_b32_e32 v31, v153
	v_or_b32_e32 v30, v50, v187
	v_lshl_add_u64 v[30:31], v[32:33], 0, v[30:31]
	v_lshl_add_u64 v[30:31], v[30:31], 0, v[140:141]
	v_lshlrev_b32_e32 v32, 16, v28
	v_and_b32_e32 v33, 0xffff0000, v28
	v_lshlrev_b32_e32 v28, 16, v29
	v_and_b32_e32 v29, 0xffff0000, v29
	v_pk_fma_f32 v[26:27], v[26:27], v[110:111], v[28:29]
	v_pk_fma_f32 v[24:25], v[24:25], v[108:109], v[32:33]
	v_lshl_add_u64 v[28:29], v[56:57], 0, v[38:39]
	v_cvt_pk_bf16_f32 v24, v24, v25
	v_cvt_pk_bf16_f32 v25, v26, v27
	global_store_dwordx2 v[34:35], v[24:25], off
	v_or_b32_e32 v202, 0x80, v240
	v_ashrrev_i32_e32 v204, 6, v202
	v_ashrrev_i32_e32 v205, 31, v204
	v_lshlrev_b64 v[204:205], 14, v[204:205]
	v_lshlrev_b32_e32 v206, 1, v202
	v_lshl_add_u64 v[204:205], s[10:11], 0, v[204:205]
	v_and_b32_e32 v209, 16, v206
	v_and_b32_e32 v202, 8, v206
	v_mov_b32_e32 v203, v153
	v_or_b32_e32 v214, 0x90, v240
	v_ashrrev_i32_e32 v216, 6, v214
	v_ashrrev_i32_e32 v217, 31, v216
	v_lshlrev_b64 v[216:217], 14, v[216:217]
	v_lshlrev_b32_e32 v218, 1, v214
	v_lshl_add_u64 v[216:217], s[10:11], 0, v[216:217]
	v_and_b32_e32 v224, 48, v218
	v_and_b32_e32 v214, 8, v218
	v_mov_b32_e32 v215, v153
	v_add_u32_e32 v227, 0x80, v184
	v_ashrrev_i32_e32 v226, 7, v227
	v_ashrrev_i32_e32 v227, 31, v226
	v_lshlrev_b64 v[228:229], 19, v[226:227]
	v_lshl_add_u64 v[230:231], v[204:205], 0, v[228:229]
	v_lshl_add_u64 v[232:233], v[216:217], 0, v[228:229]
	v_add_u32_e32 v234, 0xa0, v184
	v_lshrrev_b32_e32 v206, 3, v234
	v_lshlrev_b32_e32 v218, 6, v234
	v_lshlrev_b32_e32 v234, 2, v234
	v_and_or_b32 v206, v206, 12, s89
	v_and_b32_e32 v226, 0x3c0, v218
	v_and_b32_e32 v227, 32, v234
	v_mov_b32_e32 v235, v153
	v_lshlrev_b32_e32 v234, 10, v206
	v_or_b32_e32 v204, v227, v226
	v_lshl_add_u64 v[216:217], v[230:231], 0, v[234:235]
	v_mov_b32_e32 v229, v153
	v_or_b32_e32 v228, v204, v209
	v_lshl_add_u64 v[228:229], v[216:217], 0, v[228:229]
	v_lshl_add_u64 v[228:229], v[228:229], 0, v[202:203]
	v_lshl_add_u64 v[218:219], v[232:233], 0, v[234:235]
	global_load_dwordx2 v[198:199], v[228:229], off
	v_mov_b32_e32 v207, v153
	v_bitop3_b32 v206, v226, v227, v224 bitop3:0x36
	v_lshl_add_u64 v[206:207], v[218:219], 0, v[206:207]
	v_lshl_add_u64 v[206:207], v[206:207], 0, v[214:215]
	global_load_dwordx2 v[200:201], v[206:207], off
	s_waitcnt vmcnt(0)
	v_mov_b32_e32 v24, v198
	v_mov_b32_e32 v25, v199
	v_mov_b32_e32 v27, v153
	v_bitop3_b32 v26, v48, v49, v188 bitop3:0x36
	v_lshl_add_u64 v[26:27], v[28:29], 0, v[26:27]
	v_lshl_add_u64 v[26:27], v[26:27], 0, v[136:137]
	v_lshlrev_b32_e32 v28, 16, v24
	v_and_b32_e32 v29, 0xffff0000, v24
	v_lshlrev_b32_e32 v24, 16, v25
	v_and_b32_e32 v25, 0xffff0000, v25
	v_pk_fma_f32 v[22:23], v[22:23], v[98:99], v[24:25]
	v_pk_fma_f32 v[20:21], v[20:21], v[96:97], v[28:29]
	v_mov_b32_e32 v25, v153
	v_cvt_pk_bf16_f32 v20, v20, v21
	v_cvt_pk_bf16_f32 v21, v22, v23
	global_store_dwordx2 v[30:31], v[20:21], off
	v_mov_b32_e32 v20, v200
	v_mov_b32_e32 v21, v201
	v_add_u32_e32 v22, 0xb0, v184
	v_lshrrev_b32_e32 v24, 3, v22
	v_lshlrev_b32_e32 v28, 6, v22
	v_lshlrev_b32_e32 v22, 2, v22
	v_and_or_b32 v24, v24, 14, s89
	v_and_b32_e32 v32, 0x3c0, v28
	v_and_b32_e32 v33, 32, v22
	v_mov_b32_e32 v23, v153
	v_lshlrev_b32_e32 v22, 10, v24
	v_or_b32_e32 v34, v33, v32
	v_or_b32_e32 v24, v34, v185
	v_lshl_add_u64 v[28:29], v[68:69], 0, v[22:23]
	v_lshl_add_u64 v[24:25], v[28:29], 0, v[24:25]
	v_lshl_add_u64 v[24:25], v[24:25], 0, v[152:153]
	v_lshlrev_b32_e32 v30, 16, v20
	v_and_b32_e32 v31, 0xffff0000, v20
	v_lshlrev_b32_e32 v20, 16, v21
	v_and_b32_e32 v21, 0xffff0000, v21
	v_pk_fma_f32 v[18:19], v[18:19], v[90:91], v[20:21]
	v_pk_fma_f32 v[16:17], v[16:17], v[88:89], v[30:31]
	s_nop 0
	v_cvt_pk_bf16_f32 v16, v16, v17
	v_cvt_pk_bf16_f32 v17, v18, v19
	global_store_dwordx2 v[26:27], v[16:17], off
	v_or_b32_e32 v202, 32, v185
	v_add_u32_e32 v205, 0x80, v184
	v_ashrrev_i32_e32 v204, 7, v205
	v_ashrrev_i32_e32 v205, 31, v204
	v_lshlrev_b64 v[206:207], 19, v[204:205]
	v_lshl_add_u64 v[204:205], v[158:159], 0, v[206:207]
	v_mov_b32_e32 v209, v153
	v_add_u32_e32 v214, 0xb0, v184
	v_lshrrev_b32_e32 v208, 3, v214
	v_lshlrev_b32_e32 v216, 6, v214
	v_lshlrev_b32_e32 v214, 2, v214
	v_and_or_b32 v208, v208, 14, s89
	v_and_b32_e32 v218, 0x3c0, v216
	v_and_b32_e32 v219, 32, v214
	v_mov_b32_e32 v215, v153
	v_lshlrev_b32_e32 v214, 10, v208
	v_or_b32_e32 v224, v219, v218
	v_or_b32_e32 v208, v224, v185
	v_lshl_add_u64 v[216:217], v[204:205], 0, v[214:215]
	v_lshl_add_u64 v[208:209], v[216:217], 0, v[208:209]
	v_lshl_add_u64 v[208:209], v[208:209], 0, v[152:153]
	global_load_dwordx2 v[198:199], v[208:209], off
	v_mov_b32_e32 v227, v153
	v_bitop3_b32 v226, v218, v219, v202 bitop3:0x36
	v_lshl_add_u64 v[226:227], v[216:217], 0, v[226:227]
	v_lshl_add_u64 v[226:227], v[226:227], 0, v[152:153]
	global_load_dwordx2 v[200:201], v[226:227], off
	s_waitcnt vmcnt(0)
; #define PG8_BAR __builtin_amdgcn_s_barrier()
; __device__ __forceinline__ unsigned pk_bf16(float lo, float hi) { f32x2 v = {lo, hi}; bf16x2_t b = __builtin_convertvector(v, bf16x2_t); return __builtin_bit_cast(unsigned, b); }
; __device__ __forceinline__ f32x4 unpack4(u32x2 w) { return (f32x4){bf_lo(w.x), bf_hi(w.x), bf_lo(w.y), bf_hi(w.y)}; }
; template <class Epi, class Sched, bool ALIGN_EPI = false, bool SP2 = false>
; __device__ __forceinline__ void gemm_phase(PG8_LAS unsigned char* lds, const Gemm g, const Sched& S, const Epi& E) {
;     ...
;         if (!has_next) break;
; #pragma unroll
;         for (int a = 0; a < 2; ++a)
; #pragma unroll
;             for (int b = 0; b < 2; ++b)
; #pragma unroll
;                 for (int m = 0; m < 4; ++m)
; #pragma unroll
;                     for (int n = 0; n < 2; ++n) acc[a][b][m][n] = (f32x4){0.f, 0.f, 0.f, 0.f};
;         cur = nxt; cA = nA; cB = nB; ++ui;
;         if constexpr (ALIGN_EPI) { if (wr == 1) PG8_BAR; }
;     __device__ __forceinline__ void operator()(const f32x4 (&acc)[2][2][4][2], const Unit& u, int wr, int wc, int fr, int fq) const {
;     ...
;             for (int m = 0; m < 4; ++m) { const int rr = rowl + ai * HALF + m * 16;
; #pragma unroll
;                 for (int bj = 0; bj < 2; ++bj)
; #pragma unroll
;                     for (int n = 0; n < 2; ++n) { const int c = c0 + bj * HALF + n * 16; char* xp = (char*)xr + blk_off(rr, c, DM / 64);
;                         const f32x4 bs = base_f32 ? *(const f32x4*)(base_f32 + (size_t)rr * DM + c) : unpack4(*(const u32x2*)xp);
;                         const f32x4 o = bs + gv[bj][n] * acc[ai][bj][m][n];
;                         u32x2 w; w.x = pk_bf16(o[0], o[1]); w.y = pk_bf16(o[2], o[3]);
;                         *(u32x2*)xp = w; } }
	v_mov_b32_e32 v16, v198
	v_mov_b32_e32 v17, v199
	v_mov_b32_e32 v19, v153
	v_bitop3_b32 v18, v32, v33, v186 bitop3:0x36
	v_lshl_add_u64 v[18:19], v[28:29], 0, v[18:19]
	v_lshl_add_u64 v[18:19], v[18:19], 0, v[152:153]
	v_or_b32_e32 v152, v34, v187
	v_lshlrev_b32_e32 v20, 16, v16
	v_and_b32_e32 v21, 0xffff0000, v16
	v_lshlrev_b32_e32 v16, 16, v17
	v_and_b32_e32 v17, 0xffff0000, v17
	v_pk_fma_f32 v[14:15], v[14:15], v[114:115], v[16:17]
	v_pk_fma_f32 v[12:13], v[12:13], v[112:113], v[20:21]
	s_nop 0
	v_cvt_pk_bf16_f32 v12, v12, v13
	v_cvt_pk_bf16_f32 v13, v14, v15
	global_store_dwordx2 v[24:25], v[12:13], off
	v_mov_b32_e32 v12, v200
	v_mov_b32_e32 v13, v201
	v_lshl_add_u64 v[14:15], v[60:61], 0, v[22:23]
	v_lshl_add_u64 v[14:15], v[14:15], 0, v[152:153]
	v_lshl_add_u64 v[14:15], v[14:15], 0, v[140:141]
	v_bitop3_b32 v152, v32, v33, v188 bitop3:0x36
	v_lshlrev_b32_e32 v16, 16, v12
	v_and_b32_e32 v17, 0xffff0000, v12
	v_lshlrev_b32_e32 v12, 16, v13
	v_and_b32_e32 v13, 0xffff0000, v13
	v_pk_fma_f32 v[10:11], v[10:11], v[110:111], v[12:13]
	v_pk_fma_f32 v[8:9], v[8:9], v[108:109], v[16:17]
	s_nop 0
	v_cvt_pk_bf16_f32 v8, v8, v9
	v_cvt_pk_bf16_f32 v9, v10, v11
	global_store_dwordx2 v[18:19], v[8:9], off
	v_or_b32_e32 v202, 0x80, v240
	v_ashrrev_i32_e32 v204, 6, v202
	v_ashrrev_i32_e32 v205, 31, v204
	v_lshlrev_b64 v[204:205], 14, v[204:205]
	v_lshlrev_b32_e32 v206, 1, v202
	v_lshl_add_u64 v[204:205], s[10:11], 0, v[204:205]
	v_and_b32_e32 v209, 16, v206
	v_and_b32_e32 v202, 8, v206
	v_mov_b32_e32 v203, v153
	v_or_b32_e32 v214, 0x90, v240
	v_ashrrev_i32_e32 v216, 6, v214
	v_ashrrev_i32_e32 v217, 31, v216
	v_lshlrev_b64 v[216:217], 14, v[216:217]
	v_lshlrev_b32_e32 v218, 1, v214
	v_lshl_add_u64 v[216:217], s[10:11], 0, v[216:217]
	v_and_b32_e32 v224, 48, v218
	v_and_b32_e32 v214, 8, v218
	v_mov_b32_e32 v215, v153
	v_add_u32_e32 v227, 0x80, v184
	v_ashrrev_i32_e32 v226, 7, v227
	v_ashrrev_i32_e32 v227, 31, v226
	v_lshlrev_b64 v[228:229], 19, v[226:227]
	v_lshl_add_u64 v[230:231], v[204:205], 0, v[228:229]
	v_lshl_add_u64 v[232:233], v[216:217], 0, v[228:229]
	v_add_u32_e32 v234, 0xb0, v184
	v_lshrrev_b32_e32 v206, 3, v234
	v_lshlrev_b32_e32 v218, 6, v234
	v_lshlrev_b32_e32 v234, 2, v234
	v_and_or_b32 v206, v206, 14, s89
	v_and_b32_e32 v226, 0x3c0, v218
	v_and_b32_e32 v227, 32, v234
	v_mov_b32_e32 v235, v153
	v_lshlrev_b32_e32 v234, 10, v206
	v_or_b32_e32 v204, v227, v226
	v_or_b32_e32 v216, v204, v209
	v_lshl_add_u64 v[228:229], v[230:231], 0, v[234:235]
	v_mov_b32_e32 v217, v153
	v_lshl_add_u64 v[228:229], v[228:229], 0, v[216:217]
	v_lshl_add_u64 v[228:229], v[228:229], 0, v[202:203]
	v_bitop3_b32 v216, v226, v227, v224 bitop3:0x36
	global_load_dwordx2 v[198:199], v[228:229], off
	v_lshl_add_u64 v[218:219], v[232:233], 0, v[234:235]
	v_lshl_add_u64 v[218:219], v[218:219], 0, v[216:217]
	v_lshl_add_u64 v[218:219], v[218:219], 0, v[214:215]
	global_load_dwordx2 v[200:201], v[218:219], off
	s_waitcnt vmcnt(0)
	v_mov_b32_e32 v8, v198
	v_mov_b32_e32 v9, v199
	v_lshl_add_u64 v[10:11], v[56:57], 0, v[22:23]
	v_lshl_add_u64 v[10:11], v[10:11], 0, v[152:153]
	v_lshl_add_u64 v[10:11], v[10:11], 0, v[136:137]
	v_lshlrev_b32_e32 v12, 16, v8
	v_and_b32_e32 v13, 0xffff0000, v8
	v_lshlrev_b32_e32 v8, 16, v9
	v_and_b32_e32 v9, 0xffff0000, v9
	v_pk_fma_f32 v[6:7], v[6:7], v[98:99], v[8:9]
	v_pk_fma_f32 v[4:5], v[4:5], v[96:97], v[12:13]
	s_nop 0
	v_cvt_pk_bf16_f32 v4, v4, v5
	v_cvt_pk_bf16_f32 v5, v6, v7
	global_store_dwordx2 v[14:15], v[4:5], off
	v_mov_b32_e32 v4, v200
	v_mov_b32_e32 v5, v201
	v_lshlrev_b32_e32 v6, 16, v4
	v_and_b32_e32 v7, 0xffff0000, v4
	v_lshlrev_b32_e32 v4, 16, v5
	v_and_b32_e32 v5, 0xffff0000, v5
	v_pk_fma_f32 v[2:3], v[2:3], v[90:91], v[4:5]
	v_pk_fma_f32 v[0:1], v[0:1], v[88:89], v[6:7]
	s_nop 0
	v_cvt_pk_bf16_f32 v0, v0, v1
	v_cvt_pk_bf16_f32 v1, v2, v3
	global_store_dwordx2 v[10:11], v[0:1], off
	s_cbranch_vccnz .LBB0_1089
	s_andn2_b64 vcc, exec, s[26:27]
	s_cbranch_vccnz .LBB0_1088
	s_barrier
	s_branch .LBB0_1088

; __device__ __forceinline__ unsigned pk_bf16(float lo, float hi) { f32x2 v = {lo, hi}; bf16x2_t b = __builtin_convertvector(v, bf16x2_t); return __builtin_bit_cast(unsigned, b); }
; __device__ __forceinline__ f32x4 unpack4(u32x2 w) { return (f32x4){bf_lo(w.x), bf_hi(w.x), bf_lo(w.y), bf_hi(w.y)}; }
;     __device__ __forceinline__ void operator()(const f32x4 (&acc)[2][2][4][2], const Unit& u, int wr, int wc, int fr, int fq) const {
;         const int rowl = u.pm * BM + wr * 64 + fr, b = u.pm >> 3;
;         const int c0 = u.pn * BM + wc * 32 + 4 * fq;
;         f32x4 gv[2][2];
; #pragma unroll
;         for (int bj = 0; bj < 2; ++bj)
; #pragma unroll
;             for (int n = 0; n < 2; ++n) gv[bj][n] = *(const f32x4*)(gate + (size_t)b * NMOD + c0 + bj * HALF + n * 16);
; #pragma unroll
;         for (int ai = 0; ai < 2; ++ai)
; #pragma unroll
;             for (int m = 0; m < 4; ++m) { const int rr = rowl + ai * HALF + m * 16;
; #pragma unroll
;                 for (int bj = 0; bj < 2; ++bj)
; #pragma unroll
;                     for (int n = 0; n < 2; ++n) { const int c = c0 + bj * HALF + n * 16; char* xp = (char*)xr + blk_off(rr, c, DM / 64);
;                         const f32x4 bs = base_f32 ? *(const f32x4*)(base_f32 + (size_t)rr * DM + c) : unpack4(*(const u32x2*)xp);
;                         const f32x4 o = bs + gv[bj][n] * acc[ai][bj][m][n];
;                         u32x2 w; w.x = pk_bf16(o[0], o[1]); w.y = pk_bf16(o[2], o[3]);
;                         *(u32x2*)xp = w; } }
.LBB0_1488:
	s_lshl_b32 s9, s4, 8
	s_add_i32 s9, s9, s62
	v_or_b32_e32 v182, s9, v176
	s_ashr_i32 s4, s4, 3
	v_lshl_or_b32 v172, s73, 8, v178
	v_lshlrev_b32_e32 v88, 6, v182
	s_mul_hi_i32 s7, s4, 0xc000
	s_mul_i32 s4, s4, 0xc000
	v_and_b32_e32 v192, 0x3c0, v88
	v_ashrrev_i32_e32 v88, 6, v172
	s_add_u32 s6, s60, s4
	v_ashrrev_i32_e32 v89, 31, v88
	s_addc_u32 s7, s61, s7
	s_ashr_i32 s34, s9, 7
	v_lshlrev_b64 v[88:89], 14, v[88:89]
	s_ashr_i32 s35, s34, 31
	v_lshl_add_u64 v[158:159], s[10:11], 0, v[88:89]
	v_lshlrev_b32_e32 v88, 2, v182
	s_lshl_b64 s[40:41], s[34:35], 19
	v_lshlrev_b32_e32 v90, 1, v172
	v_and_b32_e32 v193, 32, v88
	v_and_b32_e32 v183, 16, v90
	v_lshl_add_u64 v[160:161], v[158:159], 0, s[40:41]
	v_or_b32_e32 v188, v193, v192
	v_lshl_add_u64 v[168:169], v[160:161], 0, s[22:23]
	v_or_b32_e32 v162, v188, v183
	v_mov_b32_e32 v163, v149
	v_and_b32_e32 v148, 8, v90
	v_lshl_add_u64 v[88:89], v[168:169], 0, v[162:163]
	v_lshl_add_u64 v[170:171], v[88:89], 0, v[148:149]
	v_ashrrev_i32_e32 v173, 31, v172
	v_mov_b32_e32 v240, v172
	v_mov_b32_e32 v241, v173
	v_mov_b32_e32 v238, v188
	v_mov_b32_e32 v239, v189
	v_mov_b32_e32 v236, v192
	v_mov_b32_e32 v237, v193
	global_load_dwordx2 v[196:197], v[170:171], off
	v_or_b32_e32 v204, 32, v183
	v_mov_b32_e32 v207, v149
	v_bitop3_b32 v206, v192, v193, v204 bitop3:0x36
	v_lshl_add_u64 v[208:209], v[168:169], 0, v[206:207]
	v_lshl_add_u64 v[210:211], v[208:209], 0, v[148:149]
	v_mov_b32_e32 v213, v149
	v_mov_b32_e32 v209, v149
	global_load_dwordx2 v[198:199], v[210:211], off
	v_or_b32_e32 v214, 0x80, v172
	v_ashrrev_i32_e32 v216, 6, v214
	v_ashrrev_i32_e32 v217, 31, v216
	v_lshlrev_b64 v[216:217], 14, v[216:217]
	v_lshlrev_b32_e32 v208, 1, v214
	v_lshl_add_u64 v[216:217], s[10:11], 0, v[216:217]
	v_and_b32_e32 v205, 16, v208
	v_lshl_add_u64 v[224:225], v[216:217], 0, s[40:41]
	v_and_b32_e32 v214, 8, v208
	v_or_b32_e32 v208, v188, v205
	v_lshl_add_u64 v[226:227], v[224:225], 0, s[22:23]
	v_mov_b32_e32 v215, v149
	v_lshl_add_u64 v[226:227], v[226:227], 0, v[208:209]
	v_lshl_add_u64 v[226:227], v[226:227], 0, v[214:215]
	global_load_dwordx2 v[200:201], v[226:227], off
	v_or_b32_e32 v228, 0x90, v172
	v_ashrrev_i32_e32 v230, 6, v228
	v_ashrrev_i32_e32 v231, 31, v230
	v_lshlrev_b64 v[230:231], 14, v[230:231]
	v_lshlrev_b32_e32 v212, 1, v228
	v_lshl_add_u64 v[230:231], s[10:11], 0, v[230:231]
	v_and_b32_e32 v210, 48, v212
	v_lshl_add_u64 v[232:233], v[230:231], 0, s[40:41]
	v_and_b32_e32 v228, 8, v212
	v_bitop3_b32 v212, v192, v193, v210 bitop3:0x36
	v_lshl_add_u64 v[234:235], v[232:233], 0, s[22:23]
	v_mov_b32_e32 v229, v149
	v_lshl_add_u64 v[234:235], v[234:235], 0, v[212:213]
	v_lshl_add_u64 v[234:235], v[234:235], 0, v[228:229]
	global_load_dwordx2 v[202:203], v[234:235], off
	s_waitcnt vmcnt(0)
	v_mov_b32_e32 v174, v196
	v_mov_b32_e32 v175, v197
	v_lshl_add_u64 v[88:89], v[172:173], 2, s[6:7]
	global_load_dwordx4 v[112:115], v[88:89], off
	v_or_b32_e32 v184, 32, v183
	v_mov_b32_e32 v167, v149
	v_bitop3_b32 v166, v192, v193, v184 bitop3:0x36
	v_lshl_add_u64 v[168:169], v[168:169], 0, v[166:167]
	v_lshl_add_u64 v[186:187], v[168:169], 0, v[148:149]
	global_load_dwordx4 v[108:111], v[88:89], off offset:64
	global_load_dwordx4 v[96:99], v[88:89], off offset:512
	s_nop 0
	global_load_dwordx4 v[88:91], v[88:89], off offset:576
	v_mov_b32_e32 v173, v149
	s_or_b32 s4, s9, 16
	s_lshr_b32 s4, s4, 3
	s_and_b32 s4, s4, 10
	s_or_b32 s4, s4, s65
	s_lshl_b32 s4, s4, 10
	s_andn2_b64 vcc, exec, s[2:3]
	s_mov_b64 s[2:3], -1
	s_waitcnt vmcnt(0)
	v_lshlrev_b32_e32 v168, 16, v174
	v_and_b32_e32 v169, 0xffff0000, v174
	v_lshlrev_b32_e32 v174, 16, v175
	v_and_b32_e32 v175, 0xffff0000, v175
	v_pk_fma_f32 v[142:143], v[142:143], v[114:115], v[174:175]
	v_pk_fma_f32 v[140:141], v[140:141], v[112:113], v[168:169]
	v_mov_b32_e32 v169, v149
	v_cvt_pk_bf16_f32 v140, v140, v141
	v_cvt_pk_bf16_f32 v141, v142, v143
	global_store_dwordx2 v[170:171], v[140:141], off
	v_mov_b32_e32 v174, v198
	v_mov_b32_e32 v175, v199
	v_or_b32_e32 v140, 0x80, v172
	v_ashrrev_i32_e32 v142, 6, v140
	v_ashrrev_i32_e32 v143, 31, v142
	v_lshlrev_b64 v[142:143], 14, v[142:143]
	v_lshlrev_b32_e32 v168, 1, v140
	v_lshl_add_u64 v[142:143], s[10:11], 0, v[142:143]
	v_and_b32_e32 v185, 16, v168
	v_lshl_add_u64 v[170:171], v[142:143], 0, s[40:41]
	v_and_b32_e32 v140, 8, v168
	v_or_b32_e32 v168, v188, v185
	v_lshl_add_u64 v[188:189], v[170:171], 0, s[22:23]
	v_mov_b32_e32 v141, v149
	v_lshl_add_u64 v[188:189], v[188:189], 0, v[168:169]
	v_lshl_add_u64 v[188:189], v[188:189], 0, v[140:141]
	v_lshlrev_b32_e32 v190, 16, v174
	v_and_b32_e32 v191, 0xffff0000, v174
	v_lshlrev_b32_e32 v174, 16, v175
	v_and_b32_e32 v175, 0xffff0000, v175
	v_pk_fma_f32 v[138:139], v[138:139], v[110:111], v[174:175]
	v_pk_fma_f32 v[136:137], v[136:137], v[108:109], v[190:191]
	s_nop 0
	v_cvt_pk_bf16_f32 v136, v136, v137
	v_cvt_pk_bf16_f32 v137, v138, v139
	global_store_dwordx2 v[186:187], v[136:137], off
	v_mov_b32_e32 v190, v200
	v_mov_b32_e32 v191, v201
	v_or_b32_e32 v136, 0x90, v172
	v_ashrrev_i32_e32 v138, 6, v136
	v_ashrrev_i32_e32 v139, 31, v138
	v_lshlrev_b64 v[138:139], 14, v[138:139]
	v_lshlrev_b32_e32 v172, 1, v136
	v_lshl_add_u64 v[138:139], s[10:11], 0, v[138:139]
	v_and_b32_e32 v186, 48, v172
	v_lshl_add_u64 v[174:175], v[138:139], 0, s[40:41]
	v_and_b32_e32 v136, 8, v172
	v_bitop3_b32 v172, v192, v193, v186 bitop3:0x36
	v_lshl_add_u64 v[192:193], v[174:175], 0, s[22:23]
	v_mov_b32_e32 v137, v149
	v_lshl_add_u64 v[192:193], v[192:193], 0, v[172:173]
	v_lshl_add_u64 v[192:193], v[192:193], 0, v[136:137]
	v_lshlrev_b32_e32 v194, 16, v190
	v_and_b32_e32 v195, 0xffff0000, v190
; __device__ __forceinline__ unsigned pk_bf16(float lo, float hi) { f32x2 v = {lo, hi}; bf16x2_t b = __builtin_convertvector(v, bf16x2_t); return __builtin_bit_cast(unsigned, b); }
; __device__ __forceinline__ f32x4 unpack4(u32x2 w) { return (f32x4){bf_lo(w.x), bf_hi(w.x), bf_lo(w.y), bf_hi(w.y)}; }
;     __device__ __forceinline__ void operator()(const f32x4 (&acc)[2][2][4][2], const Unit& u, int wr, int wc, int fr, int fq) const {
;     ...
;             for (int m = 0; m < 4; ++m) { const int rr = rowl + ai * HALF + m * 16;
; #pragma unroll
;                 for (int bj = 0; bj < 2; ++bj)
; #pragma unroll
;                     for (int n = 0; n < 2; ++n) { const int c = c0 + bj * HALF + n * 16; char* xp = (char*)xr + blk_off(rr, c, DM / 64);
;                         const f32x4 bs = base_f32 ? *(const f32x4*)(base_f32 + (size_t)rr * DM + c) : unpack4(*(const u32x2*)xp);
;                         const f32x4 o = bs + gv[bj][n] * acc[ai][bj][m][n];
;                         u32x2 w; w.x = pk_bf16(o[0], o[1]); w.y = pk_bf16(o[2], o[3]);
;                         *(u32x2*)xp = w; } }
	v_lshlrev_b32_e32 v190, 16, v191
	v_and_b32_e32 v191, 0xffff0000, v191
	v_pk_fma_f32 v[134:135], v[134:135], v[98:99], v[190:191]
	v_pk_fma_f32 v[132:133], v[132:133], v[96:97], v[194:195]
	s_nop 0
	v_cvt_pk_bf16_f32 v132, v132, v133
	v_cvt_pk_bf16_f32 v133, v134, v135
	global_store_dwordx2 v[188:189], v[132:133], off
	v_mov_b32_e32 v132, v202
	v_mov_b32_e32 v133, v203
	v_lshl_add_u64 v[134:135], v[160:161], 0, s[4:5]
	v_lshl_add_u64 v[188:189], v[134:135], 0, v[162:163]
	v_lshl_add_u64 v[188:189], v[188:189], 0, v[148:149]
	v_lshlrev_b32_e32 v190, 16, v132
	v_and_b32_e32 v191, 0xffff0000, v132
	v_lshlrev_b32_e32 v132, 16, v133
	v_and_b32_e32 v133, 0xffff0000, v133
	v_pk_fma_f32 v[130:131], v[130:131], v[90:91], v[132:133]
	v_pk_fma_f32 v[128:129], v[128:129], v[88:89], v[190:191]
	s_nop 0
	v_cvt_pk_bf16_f32 v128, v128, v129
	v_cvt_pk_bf16_f32 v129, v130, v131
	global_store_dwordx2 v[192:193], v[128:129], off
	s_mov_b32 s99, s5
	v_or_b32_e32 v204, 32, v183
	v_mov_b32_e32 v207, v149
	v_bitop3_b32 v206, v236, v237, v204 bitop3:0x36
	v_mov_b32_e32 v209, v149
	s_or_b32 s98, s9, 16
	s_lshr_b32 s98, s98, 3
	s_and_b32 s98, s98, 10
	s_or_b32 s98, s98, s65
	s_lshl_b32 s98, s98, 10
	v_mov_b32_e32 v211, v149
	v_or_b32_e32 v212, 0x80, v240
	v_ashrrev_i32_e32 v214, 6, v212
	v_ashrrev_i32_e32 v215, 31, v214
	v_lshlrev_b64 v[214:215], 14, v[214:215]
	v_lshlrev_b32_e32 v210, 1, v212
	v_lshl_add_u64 v[214:215], s[10:11], 0, v[214:215]
	v_and_b32_e32 v205, 16, v210
	v_lshl_add_u64 v[216:217], v[214:215], 0, s[40:41]
	v_and_b32_e32 v212, 8, v210
	v_or_b32_e32 v210, v238, v205
	v_mov_b32_e32 v213, v149
	v_or_b32_e32 v224, 0x90, v240
	v_ashrrev_i32_e32 v226, 6, v224
	v_ashrrev_i32_e32 v227, 31, v226
	v_lshlrev_b64 v[226:227], 14, v[226:227]
	v_lshlrev_b32_e32 v208, 1, v224
	v_lshl_add_u64 v[226:227], s[10:11], 0, v[226:227]
	v_and_b32_e32 v228, 48, v208
	v_lshl_add_u64 v[230:231], v[226:227], 0, s[40:41]
	v_and_b32_e32 v224, 8, v208
	v_bitop3_b32 v208, v236, v237, v228 bitop3:0x36
	v_mov_b32_e32 v225, v149
	v_lshl_add_u64 v[232:233], v[160:161], 0, s[98:99]
	v_lshl_add_u64 v[234:235], v[232:233], 0, v[162:163]
	v_lshl_add_u64 v[234:235], v[234:235], 0, v[148:149]
	global_load_dwordx2 v[196:197], v[234:235], off
	v_lshl_add_u64 v[214:215], v[232:233], 0, v[206:207]
	v_lshl_add_u64 v[214:215], v[214:215], 0, v[148:149]
	global_load_dwordx2 v[198:199], v[214:215], off
	v_lshl_add_u64 v[204:205], v[216:217], 0, s[98:99]
	v_lshl_add_u64 v[204:205], v[204:205], 0, v[210:211]
	v_lshl_add_u64 v[204:205], v[204:205], 0, v[212:213]
	global_load_dwordx2 v[200:201], v[204:205], off
	v_lshl_add_u64 v[226:227], v[230:231], 0, s[98:99]
	v_lshl_add_u64 v[226:227], v[226:227], 0, v[208:209]
	v_lshl_add_u64 v[226:227], v[226:227], 0, v[224:225]
	global_load_dwordx2 v[202:203], v[226:227], off
	s_waitcnt vmcnt(0)
	v_mov_b32_e32 v128, v196
	v_mov_b32_e32 v129, v197
	v_lshl_add_u64 v[130:131], v[134:135], 0, v[166:167]
	v_lshl_add_u64 v[130:131], v[130:131], 0, v[148:149]
	v_lshlrev_b32_e32 v132, 16, v128
	v_and_b32_e32 v133, 0xffff0000, v128
	v_lshlrev_b32_e32 v128, 16, v129
	v_and_b32_e32 v129, 0xffff0000, v129
	v_pk_fma_f32 v[126:127], v[126:127], v[114:115], v[128:129]
	v_pk_fma_f32 v[124:125], v[124:125], v[112:113], v[132:133]
	s_nop 0
	v_cvt_pk_bf16_f32 v124, v124, v125
	v_cvt_pk_bf16_f32 v125, v126, v127
	global_store_dwordx2 v[188:189], v[124:125], off
	v_mov_b32_e32 v124, v198
	v_mov_b32_e32 v125, v199
	v_lshl_add_u64 v[126:127], v[170:171], 0, s[4:5]
	v_lshl_add_u64 v[126:127], v[126:127], 0, v[168:169]
	v_lshl_add_u64 v[126:127], v[126:127], 0, v[140:141]
	v_lshlrev_b32_e32 v128, 16, v124
	v_and_b32_e32 v129, 0xffff0000, v124
	v_lshlrev_b32_e32 v124, 16, v125
	v_and_b32_e32 v125, 0xffff0000, v125
	v_pk_fma_f32 v[122:123], v[122:123], v[110:111], v[124:125]
	v_pk_fma_f32 v[120:121], v[120:121], v[108:109], v[128:129]
	s_nop 0
	v_cvt_pk_bf16_f32 v120, v120, v121
	v_cvt_pk_bf16_f32 v121, v122, v123
	global_store_dwordx2 v[130:131], v[120:121], off
	v_mov_b32_e32 v120, v200
	v_mov_b32_e32 v121, v201
	v_lshl_add_u64 v[122:123], v[174:175], 0, s[4:5]
	v_lshl_add_u64 v[122:123], v[122:123], 0, v[172:173]
	v_lshl_add_u64 v[122:123], v[122:123], 0, v[136:137]
	s_or_b32 s4, s9, 32
	s_lshr_b32 s4, s4, 3
	s_and_b32 s4, s4, 12
	s_or_b32 s4, s4, s65
	s_lshl_b32 s4, s4, 10
	v_lshlrev_b32_e32 v124, 16, v120
	v_and_b32_e32 v125, 0xffff0000, v120
	v_lshlrev_b32_e32 v120, 16, v121
	v_and_b32_e32 v121, 0xffff0000, v121
	v_pk_fma_f32 v[118:119], v[118:119], v[98:99], v[120:121]
	v_pk_fma_f32 v[116:117], v[116:117], v[96:97], v[124:125]
	s_nop 0
	v_cvt_pk_bf16_f32 v116, v116, v117
	v_cvt_pk_bf16_f32 v117, v118, v119
	global_store_dwordx2 v[126:127], v[116:117], off
	v_mov_b32_e32 v116, v202
	v_mov_b32_e32 v117, v203
	v_lshl_add_u64 v[118:119], v[160:161], 0, s[4:5]
	v_lshl_add_u64 v[120:121], v[118:119], 0, v[162:163]
	v_lshl_add_u64 v[120:121], v[120:121], 0, v[148:149]
	v_lshlrev_b32_e32 v124, 16, v116
	v_and_b32_e32 v125, 0xffff0000, v116
	v_lshlrev_b32_e32 v116, 16, v117
	v_and_b32_e32 v117, 0xffff0000, v117
	v_pk_fma_f32 v[106:107], v[106:107], v[90:91], v[116:117]
	v_pk_fma_f32 v[104:105], v[104:105], v[88:89], v[124:125]
	s_nop 0
	v_cvt_pk_bf16_f32 v104, v104, v105
	v_cvt_pk_bf16_f32 v105, v106, v107
	global_store_dwordx2 v[122:123], v[104:105], off
	s_mov_b32 s99, s5
	v_or_b32_e32 v204, 32, v183
	v_mov_b32_e32 v207, v149
	v_bitop3_b32 v206, v236, v237, v204 bitop3:0x36
	v_mov_b32_e32 v209, v149
	v_mov_b32_e32 v211, v149
	v_or_b32_e32 v212, 0x80, v240
	v_ashrrev_i32_e32 v214, 6, v212
	v_ashrrev_i32_e32 v215, 31, v214
	v_lshlrev_b64 v[214:215], 14, v[214:215]
	v_lshlrev_b32_e32 v210, 1, v212
; __device__ __forceinline__ unsigned pk_bf16(float lo, float hi) { f32x2 v = {lo, hi}; bf16x2_t b = __builtin_convertvector(v, bf16x2_t); return __builtin_bit_cast(unsigned, b); }
; __device__ __forceinline__ f32x4 unpack4(u32x2 w) { return (f32x4){bf_lo(w.x), bf_hi(w.x), bf_lo(w.y), bf_hi(w.y)}; }
;     __device__ __forceinline__ void operator()(const f32x4 (&acc)[2][2][4][2], const Unit& u, int wr, int wc, int fr, int fq) const {
;     ...
;             for (int m = 0; m < 4; ++m) { const int rr = rowl + ai * HALF + m * 16;
; #pragma unroll
;                 for (int bj = 0; bj < 2; ++bj)
; #pragma unroll
;                     for (int n = 0; n < 2; ++n) { const int c = c0 + bj * HALF + n * 16; char* xp = (char*)xr + blk_off(rr, c, DM / 64);
;                         const f32x4 bs = base_f32 ? *(const f32x4*)(base_f32 + (size_t)rr * DM + c) : unpack4(*(const u32x2*)xp);
;                         const f32x4 o = bs + gv[bj][n] * acc[ai][bj][m][n];
;                         u32x2 w; w.x = pk_bf16(o[0], o[1]); w.y = pk_bf16(o[2], o[3]);
;                         *(u32x2*)xp = w; } }
	v_lshl_add_u64 v[214:215], s[10:11], 0, v[214:215]
	v_and_b32_e32 v205, 16, v210
	v_lshl_add_u64 v[216:217], v[214:215], 0, s[40:41]
	v_and_b32_e32 v212, 8, v210
	v_or_b32_e32 v210, v238, v205
	v_mov_b32_e32 v213, v149
	v_or_b32_e32 v224, 0x90, v240
	v_ashrrev_i32_e32 v226, 6, v224
	v_ashrrev_i32_e32 v227, 31, v226
	v_lshlrev_b64 v[226:227], 14, v[226:227]
	v_lshlrev_b32_e32 v208, 1, v224
	v_lshl_add_u64 v[226:227], s[10:11], 0, v[226:227]
	v_and_b32_e32 v228, 48, v208
	v_lshl_add_u64 v[230:231], v[226:227], 0, s[40:41]
	v_and_b32_e32 v224, 8, v208
	v_bitop3_b32 v208, v236, v237, v228 bitop3:0x36
	v_mov_b32_e32 v225, v149
	s_or_b32 s98, s9, 32
	s_lshr_b32 s98, s98, 3
	s_and_b32 s98, s98, 12
	s_or_b32 s98, s98, s65
	s_lshl_b32 s98, s98, 10
	v_lshl_add_u64 v[232:233], v[160:161], 0, s[98:99]
	v_lshl_add_u64 v[234:235], v[232:233], 0, v[162:163]
	v_lshl_add_u64 v[234:235], v[234:235], 0, v[148:149]
	global_load_dwordx2 v[196:197], v[234:235], off
	v_lshl_add_u64 v[214:215], v[232:233], 0, v[206:207]
	v_lshl_add_u64 v[214:215], v[214:215], 0, v[148:149]
	global_load_dwordx2 v[198:199], v[214:215], off
	v_lshl_add_u64 v[204:205], v[216:217], 0, s[98:99]
	v_lshl_add_u64 v[204:205], v[204:205], 0, v[210:211]
	v_lshl_add_u64 v[204:205], v[204:205], 0, v[212:213]
	global_load_dwordx2 v[200:201], v[204:205], off
	v_lshl_add_u64 v[226:227], v[230:231], 0, s[98:99]
	v_lshl_add_u64 v[226:227], v[226:227], 0, v[208:209]
	v_lshl_add_u64 v[226:227], v[226:227], 0, v[224:225]
	global_load_dwordx2 v[202:203], v[226:227], off
	s_waitcnt vmcnt(0)
	v_mov_b32_e32 v104, v196
	v_mov_b32_e32 v105, v197
	v_lshl_add_u64 v[106:107], v[118:119], 0, v[166:167]
	v_lshl_add_u64 v[106:107], v[106:107], 0, v[148:149]
	v_lshlrev_b32_e32 v116, 16, v104
	v_and_b32_e32 v117, 0xffff0000, v104
	v_lshlrev_b32_e32 v104, 16, v105
	v_and_b32_e32 v105, 0xffff0000, v105
	v_pk_fma_f32 v[102:103], v[102:103], v[114:115], v[104:105]
	v_pk_fma_f32 v[100:101], v[100:101], v[112:113], v[116:117]
	s_nop 0
	v_cvt_pk_bf16_f32 v100, v100, v101
	v_cvt_pk_bf16_f32 v101, v102, v103
	global_store_dwordx2 v[120:121], v[100:101], off
	v_mov_b32_e32 v100, v198
	v_mov_b32_e32 v101, v199
	v_lshl_add_u64 v[102:103], v[170:171], 0, s[4:5]
	v_lshl_add_u64 v[102:103], v[102:103], 0, v[168:169]
	v_lshl_add_u64 v[102:103], v[102:103], 0, v[140:141]
	v_lshlrev_b32_e32 v104, 16, v100
	v_and_b32_e32 v105, 0xffff0000, v100
	v_lshlrev_b32_e32 v100, 16, v101
	v_and_b32_e32 v101, 0xffff0000, v101
	v_pk_fma_f32 v[94:95], v[94:95], v[110:111], v[100:101]
	v_pk_fma_f32 v[92:93], v[92:93], v[108:109], v[104:105]
	s_nop 0
	v_cvt_pk_bf16_f32 v92, v92, v93
	v_cvt_pk_bf16_f32 v93, v94, v95
	global_store_dwordx2 v[106:107], v[92:93], off
	v_mov_b32_e32 v92, v200
	v_mov_b32_e32 v93, v201
	v_lshl_add_u64 v[94:95], v[174:175], 0, s[4:5]
	v_lshl_add_u64 v[94:95], v[94:95], 0, v[172:173]
	v_lshl_add_u64 v[94:95], v[94:95], 0, v[136:137]
	s_or_b32 s4, s9, 48
	s_lshr_b32 s4, s4, 3
	s_and_b32 s4, s4, 14
	s_or_b32 s4, s4, s65
	s_lshl_b32 s4, s4, 10
	v_lshlrev_b32_e32 v100, 16, v92
	v_and_b32_e32 v101, 0xffff0000, v92
	v_lshlrev_b32_e32 v92, 16, v93
	v_and_b32_e32 v93, 0xffff0000, v93
	v_pk_fma_f32 v[86:87], v[86:87], v[98:99], v[92:93]
	v_pk_fma_f32 v[84:85], v[84:85], v[96:97], v[100:101]
	s_nop 0
	v_cvt_pk_bf16_f32 v84, v84, v85
	v_cvt_pk_bf16_f32 v85, v86, v87
	global_store_dwordx2 v[102:103], v[84:85], off
	v_mov_b32_e32 v84, v202
	v_mov_b32_e32 v85, v203
	v_lshl_add_u64 v[86:87], v[160:161], 0, s[4:5]
	v_lshl_add_u64 v[92:93], v[86:87], 0, v[162:163]
	v_lshl_add_u64 v[92:93], v[92:93], 0, v[148:149]
	v_lshlrev_b32_e32 v100, 16, v84
	v_and_b32_e32 v101, 0xffff0000, v84
	v_lshlrev_b32_e32 v84, 16, v85
	v_and_b32_e32 v85, 0xffff0000, v85
	v_pk_fma_f32 v[82:83], v[82:83], v[90:91], v[84:85]
	v_pk_fma_f32 v[80:81], v[80:81], v[88:89], v[100:101]
	s_nop 0
	v_cvt_pk_bf16_f32 v80, v80, v81
	v_cvt_pk_bf16_f32 v81, v82, v83
	global_store_dwordx2 v[94:95], v[80:81], off
	s_mov_b32 s99, s5
	v_or_b32_e32 v204, 32, v183
	v_mov_b32_e32 v207, v149
	v_bitop3_b32 v206, v236, v237, v204 bitop3:0x36
	v_mov_b32_e32 v209, v149
	v_mov_b32_e32 v211, v149
	v_or_b32_e32 v212, 0x80, v240
	v_ashrrev_i32_e32 v214, 6, v212
	v_ashrrev_i32_e32 v215, 31, v214
	v_lshlrev_b64 v[214:215], 14, v[214:215]
	v_lshlrev_b32_e32 v210, 1, v212
	v_lshl_add_u64 v[214:215], s[10:11], 0, v[214:215]
	v_and_b32_e32 v205, 16, v210
	v_lshl_add_u64 v[216:217], v[214:215], 0, s[40:41]
	v_and_b32_e32 v212, 8, v210
	v_or_b32_e32 v210, v238, v205
	v_mov_b32_e32 v213, v149
	v_or_b32_e32 v224, 0x90, v240
	v_ashrrev_i32_e32 v226, 6, v224
	v_ashrrev_i32_e32 v227, 31, v226
	v_lshlrev_b64 v[226:227], 14, v[226:227]
	v_lshlrev_b32_e32 v208, 1, v224
	v_lshl_add_u64 v[226:227], s[10:11], 0, v[226:227]
	v_and_b32_e32 v228, 48, v208
	v_lshl_add_u64 v[230:231], v[226:227], 0, s[40:41]
	v_and_b32_e32 v224, 8, v208
	v_bitop3_b32 v208, v236, v237, v228 bitop3:0x36
	v_mov_b32_e32 v225, v149
	s_or_b32 s98, s9, 48
	s_lshr_b32 s98, s98, 3
	s_and_b32 s98, s98, 14
	s_or_b32 s98, s98, s65
	s_lshl_b32 s98, s98, 10
	v_lshl_add_u64 v[232:233], v[160:161], 0, s[98:99]
	v_lshl_add_u64 v[234:235], v[232:233], 0, v[162:163]
	v_lshl_add_u64 v[234:235], v[234:235], 0, v[148:149]
	global_load_dwordx2 v[196:197], v[234:235], off
	v_lshl_add_u64 v[214:215], v[232:233], 0, v[206:207]
	v_lshl_add_u64 v[214:215], v[214:215], 0, v[148:149]
	global_load_dwordx2 v[198:199], v[214:215], off
	v_lshl_add_u64 v[204:205], v[216:217], 0, s[98:99]
	v_lshl_add_u64 v[204:205], v[204:205], 0, v[210:211]
	v_lshl_add_u64 v[204:205], v[204:205], 0, v[212:213]
	global_load_dwordx2 v[200:201], v[204:205], off
	v_lshl_add_u64 v[226:227], v[230:231], 0, s[98:99]
	v_lshl_add_u64 v[226:227], v[226:227], 0, v[208:209]
	v_lshl_add_u64 v[226:227], v[226:227], 0, v[224:225]
	global_load_dwordx2 v[202:203], v[226:227], off
	s_waitcnt vmcnt(0)
; __device__ __forceinline__ unsigned pk_bf16(float lo, float hi) { f32x2 v = {lo, hi}; bf16x2_t b = __builtin_convertvector(v, bf16x2_t); return __builtin_bit_cast(unsigned, b); }
; __device__ __forceinline__ f32x4 unpack4(u32x2 w) { return (f32x4){bf_lo(w.x), bf_hi(w.x), bf_lo(w.y), bf_hi(w.y)}; }
;     __device__ __forceinline__ void operator()(const f32x4 (&acc)[2][2][4][2], const Unit& u, int wr, int wc, int fr, int fq) const {
;     ...
;             for (int m = 0; m < 4; ++m) { const int rr = rowl + ai * HALF + m * 16;
; #pragma unroll
;                 for (int bj = 0; bj < 2; ++bj)
; #pragma unroll
;                     for (int n = 0; n < 2; ++n) { const int c = c0 + bj * HALF + n * 16; char* xp = (char*)xr + blk_off(rr, c, DM / 64);
;                         const f32x4 bs = base_f32 ? *(const f32x4*)(base_f32 + (size_t)rr * DM + c) : unpack4(*(const u32x2*)xp);
;                         const f32x4 o = bs + gv[bj][n] * acc[ai][bj][m][n];
;                         u32x2 w; w.x = pk_bf16(o[0], o[1]); w.y = pk_bf16(o[2], o[3]);
;                         *(u32x2*)xp = w; } }
	v_mov_b32_e32 v80, v196
	v_mov_b32_e32 v81, v197
	v_lshl_add_u64 v[82:83], v[86:87], 0, v[166:167]
	v_lshl_add_u64 v[82:83], v[82:83], 0, v[148:149]
	v_lshlrev_b32_e32 v84, 16, v80
	v_and_b32_e32 v85, 0xffff0000, v80
	v_lshlrev_b32_e32 v80, 16, v81
	v_and_b32_e32 v81, 0xffff0000, v81
	v_pk_fma_f32 v[78:79], v[78:79], v[114:115], v[80:81]
	v_pk_fma_f32 v[76:77], v[76:77], v[112:113], v[84:85]
	s_nop 0
	v_cvt_pk_bf16_f32 v76, v76, v77
	v_cvt_pk_bf16_f32 v77, v78, v79
	global_store_dwordx2 v[92:93], v[76:77], off
	v_mov_b32_e32 v76, v198
	v_mov_b32_e32 v77, v199
	v_lshl_add_u64 v[78:79], v[170:171], 0, s[4:5]
	v_lshl_add_u64 v[78:79], v[78:79], 0, v[168:169]
	v_lshl_add_u64 v[78:79], v[78:79], 0, v[140:141]
	v_lshlrev_b32_e32 v80, 16, v76
	v_and_b32_e32 v81, 0xffff0000, v76
	v_lshlrev_b32_e32 v76, 16, v77
	v_and_b32_e32 v77, 0xffff0000, v77
	v_pk_fma_f32 v[74:75], v[74:75], v[110:111], v[76:77]
	v_pk_fma_f32 v[72:73], v[72:73], v[108:109], v[80:81]
	s_nop 0
	v_cvt_pk_bf16_f32 v72, v72, v73
	v_cvt_pk_bf16_f32 v73, v74, v75
	global_store_dwordx2 v[82:83], v[72:73], off
	v_mov_b32_e32 v72, v200
	v_mov_b32_e32 v73, v201
	v_lshl_add_u64 v[74:75], v[174:175], 0, s[4:5]
	v_lshl_add_u64 v[74:75], v[74:75], 0, v[172:173]
	v_lshl_add_u64 v[74:75], v[74:75], 0, v[136:137]
	v_lshlrev_b32_e32 v76, 16, v72
	v_and_b32_e32 v77, 0xffff0000, v72
	v_lshlrev_b32_e32 v72, 16, v73
	v_and_b32_e32 v73, 0xffff0000, v73
	v_pk_fma_f32 v[70:71], v[70:71], v[98:99], v[72:73]
	v_pk_fma_f32 v[68:69], v[68:69], v[96:97], v[76:77]
	v_mov_b32_e32 v73, v149
	v_cvt_pk_bf16_f32 v68, v68, v69
	v_cvt_pk_bf16_f32 v69, v70, v71
	global_store_dwordx2 v[78:79], v[68:69], off
	v_mov_b32_e32 v70, v202
	v_mov_b32_e32 v71, v203
	v_add_u32_e32 v69, 0x80, v182
	v_ashrrev_i32_e32 v68, 7, v69
	v_lshlrev_b32_e32 v72, 6, v69
	v_lshlrev_b32_e32 v76, 2, v69
	v_ashrrev_i32_e32 v69, 31, v68
	v_and_b32_e32 v82, 0x3c0, v72
	v_and_b32_e32 v83, 32, v76
	v_lshlrev_b64 v[76:77], 19, v[68:69]
	v_or_b32_e32 v84, v83, v82
	v_lshl_add_u64 v[68:69], v[158:159], 0, v[76:77]
	v_or_b32_e32 v72, v84, v183
	v_lshl_add_u64 v[78:79], v[68:69], 0, s[22:23]
	v_lshl_add_u64 v[72:73], v[78:79], 0, v[72:73]
	v_lshl_add_u64 v[72:73], v[72:73], 0, v[148:149]
	v_lshlrev_b32_e32 v80, 16, v70
	v_and_b32_e32 v81, 0xffff0000, v70
	v_lshlrev_b32_e32 v70, 16, v71
	v_and_b32_e32 v71, 0xffff0000, v71
	v_pk_fma_f32 v[66:67], v[66:67], v[90:91], v[70:71]
	v_pk_fma_f32 v[64:65], v[64:65], v[88:89], v[80:81]
	s_nop 0
	v_cvt_pk_bf16_f32 v64, v64, v65
	v_cvt_pk_bf16_f32 v65, v66, v67
	global_store_dwordx2 v[74:75], v[64:65], off
	v_or_b32_e32 v204, 32, v183
	v_or_b32_e32 v206, 0x80, v240
	v_ashrrev_i32_e32 v208, 6, v206
	v_ashrrev_i32_e32 v209, 31, v208
	v_lshlrev_b64 v[208:209], 14, v[208:209]
	v_lshlrev_b32_e32 v210, 1, v206
	v_lshl_add_u64 v[208:209], s[10:11], 0, v[208:209]
	v_and_b32_e32 v205, 16, v210
	v_and_b32_e32 v206, 8, v210
	v_mov_b32_e32 v207, v149
	v_or_b32_e32 v212, 0x90, v240
	v_ashrrev_i32_e32 v214, 6, v212
	v_ashrrev_i32_e32 v215, 31, v214
	v_lshlrev_b64 v[214:215], 14, v[214:215]
	v_lshlrev_b32_e32 v216, 1, v212
	v_lshl_add_u64 v[214:215], s[10:11], 0, v[214:215]
	v_and_b32_e32 v224, 48, v216
	v_and_b32_e32 v212, 8, v216
	v_mov_b32_e32 v213, v149
	v_mov_b32_e32 v227, v149
	v_add_u32_e32 v229, 0x80, v182
	v_ashrrev_i32_e32 v228, 7, v229
	v_lshlrev_b32_e32 v226, 6, v229
	v_lshlrev_b32_e32 v230, 2, v229
	v_ashrrev_i32_e32 v229, 31, v228
	v_and_b32_e32 v232, 0x3c0, v226
	v_and_b32_e32 v233, 32, v230
	v_lshlrev_b64 v[230:231], 19, v[228:229]
	v_or_b32_e32 v234, v233, v232
	v_lshl_add_u64 v[228:229], v[158:159], 0, v[230:231]
	v_or_b32_e32 v226, v234, v183
	v_lshl_add_u64 v[210:211], v[228:229], 0, s[22:23]
	v_lshl_add_u64 v[226:227], v[210:211], 0, v[226:227]
	v_lshl_add_u64 v[226:227], v[226:227], 0, v[148:149]
	global_load_dwordx2 v[196:197], v[226:227], off
	v_mov_b32_e32 v217, v149
	v_bitop3_b32 v216, v232, v233, v204 bitop3:0x36
	v_lshl_add_u64 v[216:217], v[210:211], 0, v[216:217]
	v_lshl_add_u64 v[216:217], v[216:217], 0, v[148:149]
	v_mov_b32_e32 v229, v149
	global_load_dwordx2 v[198:199], v[216:217], off
	v_lshl_add_u64 v[226:227], v[208:209], 0, v[230:231]
	v_or_b32_e32 v228, v234, v205
	v_lshl_add_u64 v[210:211], v[226:227], 0, s[22:23]
	v_lshl_add_u64 v[228:229], v[210:211], 0, v[228:229]
	v_lshl_add_u64 v[228:229], v[228:229], 0, v[206:207]
	v_mov_b32_e32 v209, v149
	global_load_dwordx2 v[200:201], v[228:229], off
	v_lshl_add_u64 v[204:205], v[214:215], 0, v[230:231]
	v_bitop3_b32 v208, v232, v233, v224 bitop3:0x36
	v_lshl_add_u64 v[216:217], v[204:205], 0, s[22:23]
	v_lshl_add_u64 v[208:209], v[216:217], 0, v[208:209]
	v_lshl_add_u64 v[208:209], v[208:209], 0, v[212:213]
	global_load_dwordx2 v[202:203], v[208:209], off
	s_waitcnt vmcnt(0)
; __device__ __forceinline__ unsigned pk_bf16(float lo, float hi) { f32x2 v = {lo, hi}; bf16x2_t b = __builtin_convertvector(v, bf16x2_t); return __builtin_bit_cast(unsigned, b); }
; __device__ __forceinline__ f32x4 unpack4(u32x2 w) { return (f32x4){bf_lo(w.x), bf_hi(w.x), bf_lo(w.y), bf_hi(w.y)}; }
;     __device__ __forceinline__ void operator()(const f32x4 (&acc)[2][2][4][2], const Unit& u, int wr, int wc, int fr, int fq) const {
;     ...
;             for (int m = 0; m < 4; ++m) { const int rr = rowl + ai * HALF + m * 16;
; #pragma unroll
;                 for (int bj = 0; bj < 2; ++bj)
; #pragma unroll
;                     for (int n = 0; n < 2; ++n) { const int c = c0 + bj * HALF + n * 16; char* xp = (char*)xr + blk_off(rr, c, DM / 64);
;                         const f32x4 bs = base_f32 ? *(const f32x4*)(base_f32 + (size_t)rr * DM + c) : unpack4(*(const u32x2*)xp);
;                         const f32x4 o = bs + gv[bj][n] * acc[ai][bj][m][n];
;                         u32x2 w; w.x = pk_bf16(o[0], o[1]); w.y = pk_bf16(o[2], o[3]);
;                         *(u32x2*)xp = w; } }
	v_mov_b32_e32 v64, v196
	v_mov_b32_e32 v65, v197
	v_mov_b32_e32 v67, v149
	v_bitop3_b32 v66, v82, v83, v184 bitop3:0x36
	v_lshl_add_u64 v[66:67], v[78:79], 0, v[66:67]
	v_lshl_add_u64 v[66:67], v[66:67], 0, v[148:149]
	v_lshlrev_b32_e32 v70, 16, v64
	v_and_b32_e32 v71, 0xffff0000, v64
	v_lshlrev_b32_e32 v64, 16, v65
	v_and_b32_e32 v65, 0xffff0000, v65
	v_pk_fma_f32 v[62:63], v[62:63], v[114:115], v[64:65]
	v_pk_fma_f32 v[60:61], v[60:61], v[112:113], v[70:71]
	v_mov_b32_e32 v65, v149
	v_cvt_pk_bf16_f32 v60, v60, v61
	v_cvt_pk_bf16_f32 v61, v62, v63
	global_store_dwordx2 v[72:73], v[60:61], off
	v_mov_b32_e32 v62, v198
	v_mov_b32_e32 v63, v199
	v_lshl_add_u64 v[60:61], v[142:143], 0, v[76:77]
	v_or_b32_e32 v64, v84, v185
	v_lshl_add_u64 v[70:71], v[60:61], 0, s[22:23]
	v_lshl_add_u64 v[64:65], v[70:71], 0, v[64:65]
	v_lshl_add_u64 v[64:65], v[64:65], 0, v[140:141]
	v_lshlrev_b32_e32 v70, 16, v62
	v_and_b32_e32 v71, 0xffff0000, v62
	v_lshlrev_b32_e32 v62, 16, v63
	v_and_b32_e32 v63, 0xffff0000, v63
	v_pk_fma_f32 v[58:59], v[58:59], v[110:111], v[62:63]
	v_pk_fma_f32 v[56:57], v[56:57], v[108:109], v[70:71]
	v_mov_b32_e32 v63, v149
	v_cvt_pk_bf16_f32 v56, v56, v57
	v_cvt_pk_bf16_f32 v57, v58, v59
	global_store_dwordx2 v[66:67], v[56:57], off
	v_mov_b32_e32 v58, v200
	v_mov_b32_e32 v59, v201
	v_lshl_add_u64 v[56:57], v[138:139], 0, v[76:77]
	v_bitop3_b32 v62, v82, v83, v186 bitop3:0x36
	v_lshl_add_u64 v[66:67], v[56:57], 0, s[22:23]
	v_lshl_add_u64 v[62:63], v[66:67], 0, v[62:63]
	v_lshl_add_u64 v[62:63], v[62:63], 0, v[136:137]
	v_lshlrev_b32_e32 v66, 16, v58
	v_and_b32_e32 v67, 0xffff0000, v58
	v_lshlrev_b32_e32 v58, 16, v59
	v_and_b32_e32 v59, 0xffff0000, v59
	v_pk_fma_f32 v[54:55], v[54:55], v[98:99], v[58:59]
	v_pk_fma_f32 v[52:53], v[52:53], v[96:97], v[66:67]
	v_mov_b32_e32 v59, v149
	v_cvt_pk_bf16_f32 v52, v52, v53
	v_cvt_pk_bf16_f32 v53, v54, v55
	global_store_dwordx2 v[64:65], v[52:53], off
	v_mov_b32_e32 v52, v202
	v_mov_b32_e32 v53, v203
	v_add_u32_e32 v54, 0x90, v182
	v_lshrrev_b32_e32 v58, 3, v54
	v_lshlrev_b32_e32 v64, 6, v54
	v_lshlrev_b32_e32 v54, 2, v54
	v_and_or_b32 v58, v58, 10, s65
	v_and_b32_e32 v70, 0x3c0, v64
	v_and_b32_e32 v71, 32, v54
	v_mov_b32_e32 v55, v149
	v_lshlrev_b32_e32 v54, 10, v58
	v_or_b32_e32 v72, v71, v70
	v_or_b32_e32 v58, v72, v183
	v_lshl_add_u64 v[64:65], v[68:69], 0, v[54:55]
	v_lshl_add_u64 v[58:59], v[64:65], 0, v[58:59]
	v_lshl_add_u64 v[58:59], v[58:59], 0, v[148:149]
	v_lshlrev_b32_e32 v66, 16, v52
	v_and_b32_e32 v67, 0xffff0000, v52
	v_lshlrev_b32_e32 v52, 16, v53
	v_and_b32_e32 v53, 0xffff0000, v53
	v_pk_fma_f32 v[50:51], v[50:51], v[90:91], v[52:53]
	v_pk_fma_f32 v[48:49], v[48:49], v[88:89], v[66:67]
	s_nop 0
	v_cvt_pk_bf16_f32 v48, v48, v49
	v_cvt_pk_bf16_f32 v49, v50, v51
	global_store_dwordx2 v[62:63], v[48:49], off
	v_or_b32_e32 v204, 32, v183
	v_or_b32_e32 v206, 0x80, v240
	v_ashrrev_i32_e32 v208, 6, v206
	v_ashrrev_i32_e32 v209, 31, v208
	v_lshlrev_b64 v[208:209], 14, v[208:209]
	v_lshlrev_b32_e32 v210, 1, v206
	v_lshl_add_u64 v[208:209], s[10:11], 0, v[208:209]
	v_and_b32_e32 v205, 16, v210
	v_and_b32_e32 v206, 8, v210
	v_mov_b32_e32 v207, v149
	v_or_b32_e32 v212, 0x90, v240
	v_ashrrev_i32_e32 v214, 6, v212
	v_ashrrev_i32_e32 v215, 31, v214
	v_lshlrev_b64 v[214:215], 14, v[214:215]
	v_lshlrev_b32_e32 v216, 1, v212
	v_lshl_add_u64 v[214:215], s[10:11], 0, v[214:215]
	v_and_b32_e32 v224, 48, v216
	v_and_b32_e32 v212, 8, v216
	v_mov_b32_e32 v213, v149
	v_add_u32_e32 v227, 0x80, v182
	v_ashrrev_i32_e32 v226, 7, v227
	v_ashrrev_i32_e32 v227, 31, v226
	v_lshlrev_b64 v[228:229], 19, v[226:227]
	v_lshl_add_u64 v[226:227], v[158:159], 0, v[228:229]
	v_lshl_add_u64 v[230:231], v[208:209], 0, v[228:229]
	v_lshl_add_u64 v[232:233], v[214:215], 0, v[228:229]
	v_mov_b32_e32 v235, v149
	v_add_u32_e32 v210, 0x90, v182
	v_lshrrev_b32_e32 v234, 3, v210
	v_lshlrev_b32_e32 v216, 6, v210
	v_lshlrev_b32_e32 v210, 2, v210
	v_and_or_b32 v234, v234, 10, s65
	v_and_b32_e32 v208, 0x3c0, v216
	v_and_b32_e32 v209, 32, v210
	v_mov_b32_e32 v211, v149
	v_lshlrev_b32_e32 v210, 10, v234
	v_or_b32_e32 v214, v209, v208
	v_or_b32_e32 v234, v214, v183
	v_lshl_add_u64 v[216:217], v[226:227], 0, v[210:211]
	v_lshl_add_u64 v[234:235], v[216:217], 0, v[234:235]
	v_lshl_add_u64 v[234:235], v[234:235], 0, v[148:149]
	global_load_dwordx2 v[196:197], v[234:235], off
	v_mov_b32_e32 v229, v149
	v_bitop3_b32 v228, v208, v209, v204 bitop3:0x36
	v_lshl_add_u64 v[228:229], v[216:217], 0, v[228:229]
	v_lshl_add_u64 v[228:229], v[228:229], 0, v[148:149]
	v_lshl_add_u64 v[226:227], v[230:231], 0, v[210:211]
	global_load_dwordx2 v[198:199], v[228:229], off
	v_mov_b32_e32 v235, v149
	v_or_b32_e32 v234, v214, v205
	v_lshl_add_u64 v[234:235], v[226:227], 0, v[234:235]
	v_lshl_add_u64 v[234:235], v[234:235], 0, v[206:207]
	v_lshl_add_u64 v[216:217], v[232:233], 0, v[210:211]
	global_load_dwordx2 v[200:201], v[234:235], off
	v_mov_b32_e32 v231, v149
	v_bitop3_b32 v230, v208, v209, v224 bitop3:0x36
	v_lshl_add_u64 v[230:231], v[216:217], 0, v[230:231]
	v_lshl_add_u64 v[230:231], v[230:231], 0, v[212:213]
	global_load_dwordx2 v[202:203], v[230:231], off
	s_waitcnt vmcnt(0)
; __device__ __forceinline__ unsigned pk_bf16(float lo, float hi) { f32x2 v = {lo, hi}; bf16x2_t b = __builtin_convertvector(v, bf16x2_t); return __builtin_bit_cast(unsigned, b); }
; __device__ __forceinline__ f32x4 unpack4(u32x2 w) { return (f32x4){bf_lo(w.x), bf_hi(w.x), bf_lo(w.y), bf_hi(w.y)}; }
;     __device__ __forceinline__ void operator()(const f32x4 (&acc)[2][2][4][2], const Unit& u, int wr, int wc, int fr, int fq) const {
;     ...
;             for (int m = 0; m < 4; ++m) { const int rr = rowl + ai * HALF + m * 16;
; #pragma unroll
;                 for (int bj = 0; bj < 2; ++bj)
; #pragma unroll
;                     for (int n = 0; n < 2; ++n) { const int c = c0 + bj * HALF + n * 16; char* xp = (char*)xr + blk_off(rr, c, DM / 64);
;                         const f32x4 bs = base_f32 ? *(const f32x4*)(base_f32 + (size_t)rr * DM + c) : unpack4(*(const u32x2*)xp);
;                         const f32x4 o = bs + gv[bj][n] * acc[ai][bj][m][n];
;                         u32x2 w; w.x = pk_bf16(o[0], o[1]); w.y = pk_bf16(o[2], o[3]);
;                         *(u32x2*)xp = w; } }
	v_mov_b32_e32 v48, v196
	v_mov_b32_e32 v49, v197
	v_mov_b32_e32 v51, v149
	v_bitop3_b32 v50, v70, v71, v184 bitop3:0x36
	v_lshl_add_u64 v[50:51], v[64:65], 0, v[50:51]
	v_lshl_add_u64 v[50:51], v[50:51], 0, v[148:149]
	v_lshlrev_b32_e32 v52, 16, v48
	v_and_b32_e32 v53, 0xffff0000, v48
	v_lshlrev_b32_e32 v48, 16, v49
	v_and_b32_e32 v49, 0xffff0000, v49
	v_pk_fma_f32 v[46:47], v[46:47], v[114:115], v[48:49]
	v_pk_fma_f32 v[44:45], v[44:45], v[112:113], v[52:53]
	v_lshl_add_u64 v[48:49], v[60:61], 0, v[54:55]
	v_cvt_pk_bf16_f32 v44, v44, v45
	v_cvt_pk_bf16_f32 v45, v46, v47
	global_store_dwordx2 v[58:59], v[44:45], off
	v_mov_b32_e32 v44, v198
	v_mov_b32_e32 v45, v199
	v_mov_b32_e32 v47, v149
	v_or_b32_e32 v46, v72, v185
	v_lshl_add_u64 v[46:47], v[48:49], 0, v[46:47]
	v_lshl_add_u64 v[46:47], v[46:47], 0, v[140:141]
	v_lshlrev_b32_e32 v48, 16, v44
	v_and_b32_e32 v49, 0xffff0000, v44
	v_lshlrev_b32_e32 v44, 16, v45
	v_and_b32_e32 v45, 0xffff0000, v45
	v_pk_fma_f32 v[42:43], v[42:43], v[110:111], v[44:45]
	v_pk_fma_f32 v[40:41], v[40:41], v[108:109], v[48:49]
	v_lshl_add_u64 v[44:45], v[56:57], 0, v[54:55]
	v_cvt_pk_bf16_f32 v40, v40, v41
	v_cvt_pk_bf16_f32 v41, v42, v43
	global_store_dwordx2 v[50:51], v[40:41], off
	v_mov_b32_e32 v40, v200
	v_mov_b32_e32 v41, v201
	v_mov_b32_e32 v43, v149
	v_bitop3_b32 v42, v70, v71, v186 bitop3:0x36
	v_lshl_add_u64 v[42:43], v[44:45], 0, v[42:43]
	v_lshl_add_u64 v[42:43], v[42:43], 0, v[136:137]
	v_lshlrev_b32_e32 v44, 16, v40
	v_and_b32_e32 v45, 0xffff0000, v40
	v_lshlrev_b32_e32 v40, 16, v41
	v_and_b32_e32 v41, 0xffff0000, v41
	v_pk_fma_f32 v[38:39], v[38:39], v[98:99], v[40:41]
	v_pk_fma_f32 v[36:37], v[36:37], v[96:97], v[44:45]
	v_mov_b32_e32 v41, v149
	v_cvt_pk_bf16_f32 v36, v36, v37
	v_cvt_pk_bf16_f32 v37, v38, v39
	global_store_dwordx2 v[46:47], v[36:37], off
	v_mov_b32_e32 v36, v202
	v_mov_b32_e32 v37, v203
	v_add_u32_e32 v38, 0xa0, v182
	v_lshrrev_b32_e32 v40, 3, v38
	v_lshlrev_b32_e32 v44, 6, v38
	v_lshlrev_b32_e32 v38, 2, v38
	v_and_or_b32 v40, v40, 12, s65
	v_and_b32_e32 v48, 0x3c0, v44
	v_and_b32_e32 v49, 32, v38
	v_mov_b32_e32 v39, v149
	v_lshlrev_b32_e32 v38, 10, v40
	v_or_b32_e32 v50, v49, v48
	v_or_b32_e32 v40, v50, v183
	v_lshl_add_u64 v[44:45], v[68:69], 0, v[38:39]
	v_lshl_add_u64 v[40:41], v[44:45], 0, v[40:41]
	v_lshl_add_u64 v[40:41], v[40:41], 0, v[148:149]
	v_lshlrev_b32_e32 v46, 16, v36
	v_and_b32_e32 v47, 0xffff0000, v36
	v_lshlrev_b32_e32 v36, 16, v37
	v_and_b32_e32 v37, 0xffff0000, v37
	v_pk_fma_f32 v[34:35], v[34:35], v[90:91], v[36:37]
	v_pk_fma_f32 v[32:33], v[32:33], v[88:89], v[46:47]
	s_nop 0
	v_cvt_pk_bf16_f32 v32, v32, v33
	v_cvt_pk_bf16_f32 v33, v34, v35
	global_store_dwordx2 v[42:43], v[32:33], off
	v_or_b32_e32 v204, 32, v183
	v_or_b32_e32 v206, 0x80, v240
	v_ashrrev_i32_e32 v208, 6, v206
	v_ashrrev_i32_e32 v209, 31, v208
	v_lshlrev_b64 v[208:209], 14, v[208:209]
	v_lshlrev_b32_e32 v210, 1, v206
	v_lshl_add_u64 v[208:209], s[10:11], 0, v[208:209]
	v_and_b32_e32 v205, 16, v210
	v_and_b32_e32 v206, 8, v210
	v_mov_b32_e32 v207, v149
	v_or_b32_e32 v212, 0x90, v240
	v_ashrrev_i32_e32 v214, 6, v212
	v_ashrrev_i32_e32 v215, 31, v214
	v_lshlrev_b64 v[214:215], 14, v[214:215]
	v_lshlrev_b32_e32 v216, 1, v212
	v_lshl_add_u64 v[214:215], s[10:11], 0, v[214:215]
	v_and_b32_e32 v224, 48, v216
	v_and_b32_e32 v212, 8, v216
	v_mov_b32_e32 v213, v149
	v_add_u32_e32 v227, 0x80, v182
	v_ashrrev_i32_e32 v226, 7, v227
	v_ashrrev_i32_e32 v227, 31, v226
	v_lshlrev_b64 v[228:229], 19, v[226:227]
	v_lshl_add_u64 v[226:227], v[158:159], 0, v[228:229]
	v_lshl_add_u64 v[230:231], v[208:209], 0, v[228:229]
	v_lshl_add_u64 v[232:233], v[214:215], 0, v[228:229]
	v_mov_b32_e32 v235, v149
	v_add_u32_e32 v210, 0xa0, v182
	v_lshrrev_b32_e32 v234, 3, v210
	v_lshlrev_b32_e32 v216, 6, v210
	v_lshlrev_b32_e32 v210, 2, v210
	v_and_or_b32 v234, v234, 12, s65
	v_and_b32_e32 v208, 0x3c0, v216
	v_and_b32_e32 v209, 32, v210
	v_mov_b32_e32 v211, v149
	v_lshlrev_b32_e32 v210, 10, v234
	v_or_b32_e32 v214, v209, v208
	v_or_b32_e32 v234, v214, v183
	v_lshl_add_u64 v[216:217], v[226:227], 0, v[210:211]
	v_lshl_add_u64 v[234:235], v[216:217], 0, v[234:235]
	v_lshl_add_u64 v[234:235], v[234:235], 0, v[148:149]
	global_load_dwordx2 v[196:197], v[234:235], off
	v_mov_b32_e32 v229, v149
	v_bitop3_b32 v228, v208, v209, v204 bitop3:0x36
	v_lshl_add_u64 v[228:229], v[216:217], 0, v[228:229]
	v_lshl_add_u64 v[228:229], v[228:229], 0, v[148:149]
	v_lshl_add_u64 v[226:227], v[230:231], 0, v[210:211]
	global_load_dwordx2 v[198:199], v[228:229], off
	v_mov_b32_e32 v235, v149
	v_or_b32_e32 v234, v214, v205
	v_lshl_add_u64 v[234:235], v[226:227], 0, v[234:235]
	v_lshl_add_u64 v[234:235], v[234:235], 0, v[206:207]
	v_lshl_add_u64 v[216:217], v[232:233], 0, v[210:211]
	global_load_dwordx2 v[200:201], v[234:235], off
	v_mov_b32_e32 v231, v149
	v_bitop3_b32 v230, v208, v209, v224 bitop3:0x36
	v_lshl_add_u64 v[230:231], v[216:217], 0, v[230:231]
	v_lshl_add_u64 v[230:231], v[230:231], 0, v[212:213]
	global_load_dwordx2 v[202:203], v[230:231], off
	s_waitcnt vmcnt(0)
; __device__ __forceinline__ unsigned pk_bf16(float lo, float hi) { f32x2 v = {lo, hi}; bf16x2_t b = __builtin_convertvector(v, bf16x2_t); return __builtin_bit_cast(unsigned, b); }
; __device__ __forceinline__ f32x4 unpack4(u32x2 w) { return (f32x4){bf_lo(w.x), bf_hi(w.x), bf_lo(w.y), bf_hi(w.y)}; }
;     __device__ __forceinline__ void operator()(const f32x4 (&acc)[2][2][4][2], const Unit& u, int wr, int wc, int fr, int fq) const {
;     ...
;             for (int m = 0; m < 4; ++m) { const int rr = rowl + ai * HALF + m * 16;
; #pragma unroll
;                 for (int bj = 0; bj < 2; ++bj)
; #pragma unroll
;                     for (int n = 0; n < 2; ++n) { const int c = c0 + bj * HALF + n * 16; char* xp = (char*)xr + blk_off(rr, c, DM / 64);
;                         const f32x4 bs = base_f32 ? *(const f32x4*)(base_f32 + (size_t)rr * DM + c) : unpack4(*(const u32x2*)xp);
;                         const f32x4 o = bs + gv[bj][n] * acc[ai][bj][m][n];
;                         u32x2 w; w.x = pk_bf16(o[0], o[1]); w.y = pk_bf16(o[2], o[3]);
;                         *(u32x2*)xp = w; } }
	v_mov_b32_e32 v32, v196
	v_mov_b32_e32 v33, v197
	v_mov_b32_e32 v35, v149
	v_bitop3_b32 v34, v48, v49, v184 bitop3:0x36
	v_lshl_add_u64 v[34:35], v[44:45], 0, v[34:35]
	v_lshl_add_u64 v[34:35], v[34:35], 0, v[148:149]
	v_lshlrev_b32_e32 v36, 16, v32
	v_and_b32_e32 v37, 0xffff0000, v32
	v_lshlrev_b32_e32 v32, 16, v33
	v_and_b32_e32 v33, 0xffff0000, v33
	v_pk_fma_f32 v[30:31], v[30:31], v[114:115], v[32:33]
	v_pk_fma_f32 v[28:29], v[28:29], v[112:113], v[36:37]
	v_lshl_add_u64 v[32:33], v[60:61], 0, v[38:39]
	v_cvt_pk_bf16_f32 v28, v28, v29
	v_cvt_pk_bf16_f32 v29, v30, v31
	global_store_dwordx2 v[40:41], v[28:29], off
	v_mov_b32_e32 v28, v198
	v_mov_b32_e32 v29, v199
	v_mov_b32_e32 v31, v149
	v_or_b32_e32 v30, v50, v185
	v_lshl_add_u64 v[30:31], v[32:33], 0, v[30:31]
	v_lshl_add_u64 v[30:31], v[30:31], 0, v[140:141]
	v_lshlrev_b32_e32 v32, 16, v28
	v_and_b32_e32 v33, 0xffff0000, v28
	v_lshlrev_b32_e32 v28, 16, v29
	v_and_b32_e32 v29, 0xffff0000, v29
	v_pk_fma_f32 v[26:27], v[26:27], v[110:111], v[28:29]
	v_pk_fma_f32 v[24:25], v[24:25], v[108:109], v[32:33]
	v_lshl_add_u64 v[28:29], v[56:57], 0, v[38:39]
	v_cvt_pk_bf16_f32 v24, v24, v25
	v_cvt_pk_bf16_f32 v25, v26, v27
	global_store_dwordx2 v[34:35], v[24:25], off
	v_mov_b32_e32 v24, v200
	v_mov_b32_e32 v25, v201
	v_mov_b32_e32 v27, v149
	v_bitop3_b32 v26, v48, v49, v186 bitop3:0x36
	v_lshl_add_u64 v[26:27], v[28:29], 0, v[26:27]
	v_lshl_add_u64 v[26:27], v[26:27], 0, v[136:137]
	v_lshlrev_b32_e32 v28, 16, v24
	v_and_b32_e32 v29, 0xffff0000, v24
	v_lshlrev_b32_e32 v24, 16, v25
	v_and_b32_e32 v25, 0xffff0000, v25
	v_pk_fma_f32 v[22:23], v[22:23], v[98:99], v[24:25]
	v_pk_fma_f32 v[20:21], v[20:21], v[96:97], v[28:29]
	v_mov_b32_e32 v25, v149
	v_cvt_pk_bf16_f32 v20, v20, v21
	v_cvt_pk_bf16_f32 v21, v22, v23
	global_store_dwordx2 v[30:31], v[20:21], off
	v_mov_b32_e32 v20, v202
	v_mov_b32_e32 v21, v203
	v_add_u32_e32 v22, 0xb0, v182
	v_lshrrev_b32_e32 v24, 3, v22
	v_lshlrev_b32_e32 v28, 6, v22
	v_lshlrev_b32_e32 v22, 2, v22
	v_and_or_b32 v24, v24, 14, s65
	v_and_b32_e32 v32, 0x3c0, v28
	v_and_b32_e32 v33, 32, v22
	v_mov_b32_e32 v23, v149
	v_lshlrev_b32_e32 v22, 10, v24
	v_or_b32_e32 v34, v33, v32
	v_or_b32_e32 v24, v34, v183
	v_lshl_add_u64 v[28:29], v[68:69], 0, v[22:23]
	v_lshl_add_u64 v[24:25], v[28:29], 0, v[24:25]
	v_lshl_add_u64 v[24:25], v[24:25], 0, v[148:149]
	v_lshlrev_b32_e32 v30, 16, v20
	v_and_b32_e32 v31, 0xffff0000, v20
	v_lshlrev_b32_e32 v20, 16, v21
	v_and_b32_e32 v21, 0xffff0000, v21
	v_pk_fma_f32 v[18:19], v[18:19], v[90:91], v[20:21]
	v_pk_fma_f32 v[16:17], v[16:17], v[88:89], v[30:31]
	s_nop 0
	v_cvt_pk_bf16_f32 v16, v16, v17
	v_cvt_pk_bf16_f32 v17, v18, v19
	global_store_dwordx2 v[26:27], v[16:17], off
	v_or_b32_e32 v204, 32, v183
	v_or_b32_e32 v206, 0x80, v240
	v_ashrrev_i32_e32 v208, 6, v206
	v_ashrrev_i32_e32 v209, 31, v208
	v_lshlrev_b64 v[208:209], 14, v[208:209]
	v_lshlrev_b32_e32 v210, 1, v206
	v_lshl_add_u64 v[208:209], s[10:11], 0, v[208:209]
	v_and_b32_e32 v205, 16, v210
	v_and_b32_e32 v206, 8, v210
	v_mov_b32_e32 v207, v149
	v_or_b32_e32 v212, 0x90, v240
	v_ashrrev_i32_e32 v214, 6, v212
	v_ashrrev_i32_e32 v215, 31, v214
	v_lshlrev_b64 v[214:215], 14, v[214:215]
	v_lshlrev_b32_e32 v216, 1, v212
	v_lshl_add_u64 v[214:215], s[10:11], 0, v[214:215]
	v_and_b32_e32 v224, 48, v216
	v_and_b32_e32 v212, 8, v216
	v_mov_b32_e32 v213, v149
	v_add_u32_e32 v227, 0x80, v182
	v_ashrrev_i32_e32 v226, 7, v227
	v_ashrrev_i32_e32 v227, 31, v226
	v_lshlrev_b64 v[228:229], 19, v[226:227]
	v_lshl_add_u64 v[226:227], v[158:159], 0, v[228:229]
	v_lshl_add_u64 v[230:231], v[208:209], 0, v[228:229]
	v_lshl_add_u64 v[232:233], v[214:215], 0, v[228:229]
	v_mov_b32_e32 v235, v149
	v_add_u32_e32 v210, 0xb0, v182
	v_lshrrev_b32_e32 v234, 3, v210
	v_lshlrev_b32_e32 v216, 6, v210
	v_lshlrev_b32_e32 v210, 2, v210
	v_and_or_b32 v234, v234, 14, s65
	v_and_b32_e32 v208, 0x3c0, v216
	v_and_b32_e32 v209, 32, v210
	v_mov_b32_e32 v211, v149
	v_lshlrev_b32_e32 v210, 10, v234
	v_or_b32_e32 v214, v209, v208
	v_or_b32_e32 v234, v214, v183
	v_lshl_add_u64 v[216:217], v[226:227], 0, v[210:211]
	v_lshl_add_u64 v[234:235], v[216:217], 0, v[234:235]
	v_lshl_add_u64 v[234:235], v[234:235], 0, v[148:149]
	global_load_dwordx2 v[196:197], v[234:235], off
	v_mov_b32_e32 v229, v149
	v_bitop3_b32 v228, v208, v209, v204 bitop3:0x36
	v_lshl_add_u64 v[228:229], v[216:217], 0, v[228:229]
	v_lshl_add_u64 v[228:229], v[228:229], 0, v[148:149]
	v_or_b32_e32 v226, v214, v205
	global_load_dwordx2 v[198:199], v[228:229], off
	v_lshl_add_u64 v[234:235], v[230:231], 0, v[210:211]
	v_mov_b32_e32 v227, v149
	v_lshl_add_u64 v[234:235], v[234:235], 0, v[226:227]
	v_lshl_add_u64 v[234:235], v[234:235], 0, v[206:207]
	v_bitop3_b32 v226, v208, v209, v224 bitop3:0x36
	global_load_dwordx2 v[200:201], v[234:235], off
	v_lshl_add_u64 v[216:217], v[232:233], 0, v[210:211]
	v_lshl_add_u64 v[216:217], v[216:217], 0, v[226:227]
	v_lshl_add_u64 v[216:217], v[216:217], 0, v[212:213]
	global_load_dwordx2 v[202:203], v[216:217], off
	s_waitcnt vmcnt(0)
; #define PG8_BAR __builtin_amdgcn_s_barrier()
; __device__ __forceinline__ unsigned pk_bf16(float lo, float hi) { f32x2 v = {lo, hi}; bf16x2_t b = __builtin_convertvector(v, bf16x2_t); return __builtin_bit_cast(unsigned, b); }
; __device__ __forceinline__ f32x4 unpack4(u32x2 w) { return (f32x4){bf_lo(w.x), bf_hi(w.x), bf_lo(w.y), bf_hi(w.y)}; }
; template <class Epi, class Sched, bool ALIGN_EPI = false, bool SP2 = false>
; __device__ __forceinline__ void gemm_phase(PG8_LAS unsigned char* lds, const Gemm g, const Sched& S, const Epi& E) {
;     ...
;         if (!has_next) break;
; #pragma unroll
;         for (int a = 0; a < 2; ++a)
; #pragma unroll
;             for (int b = 0; b < 2; ++b)
; #pragma unroll
;                 for (int m = 0; m < 4; ++m)
; #pragma unroll
;                     for (int n = 0; n < 2; ++n) acc[a][b][m][n] = (f32x4){0.f, 0.f, 0.f, 0.f};
;         cur = nxt; cA = nA; cB = nB; ++ui;
;         if constexpr (ALIGN_EPI) { if (wr == 1) PG8_BAR; }
;     __device__ __forceinline__ void operator()(const f32x4 (&acc)[2][2][4][2], const Unit& u, int wr, int wc, int fr, int fq) const {
;     ...
;             for (int m = 0; m < 4; ++m) { const int rr = rowl + ai * HALF + m * 16;
; #pragma unroll
;                 for (int bj = 0; bj < 2; ++bj)
; #pragma unroll
;                     for (int n = 0; n < 2; ++n) { const int c = c0 + bj * HALF + n * 16; char* xp = (char*)xr + blk_off(rr, c, DM / 64);
;                         const f32x4 bs = base_f32 ? *(const f32x4*)(base_f32 + (size_t)rr * DM + c) : unpack4(*(const u32x2*)xp);
;                         const f32x4 o = bs + gv[bj][n] * acc[ai][bj][m][n];
;                         u32x2 w; w.x = pk_bf16(o[0], o[1]); w.y = pk_bf16(o[2], o[3]);
;                         *(u32x2*)xp = w; } }
	v_mov_b32_e32 v16, v196
	v_mov_b32_e32 v17, v197
	v_mov_b32_e32 v19, v149
	v_bitop3_b32 v18, v32, v33, v184 bitop3:0x36
	v_lshl_add_u64 v[18:19], v[28:29], 0, v[18:19]
	v_lshl_add_u64 v[18:19], v[18:19], 0, v[148:149]
	v_or_b32_e32 v148, v34, v185
	v_lshlrev_b32_e32 v20, 16, v16
	v_and_b32_e32 v21, 0xffff0000, v16
	v_lshlrev_b32_e32 v16, 16, v17
	v_and_b32_e32 v17, 0xffff0000, v17
	v_pk_fma_f32 v[14:15], v[14:15], v[114:115], v[16:17]
	v_pk_fma_f32 v[12:13], v[12:13], v[112:113], v[20:21]
	s_nop 0
	v_cvt_pk_bf16_f32 v12, v12, v13
	v_cvt_pk_bf16_f32 v13, v14, v15
	global_store_dwordx2 v[24:25], v[12:13], off
	v_mov_b32_e32 v12, v198
	v_mov_b32_e32 v13, v199
	v_lshl_add_u64 v[14:15], v[60:61], 0, v[22:23]
	v_lshl_add_u64 v[14:15], v[14:15], 0, v[148:149]
	v_lshl_add_u64 v[14:15], v[14:15], 0, v[140:141]
	v_bitop3_b32 v148, v32, v33, v186 bitop3:0x36
	v_lshlrev_b32_e32 v16, 16, v12
	v_and_b32_e32 v17, 0xffff0000, v12
	v_lshlrev_b32_e32 v12, 16, v13
	v_and_b32_e32 v13, 0xffff0000, v13
	v_pk_fma_f32 v[10:11], v[10:11], v[110:111], v[12:13]
	v_pk_fma_f32 v[8:9], v[8:9], v[108:109], v[16:17]
	s_nop 0
	v_cvt_pk_bf16_f32 v8, v8, v9
	v_cvt_pk_bf16_f32 v9, v10, v11
	global_store_dwordx2 v[18:19], v[8:9], off
	v_mov_b32_e32 v8, v200
	v_mov_b32_e32 v9, v201
	v_lshl_add_u64 v[10:11], v[56:57], 0, v[22:23]
	v_lshl_add_u64 v[10:11], v[10:11], 0, v[148:149]
	v_lshl_add_u64 v[10:11], v[10:11], 0, v[136:137]
	v_lshlrev_b32_e32 v12, 16, v8
	v_and_b32_e32 v13, 0xffff0000, v8
	v_lshlrev_b32_e32 v8, 16, v9
	v_and_b32_e32 v9, 0xffff0000, v9
	v_pk_fma_f32 v[6:7], v[6:7], v[98:99], v[8:9]
	v_pk_fma_f32 v[4:5], v[4:5], v[96:97], v[12:13]
	s_nop 0
	v_cvt_pk_bf16_f32 v4, v4, v5
	v_cvt_pk_bf16_f32 v5, v6, v7
	global_store_dwordx2 v[14:15], v[4:5], off
	v_mov_b32_e32 v4, v202
	v_mov_b32_e32 v5, v203
	v_lshlrev_b32_e32 v6, 16, v4
	v_and_b32_e32 v7, 0xffff0000, v4
	v_lshlrev_b32_e32 v4, 16, v5
	v_and_b32_e32 v5, 0xffff0000, v5
	v_pk_fma_f32 v[2:3], v[2:3], v[90:91], v[4:5]
	v_pk_fma_f32 v[0:1], v[0:1], v[88:89], v[6:7]
	s_nop 0
	v_cvt_pk_bf16_f32 v0, v0, v1
	v_cvt_pk_bf16_f32 v1, v2, v3
	global_store_dwordx2 v[10:11], v[0:1], off
	s_cbranch_vccnz .LBB0_1477
	s_andn2_b64 vcc, exec, s[12:13]
	s_cbranch_vccnz .LBB0_1476
	s_barrier
	s_branch .LBB0_1476

; __device__ __forceinline__ unsigned pk_bf16(float lo, float hi) { f32x2 v = {lo, hi}; bf16x2_t b = __builtin_convertvector(v, bf16x2_t); return __builtin_bit_cast(unsigned, b); }
; __device__ __forceinline__ f32x4 unpack4(u32x2 w) { return (f32x4){bf_lo(w.x), bf_hi(w.x), bf_lo(w.y), bf_hi(w.y)}; }
;     __device__ __forceinline__ void operator()(const f32x4 (&acc)[2][2][4][2], const Unit& u, int wr, int wc, int fr, int fq) const {
;         const int rowl = u.pm * BM + wr * 64 + fr, b = u.pm >> 3;
;         const int c0 = u.pn * BM + wc * 32 + 4 * fq;
;         f32x4 gv[2][2];
; #pragma unroll
;         for (int bj = 0; bj < 2; ++bj)
; #pragma unroll
;             for (int n = 0; n < 2; ++n) gv[bj][n] = *(const f32x4*)(gate + (size_t)b * NMOD + c0 + bj * HALF + n * 16);
; #pragma unroll
;         for (int ai = 0; ai < 2; ++ai)
; #pragma unroll
;             for (int m = 0; m < 4; ++m) { const int rr = rowl + ai * HALF + m * 16;
; #pragma unroll
;                 for (int bj = 0; bj < 2; ++bj)
; #pragma unroll
;                     for (int n = 0; n < 2; ++n) { const int c = c0 + bj * HALF + n * 16; char* xp = (char*)xr + blk_off(rr, c, DM / 64);
;                         const f32x4 bs = base_f32 ? *(const f32x4*)(base_f32 + (size_t)rr * DM + c) : unpack4(*(const u32x2*)xp);
;                         const f32x4 o = bs + gv[bj][n] * acc[ai][bj][m][n];
;                         u32x2 w; w.x = pk_bf16(o[0], o[1]); w.y = pk_bf16(o[2], o[3]);
;                         *(u32x2*)xp = w; } }
.LBB0_1708:
	s_lshl_b32 s9, s4, 8
	s_add_i32 s9, s9, s68
	v_or_b32_e32 v180, s9, v174
	s_ashr_i32 s4, s4, 3
	v_lshl_or_b32 v170, s77, 8, v176
	v_lshlrev_b32_e32 v88, 6, v180
	s_mul_hi_i32 s7, s4, 0xc000
	s_mul_i32 s4, s4, 0xc000
	v_and_b32_e32 v190, 0x3c0, v88
	v_ashrrev_i32_e32 v88, 6, v170
	s_add_u32 s6, s66, s4
	v_ashrrev_i32_e32 v89, 31, v88
	s_addc_u32 s7, s67, s7
	s_ashr_i32 s34, s9, 7
	v_lshlrev_b64 v[88:89], 14, v[88:89]
	s_ashr_i32 s35, s34, 31
	v_lshl_add_u64 v[156:157], s[10:11], 0, v[88:89]
	v_lshlrev_b32_e32 v88, 2, v180
	s_lshl_b64 s[54:55], s[34:35], 19
	v_lshlrev_b32_e32 v90, 1, v170
	v_and_b32_e32 v191, 32, v88
	v_and_b32_e32 v181, 16, v90
	v_lshl_add_u64 v[158:159], v[156:157], 0, s[54:55]
	v_or_b32_e32 v186, v191, v190
	v_lshl_add_u64 v[166:167], v[158:159], 0, s[24:25]
	v_or_b32_e32 v160, v186, v181
	v_mov_b32_e32 v161, v149
	v_and_b32_e32 v148, 8, v90
	v_lshl_add_u64 v[88:89], v[166:167], 0, v[160:161]
	v_lshl_add_u64 v[168:169], v[88:89], 0, v[148:149]
	v_ashrrev_i32_e32 v171, 31, v170
	v_mov_b32_e32 v240, v170
	v_mov_b32_e32 v241, v171
	v_mov_b32_e32 v238, v186
	v_mov_b32_e32 v239, v187
	v_mov_b32_e32 v236, v190
	v_mov_b32_e32 v237, v191
	global_load_dwordx2 v[194:195], v[168:169], off
	v_or_b32_e32 v202, 32, v181
	v_mov_b32_e32 v205, v149
	v_bitop3_b32 v204, v190, v191, v202 bitop3:0x36
	v_lshl_add_u64 v[206:207], v[166:167], 0, v[204:205]
	v_lshl_add_u64 v[208:209], v[206:207], 0, v[148:149]
	v_mov_b32_e32 v211, v149
	v_mov_b32_e32 v207, v149
	global_load_dwordx2 v[196:197], v[208:209], off
	v_or_b32_e32 v220, 0x80, v170
	v_ashrrev_i32_e32 v222, 6, v220
	v_ashrrev_i32_e32 v223, 31, v222
	v_lshlrev_b64 v[222:223], 14, v[222:223]
	v_lshlrev_b32_e32 v206, 1, v220
	v_lshl_add_u64 v[222:223], s[10:11], 0, v[222:223]
	v_and_b32_e32 v203, 16, v206
	v_lshl_add_u64 v[224:225], v[222:223], 0, s[54:55]
	v_and_b32_e32 v220, 8, v206
	v_or_b32_e32 v206, v186, v203
	v_lshl_add_u64 v[226:227], v[224:225], 0, s[24:25]
	v_mov_b32_e32 v221, v149
	v_lshl_add_u64 v[226:227], v[226:227], 0, v[206:207]
	v_lshl_add_u64 v[226:227], v[226:227], 0, v[220:221]
	global_load_dwordx2 v[198:199], v[226:227], off
	v_or_b32_e32 v228, 0x90, v170
	v_ashrrev_i32_e32 v230, 6, v228
	v_ashrrev_i32_e32 v231, 31, v230
	v_lshlrev_b64 v[230:231], 14, v[230:231]
	v_lshlrev_b32_e32 v210, 1, v228
	v_lshl_add_u64 v[230:231], s[10:11], 0, v[230:231]
	v_and_b32_e32 v208, 48, v210
	v_lshl_add_u64 v[232:233], v[230:231], 0, s[54:55]
	v_and_b32_e32 v228, 8, v210
	v_bitop3_b32 v210, v190, v191, v208 bitop3:0x36
	v_lshl_add_u64 v[234:235], v[232:233], 0, s[24:25]
	v_mov_b32_e32 v229, v149
	v_lshl_add_u64 v[234:235], v[234:235], 0, v[210:211]
	v_lshl_add_u64 v[234:235], v[234:235], 0, v[228:229]
	global_load_dwordx2 v[200:201], v[234:235], off
	s_waitcnt vmcnt(0)
	v_mov_b32_e32 v172, v194
	v_mov_b32_e32 v173, v195
	v_lshl_add_u64 v[88:89], v[170:171], 2, s[6:7]
	global_load_dwordx4 v[112:115], v[88:89], off
	v_or_b32_e32 v182, 32, v181
	v_mov_b32_e32 v163, v149
	v_bitop3_b32 v162, v190, v191, v182 bitop3:0x36
	v_lshl_add_u64 v[166:167], v[166:167], 0, v[162:163]
	v_lshl_add_u64 v[184:185], v[166:167], 0, v[148:149]
	global_load_dwordx4 v[108:111], v[88:89], off offset:64
	global_load_dwordx4 v[96:99], v[88:89], off offset:512
	s_nop 0
	global_load_dwordx4 v[88:91], v[88:89], off offset:576
	v_mov_b32_e32 v171, v149
	s_or_b32 s4, s9, 16
	s_lshr_b32 s4, s4, 3
	s_and_b32 s4, s4, 10
	s_or_b32 s4, s4, s71
	s_lshl_b32 s4, s4, 10
	s_andn2_b64 vcc, exec, s[2:3]
	s_mov_b64 s[2:3], -1
	s_waitcnt vmcnt(0)
	v_lshlrev_b32_e32 v166, 16, v172
	v_and_b32_e32 v167, 0xffff0000, v172
	v_lshlrev_b32_e32 v172, 16, v173
	v_and_b32_e32 v173, 0xffff0000, v173
	v_pk_fma_f32 v[142:143], v[142:143], v[114:115], v[172:173]
	v_pk_fma_f32 v[140:141], v[140:141], v[112:113], v[166:167]
	v_mov_b32_e32 v167, v149
	v_cvt_pk_bf16_f32 v140, v140, v141
	v_cvt_pk_bf16_f32 v141, v142, v143
	global_store_dwordx2 v[168:169], v[140:141], off
	v_mov_b32_e32 v172, v196
	v_mov_b32_e32 v173, v197
	v_or_b32_e32 v140, 0x80, v170
	v_ashrrev_i32_e32 v142, 6, v140
	v_ashrrev_i32_e32 v143, 31, v142
	v_lshlrev_b64 v[142:143], 14, v[142:143]
	v_lshlrev_b32_e32 v166, 1, v140
	v_lshl_add_u64 v[142:143], s[10:11], 0, v[142:143]
	v_and_b32_e32 v183, 16, v166
	v_lshl_add_u64 v[168:169], v[142:143], 0, s[54:55]
	v_and_b32_e32 v140, 8, v166
	v_or_b32_e32 v166, v186, v183
	v_lshl_add_u64 v[186:187], v[168:169], 0, s[24:25]
	v_mov_b32_e32 v141, v149
	v_lshl_add_u64 v[186:187], v[186:187], 0, v[166:167]
	v_lshl_add_u64 v[186:187], v[186:187], 0, v[140:141]
	v_lshlrev_b32_e32 v188, 16, v172
	v_and_b32_e32 v189, 0xffff0000, v172
	v_lshlrev_b32_e32 v172, 16, v173
	v_and_b32_e32 v173, 0xffff0000, v173
	v_pk_fma_f32 v[138:139], v[138:139], v[110:111], v[172:173]
	v_pk_fma_f32 v[136:137], v[136:137], v[108:109], v[188:189]
	s_nop 0
	v_cvt_pk_bf16_f32 v136, v136, v137
	v_cvt_pk_bf16_f32 v137, v138, v139
	global_store_dwordx2 v[184:185], v[136:137], off
	v_mov_b32_e32 v188, v198
	v_mov_b32_e32 v189, v199
	v_or_b32_e32 v136, 0x90, v170
	v_ashrrev_i32_e32 v138, 6, v136
	v_ashrrev_i32_e32 v139, 31, v138
	v_lshlrev_b64 v[138:139], 14, v[138:139]
	v_lshlrev_b32_e32 v170, 1, v136
	v_lshl_add_u64 v[138:139], s[10:11], 0, v[138:139]
	v_and_b32_e32 v184, 48, v170
	v_lshl_add_u64 v[172:173], v[138:139], 0, s[54:55]
	v_and_b32_e32 v136, 8, v170
	v_bitop3_b32 v170, v190, v191, v184 bitop3:0x36
	v_lshl_add_u64 v[190:191], v[172:173], 0, s[24:25]
	v_mov_b32_e32 v137, v149
	v_lshl_add_u64 v[190:191], v[190:191], 0, v[170:171]
	v_lshl_add_u64 v[190:191], v[190:191], 0, v[136:137]
	v_lshlrev_b32_e32 v192, 16, v188
	v_and_b32_e32 v193, 0xffff0000, v188
; __device__ __forceinline__ unsigned pk_bf16(float lo, float hi) { f32x2 v = {lo, hi}; bf16x2_t b = __builtin_convertvector(v, bf16x2_t); return __builtin_bit_cast(unsigned, b); }
; __device__ __forceinline__ f32x4 unpack4(u32x2 w) { return (f32x4){bf_lo(w.x), bf_hi(w.x), bf_lo(w.y), bf_hi(w.y)}; }
;     __device__ __forceinline__ void operator()(const f32x4 (&acc)[2][2][4][2], const Unit& u, int wr, int wc, int fr, int fq) const {
;     ...
;             for (int m = 0; m < 4; ++m) { const int rr = rowl + ai * HALF + m * 16;
; #pragma unroll
;                 for (int bj = 0; bj < 2; ++bj)
; #pragma unroll
;                     for (int n = 0; n < 2; ++n) { const int c = c0 + bj * HALF + n * 16; char* xp = (char*)xr + blk_off(rr, c, DM / 64);
;                         const f32x4 bs = base_f32 ? *(const f32x4*)(base_f32 + (size_t)rr * DM + c) : unpack4(*(const u32x2*)xp);
;                         const f32x4 o = bs + gv[bj][n] * acc[ai][bj][m][n];
;                         u32x2 w; w.x = pk_bf16(o[0], o[1]); w.y = pk_bf16(o[2], o[3]);
;                         *(u32x2*)xp = w; } }
	v_lshlrev_b32_e32 v188, 16, v189
	v_and_b32_e32 v189, 0xffff0000, v189
	v_pk_fma_f32 v[134:135], v[134:135], v[98:99], v[188:189]
	v_pk_fma_f32 v[132:133], v[132:133], v[96:97], v[192:193]
	s_nop 0
	v_cvt_pk_bf16_f32 v132, v132, v133
	v_cvt_pk_bf16_f32 v133, v134, v135
	global_store_dwordx2 v[186:187], v[132:133], off
	v_mov_b32_e32 v132, v200
	v_mov_b32_e32 v133, v201
	v_lshl_add_u64 v[134:135], v[158:159], 0, s[4:5]
	v_lshl_add_u64 v[186:187], v[134:135], 0, v[160:161]
	v_lshl_add_u64 v[186:187], v[186:187], 0, v[148:149]
	v_lshlrev_b32_e32 v188, 16, v132
	v_and_b32_e32 v189, 0xffff0000, v132
	v_lshlrev_b32_e32 v132, 16, v133
	v_and_b32_e32 v133, 0xffff0000, v133
	v_pk_fma_f32 v[130:131], v[130:131], v[90:91], v[132:133]
	v_pk_fma_f32 v[128:129], v[128:129], v[88:89], v[188:189]
	s_nop 0
	v_cvt_pk_bf16_f32 v128, v128, v129
	v_cvt_pk_bf16_f32 v129, v130, v131
	global_store_dwordx2 v[190:191], v[128:129], off
	s_mov_b32 s99, s5
	v_or_b32_e32 v202, 32, v181
	v_mov_b32_e32 v205, v149
	v_bitop3_b32 v204, v236, v237, v202 bitop3:0x36
	v_mov_b32_e32 v207, v149
	s_or_b32 s98, s9, 16
	s_lshr_b32 s98, s98, 3
	s_and_b32 s98, s98, 10
	s_or_b32 s98, s98, s71
	s_lshl_b32 s98, s98, 10
	v_mov_b32_e32 v209, v149
	v_or_b32_e32 v210, 0x80, v240
	v_ashrrev_i32_e32 v220, 6, v210
	v_ashrrev_i32_e32 v221, 31, v220
	v_lshlrev_b64 v[220:221], 14, v[220:221]
	v_lshlrev_b32_e32 v208, 1, v210
	v_lshl_add_u64 v[220:221], s[10:11], 0, v[220:221]
	v_and_b32_e32 v203, 16, v208
	v_lshl_add_u64 v[222:223], v[220:221], 0, s[54:55]
	v_and_b32_e32 v210, 8, v208
	v_or_b32_e32 v208, v238, v203
	v_mov_b32_e32 v211, v149
	v_or_b32_e32 v224, 0x90, v240
	v_ashrrev_i32_e32 v226, 6, v224
	v_ashrrev_i32_e32 v227, 31, v226
	v_lshlrev_b64 v[226:227], 14, v[226:227]
	v_lshlrev_b32_e32 v206, 1, v224
	v_lshl_add_u64 v[226:227], s[10:11], 0, v[226:227]
	v_and_b32_e32 v228, 48, v206
	v_lshl_add_u64 v[230:231], v[226:227], 0, s[54:55]
	v_and_b32_e32 v224, 8, v206
	v_bitop3_b32 v206, v236, v237, v228 bitop3:0x36
	v_mov_b32_e32 v225, v149
	v_lshl_add_u64 v[232:233], v[158:159], 0, s[98:99]
	v_lshl_add_u64 v[234:235], v[232:233], 0, v[160:161]
	v_lshl_add_u64 v[234:235], v[234:235], 0, v[148:149]
	global_load_dwordx2 v[194:195], v[234:235], off
	v_lshl_add_u64 v[220:221], v[232:233], 0, v[204:205]
	v_lshl_add_u64 v[220:221], v[220:221], 0, v[148:149]
	global_load_dwordx2 v[196:197], v[220:221], off
	v_lshl_add_u64 v[202:203], v[222:223], 0, s[98:99]
	v_lshl_add_u64 v[202:203], v[202:203], 0, v[208:209]
	v_lshl_add_u64 v[202:203], v[202:203], 0, v[210:211]
	global_load_dwordx2 v[198:199], v[202:203], off
	v_lshl_add_u64 v[226:227], v[230:231], 0, s[98:99]
	v_lshl_add_u64 v[226:227], v[226:227], 0, v[206:207]
	v_lshl_add_u64 v[226:227], v[226:227], 0, v[224:225]
	global_load_dwordx2 v[200:201], v[226:227], off
	s_waitcnt vmcnt(0)
	v_mov_b32_e32 v128, v194
	v_mov_b32_e32 v129, v195
	v_lshl_add_u64 v[130:131], v[134:135], 0, v[162:163]
	v_lshl_add_u64 v[130:131], v[130:131], 0, v[148:149]
	v_lshlrev_b32_e32 v132, 16, v128
	v_and_b32_e32 v133, 0xffff0000, v128
	v_lshlrev_b32_e32 v128, 16, v129
	v_and_b32_e32 v129, 0xffff0000, v129
	v_pk_fma_f32 v[126:127], v[126:127], v[114:115], v[128:129]
	v_pk_fma_f32 v[124:125], v[124:125], v[112:113], v[132:133]
	s_nop 0
	v_cvt_pk_bf16_f32 v124, v124, v125
	v_cvt_pk_bf16_f32 v125, v126, v127
	global_store_dwordx2 v[186:187], v[124:125], off
	v_mov_b32_e32 v124, v196
	v_mov_b32_e32 v125, v197
	v_lshl_add_u64 v[126:127], v[168:169], 0, s[4:5]
	v_lshl_add_u64 v[126:127], v[126:127], 0, v[166:167]
	v_lshl_add_u64 v[126:127], v[126:127], 0, v[140:141]
	v_lshlrev_b32_e32 v128, 16, v124
	v_and_b32_e32 v129, 0xffff0000, v124
	v_lshlrev_b32_e32 v124, 16, v125
	v_and_b32_e32 v125, 0xffff0000, v125
	v_pk_fma_f32 v[122:123], v[122:123], v[110:111], v[124:125]
	v_pk_fma_f32 v[120:121], v[120:121], v[108:109], v[128:129]
	s_nop 0
	v_cvt_pk_bf16_f32 v120, v120, v121
	v_cvt_pk_bf16_f32 v121, v122, v123
	global_store_dwordx2 v[130:131], v[120:121], off
	v_mov_b32_e32 v120, v198
	v_mov_b32_e32 v121, v199
	v_lshl_add_u64 v[122:123], v[172:173], 0, s[4:5]
	v_lshl_add_u64 v[122:123], v[122:123], 0, v[170:171]
	v_lshl_add_u64 v[122:123], v[122:123], 0, v[136:137]
	s_or_b32 s4, s9, 32
	s_lshr_b32 s4, s4, 3
	s_and_b32 s4, s4, 12
	s_or_b32 s4, s4, s71
	s_lshl_b32 s4, s4, 10
	v_lshlrev_b32_e32 v124, 16, v120
	v_and_b32_e32 v125, 0xffff0000, v120
	v_lshlrev_b32_e32 v120, 16, v121
	v_and_b32_e32 v121, 0xffff0000, v121
	v_pk_fma_f32 v[118:119], v[118:119], v[98:99], v[120:121]
	v_pk_fma_f32 v[116:117], v[116:117], v[96:97], v[124:125]
	s_nop 0
	v_cvt_pk_bf16_f32 v116, v116, v117
	v_cvt_pk_bf16_f32 v117, v118, v119
	global_store_dwordx2 v[126:127], v[116:117], off
	v_mov_b32_e32 v116, v200
	v_mov_b32_e32 v117, v201
	v_lshl_add_u64 v[118:119], v[158:159], 0, s[4:5]
	v_lshl_add_u64 v[120:121], v[118:119], 0, v[160:161]
	v_lshl_add_u64 v[120:121], v[120:121], 0, v[148:149]
	v_lshlrev_b32_e32 v124, 16, v116
	v_and_b32_e32 v125, 0xffff0000, v116
	v_lshlrev_b32_e32 v116, 16, v117
	v_and_b32_e32 v117, 0xffff0000, v117
	v_pk_fma_f32 v[106:107], v[106:107], v[90:91], v[116:117]
	v_pk_fma_f32 v[104:105], v[104:105], v[88:89], v[124:125]
	s_nop 0
	v_cvt_pk_bf16_f32 v104, v104, v105
	v_cvt_pk_bf16_f32 v105, v106, v107
	global_store_dwordx2 v[122:123], v[104:105], off
	s_mov_b32 s99, s5
	v_or_b32_e32 v202, 32, v181
	v_mov_b32_e32 v205, v149
	v_bitop3_b32 v204, v236, v237, v202 bitop3:0x36
	v_mov_b32_e32 v207, v149
	v_mov_b32_e32 v209, v149
	v_or_b32_e32 v210, 0x80, v240
	v_ashrrev_i32_e32 v220, 6, v210
	v_ashrrev_i32_e32 v221, 31, v220
	v_lshlrev_b64 v[220:221], 14, v[220:221]
	v_lshlrev_b32_e32 v208, 1, v210
; __device__ __forceinline__ unsigned pk_bf16(float lo, float hi) { f32x2 v = {lo, hi}; bf16x2_t b = __builtin_convertvector(v, bf16x2_t); return __builtin_bit_cast(unsigned, b); }
; __device__ __forceinline__ f32x4 unpack4(u32x2 w) { return (f32x4){bf_lo(w.x), bf_hi(w.x), bf_lo(w.y), bf_hi(w.y)}; }
;     __device__ __forceinline__ void operator()(const f32x4 (&acc)[2][2][4][2], const Unit& u, int wr, int wc, int fr, int fq) const {
;     ...
;             for (int m = 0; m < 4; ++m) { const int rr = rowl + ai * HALF + m * 16;
; #pragma unroll
;                 for (int bj = 0; bj < 2; ++bj)
; #pragma unroll
;                     for (int n = 0; n < 2; ++n) { const int c = c0 + bj * HALF + n * 16; char* xp = (char*)xr + blk_off(rr, c, DM / 64);
;                         const f32x4 bs = base_f32 ? *(const f32x4*)(base_f32 + (size_t)rr * DM + c) : unpack4(*(const u32x2*)xp);
;                         const f32x4 o = bs + gv[bj][n] * acc[ai][bj][m][n];
;                         u32x2 w; w.x = pk_bf16(o[0], o[1]); w.y = pk_bf16(o[2], o[3]);
;                         *(u32x2*)xp = w; } }
	v_lshl_add_u64 v[220:221], s[10:11], 0, v[220:221]
	v_and_b32_e32 v203, 16, v208
	v_lshl_add_u64 v[222:223], v[220:221], 0, s[54:55]
	v_and_b32_e32 v210, 8, v208
	v_or_b32_e32 v208, v238, v203
	v_mov_b32_e32 v211, v149
	v_or_b32_e32 v224, 0x90, v240
	v_ashrrev_i32_e32 v226, 6, v224
	v_ashrrev_i32_e32 v227, 31, v226
	v_lshlrev_b64 v[226:227], 14, v[226:227]
	v_lshlrev_b32_e32 v206, 1, v224
	v_lshl_add_u64 v[226:227], s[10:11], 0, v[226:227]
	v_and_b32_e32 v228, 48, v206
	v_lshl_add_u64 v[230:231], v[226:227], 0, s[54:55]
	v_and_b32_e32 v224, 8, v206
	v_bitop3_b32 v206, v236, v237, v228 bitop3:0x36
	v_mov_b32_e32 v225, v149
	s_or_b32 s98, s9, 32
	s_lshr_b32 s98, s98, 3
	s_and_b32 s98, s98, 12
	s_or_b32 s98, s98, s71
	s_lshl_b32 s98, s98, 10
	v_lshl_add_u64 v[232:233], v[158:159], 0, s[98:99]
	v_lshl_add_u64 v[234:235], v[232:233], 0, v[160:161]
	v_lshl_add_u64 v[234:235], v[234:235], 0, v[148:149]
	global_load_dwordx2 v[194:195], v[234:235], off
	v_lshl_add_u64 v[220:221], v[232:233], 0, v[204:205]
	v_lshl_add_u64 v[220:221], v[220:221], 0, v[148:149]
	global_load_dwordx2 v[196:197], v[220:221], off
	v_lshl_add_u64 v[202:203], v[222:223], 0, s[98:99]
	v_lshl_add_u64 v[202:203], v[202:203], 0, v[208:209]
	v_lshl_add_u64 v[202:203], v[202:203], 0, v[210:211]
	global_load_dwordx2 v[198:199], v[202:203], off
	v_lshl_add_u64 v[226:227], v[230:231], 0, s[98:99]
	v_lshl_add_u64 v[226:227], v[226:227], 0, v[206:207]
	v_lshl_add_u64 v[226:227], v[226:227], 0, v[224:225]
	global_load_dwordx2 v[200:201], v[226:227], off
	s_waitcnt vmcnt(0)
	v_mov_b32_e32 v104, v194
	v_mov_b32_e32 v105, v195
	v_lshl_add_u64 v[106:107], v[118:119], 0, v[162:163]
	v_lshl_add_u64 v[106:107], v[106:107], 0, v[148:149]
	v_lshlrev_b32_e32 v116, 16, v104
	v_and_b32_e32 v117, 0xffff0000, v104
	v_lshlrev_b32_e32 v104, 16, v105
	v_and_b32_e32 v105, 0xffff0000, v105
	v_pk_fma_f32 v[102:103], v[102:103], v[114:115], v[104:105]
	v_pk_fma_f32 v[100:101], v[100:101], v[112:113], v[116:117]
	s_nop 0
	v_cvt_pk_bf16_f32 v100, v100, v101
	v_cvt_pk_bf16_f32 v101, v102, v103
	global_store_dwordx2 v[120:121], v[100:101], off
	v_mov_b32_e32 v100, v196
	v_mov_b32_e32 v101, v197
	v_lshl_add_u64 v[102:103], v[168:169], 0, s[4:5]
	v_lshl_add_u64 v[102:103], v[102:103], 0, v[166:167]
	v_lshl_add_u64 v[102:103], v[102:103], 0, v[140:141]
	v_lshlrev_b32_e32 v104, 16, v100
	v_and_b32_e32 v105, 0xffff0000, v100
	v_lshlrev_b32_e32 v100, 16, v101
	v_and_b32_e32 v101, 0xffff0000, v101
	v_pk_fma_f32 v[94:95], v[94:95], v[110:111], v[100:101]
	v_pk_fma_f32 v[92:93], v[92:93], v[108:109], v[104:105]
	s_nop 0
	v_cvt_pk_bf16_f32 v92, v92, v93
	v_cvt_pk_bf16_f32 v93, v94, v95
	global_store_dwordx2 v[106:107], v[92:93], off
	v_mov_b32_e32 v92, v198
	v_mov_b32_e32 v93, v199
	v_lshl_add_u64 v[94:95], v[172:173], 0, s[4:5]
	v_lshl_add_u64 v[94:95], v[94:95], 0, v[170:171]
	v_lshl_add_u64 v[94:95], v[94:95], 0, v[136:137]
	s_or_b32 s4, s9, 48
	s_lshr_b32 s4, s4, 3
	s_and_b32 s4, s4, 14
	s_or_b32 s4, s4, s71
	s_lshl_b32 s4, s4, 10
	v_lshlrev_b32_e32 v100, 16, v92
	v_and_b32_e32 v101, 0xffff0000, v92
	v_lshlrev_b32_e32 v92, 16, v93
	v_and_b32_e32 v93, 0xffff0000, v93
	v_pk_fma_f32 v[86:87], v[86:87], v[98:99], v[92:93]
	v_pk_fma_f32 v[84:85], v[84:85], v[96:97], v[100:101]
	s_nop 0
	v_cvt_pk_bf16_f32 v84, v84, v85
	v_cvt_pk_bf16_f32 v85, v86, v87
	global_store_dwordx2 v[102:103], v[84:85], off
	v_mov_b32_e32 v84, v200
	v_mov_b32_e32 v85, v201
	v_lshl_add_u64 v[86:87], v[158:159], 0, s[4:5]
	v_lshl_add_u64 v[92:93], v[86:87], 0, v[160:161]
	v_lshl_add_u64 v[92:93], v[92:93], 0, v[148:149]
	v_lshlrev_b32_e32 v100, 16, v84
	v_and_b32_e32 v101, 0xffff0000, v84
	v_lshlrev_b32_e32 v84, 16, v85
	v_and_b32_e32 v85, 0xffff0000, v85
	v_pk_fma_f32 v[82:83], v[82:83], v[90:91], v[84:85]
	v_pk_fma_f32 v[80:81], v[80:81], v[88:89], v[100:101]
	s_nop 0
	v_cvt_pk_bf16_f32 v80, v80, v81
	v_cvt_pk_bf16_f32 v81, v82, v83
	global_store_dwordx2 v[94:95], v[80:81], off
	s_mov_b32 s99, s5
	v_or_b32_e32 v202, 32, v181
	v_mov_b32_e32 v205, v149
	v_bitop3_b32 v204, v236, v237, v202 bitop3:0x36
	v_mov_b32_e32 v207, v149
	v_mov_b32_e32 v209, v149
	v_or_b32_e32 v210, 0x80, v240
	v_ashrrev_i32_e32 v220, 6, v210
	v_ashrrev_i32_e32 v221, 31, v220
	v_lshlrev_b64 v[220:221], 14, v[220:221]
	v_lshlrev_b32_e32 v208, 1, v210
	v_lshl_add_u64 v[220:221], s[10:11], 0, v[220:221]
	v_and_b32_e32 v203, 16, v208
	v_lshl_add_u64 v[222:223], v[220:221], 0, s[54:55]
	v_and_b32_e32 v210, 8, v208
	v_or_b32_e32 v208, v238, v203
	v_mov_b32_e32 v211, v149
	v_or_b32_e32 v224, 0x90, v240
	v_ashrrev_i32_e32 v226, 6, v224
	v_ashrrev_i32_e32 v227, 31, v226
	v_lshlrev_b64 v[226:227], 14, v[226:227]
	v_lshlrev_b32_e32 v206, 1, v224
	v_lshl_add_u64 v[226:227], s[10:11], 0, v[226:227]
	v_and_b32_e32 v228, 48, v206
	v_lshl_add_u64 v[230:231], v[226:227], 0, s[54:55]
	v_and_b32_e32 v224, 8, v206
	v_bitop3_b32 v206, v236, v237, v228 bitop3:0x36
	v_mov_b32_e32 v225, v149
	s_or_b32 s98, s9, 48
	s_lshr_b32 s98, s98, 3
	s_and_b32 s98, s98, 14
	s_or_b32 s98, s98, s71
	s_lshl_b32 s98, s98, 10
	v_lshl_add_u64 v[232:233], v[158:159], 0, s[98:99]
	v_lshl_add_u64 v[234:235], v[232:233], 0, v[160:161]
	v_lshl_add_u64 v[234:235], v[234:235], 0, v[148:149]
	global_load_dwordx2 v[194:195], v[234:235], off
	v_lshl_add_u64 v[220:221], v[232:233], 0, v[204:205]
	v_lshl_add_u64 v[220:221], v[220:221], 0, v[148:149]
	global_load_dwordx2 v[196:197], v[220:221], off
	v_lshl_add_u64 v[202:203], v[222:223], 0, s[98:99]
	v_lshl_add_u64 v[202:203], v[202:203], 0, v[208:209]
	v_lshl_add_u64 v[202:203], v[202:203], 0, v[210:211]
	global_load_dwordx2 v[198:199], v[202:203], off
	v_lshl_add_u64 v[226:227], v[230:231], 0, s[98:99]
	v_lshl_add_u64 v[226:227], v[226:227], 0, v[206:207]
	v_lshl_add_u64 v[226:227], v[226:227], 0, v[224:225]
	global_load_dwordx2 v[200:201], v[226:227], off
	s_waitcnt vmcnt(0)
; __device__ __forceinline__ unsigned pk_bf16(float lo, float hi) { f32x2 v = {lo, hi}; bf16x2_t b = __builtin_convertvector(v, bf16x2_t); return __builtin_bit_cast(unsigned, b); }
; __device__ __forceinline__ f32x4 unpack4(u32x2 w) { return (f32x4){bf_lo(w.x), bf_hi(w.x), bf_lo(w.y), bf_hi(w.y)}; }
;     __device__ __forceinline__ void operator()(const f32x4 (&acc)[2][2][4][2], const Unit& u, int wr, int wc, int fr, int fq) const {
;     ...
;             for (int m = 0; m < 4; ++m) { const int rr = rowl + ai * HALF + m * 16;
; #pragma unroll
;                 for (int bj = 0; bj < 2; ++bj)
; #pragma unroll
;                     for (int n = 0; n < 2; ++n) { const int c = c0 + bj * HALF + n * 16; char* xp = (char*)xr + blk_off(rr, c, DM / 64);
;                         const f32x4 bs = base_f32 ? *(const f32x4*)(base_f32 + (size_t)rr * DM + c) : unpack4(*(const u32x2*)xp);
;                         const f32x4 o = bs + gv[bj][n] * acc[ai][bj][m][n];
;                         u32x2 w; w.x = pk_bf16(o[0], o[1]); w.y = pk_bf16(o[2], o[3]);
;                         *(u32x2*)xp = w; } }
	v_mov_b32_e32 v80, v194
	v_mov_b32_e32 v81, v195
	v_lshl_add_u64 v[82:83], v[86:87], 0, v[162:163]
	v_lshl_add_u64 v[82:83], v[82:83], 0, v[148:149]
	v_lshlrev_b32_e32 v84, 16, v80
	v_and_b32_e32 v85, 0xffff0000, v80
	v_lshlrev_b32_e32 v80, 16, v81
	v_and_b32_e32 v81, 0xffff0000, v81
	v_pk_fma_f32 v[78:79], v[78:79], v[114:115], v[80:81]
	v_pk_fma_f32 v[76:77], v[76:77], v[112:113], v[84:85]
	s_nop 0
	v_cvt_pk_bf16_f32 v76, v76, v77
	v_cvt_pk_bf16_f32 v77, v78, v79
	global_store_dwordx2 v[92:93], v[76:77], off
	v_mov_b32_e32 v76, v196
	v_mov_b32_e32 v77, v197
	v_lshl_add_u64 v[78:79], v[168:169], 0, s[4:5]
	v_lshl_add_u64 v[78:79], v[78:79], 0, v[166:167]
	v_lshl_add_u64 v[78:79], v[78:79], 0, v[140:141]
	v_lshlrev_b32_e32 v80, 16, v76
	v_and_b32_e32 v81, 0xffff0000, v76
	v_lshlrev_b32_e32 v76, 16, v77
	v_and_b32_e32 v77, 0xffff0000, v77
	v_pk_fma_f32 v[74:75], v[74:75], v[110:111], v[76:77]
	v_pk_fma_f32 v[72:73], v[72:73], v[108:109], v[80:81]
	s_nop 0
	v_cvt_pk_bf16_f32 v72, v72, v73
	v_cvt_pk_bf16_f32 v73, v74, v75
	global_store_dwordx2 v[82:83], v[72:73], off
	v_mov_b32_e32 v72, v198
	v_mov_b32_e32 v73, v199
	v_lshl_add_u64 v[74:75], v[172:173], 0, s[4:5]
	v_lshl_add_u64 v[74:75], v[74:75], 0, v[170:171]
	v_lshl_add_u64 v[74:75], v[74:75], 0, v[136:137]
	v_lshlrev_b32_e32 v76, 16, v72
	v_and_b32_e32 v77, 0xffff0000, v72
	v_lshlrev_b32_e32 v72, 16, v73
	v_and_b32_e32 v73, 0xffff0000, v73
	v_pk_fma_f32 v[70:71], v[70:71], v[98:99], v[72:73]
	v_pk_fma_f32 v[68:69], v[68:69], v[96:97], v[76:77]
	v_mov_b32_e32 v73, v149
	v_cvt_pk_bf16_f32 v68, v68, v69
	v_cvt_pk_bf16_f32 v69, v70, v71
	global_store_dwordx2 v[78:79], v[68:69], off
	v_mov_b32_e32 v70, v200
	v_mov_b32_e32 v71, v201
	v_add_u32_e32 v69, 0x80, v180
	v_ashrrev_i32_e32 v68, 7, v69
	v_lshlrev_b32_e32 v72, 6, v69
	v_lshlrev_b32_e32 v76, 2, v69
	v_ashrrev_i32_e32 v69, 31, v68
	v_and_b32_e32 v82, 0x3c0, v72
	v_and_b32_e32 v83, 32, v76
	v_lshlrev_b64 v[76:77], 19, v[68:69]
	v_or_b32_e32 v84, v83, v82
	v_lshl_add_u64 v[68:69], v[156:157], 0, v[76:77]
	v_or_b32_e32 v72, v84, v181
	v_lshl_add_u64 v[78:79], v[68:69], 0, s[24:25]
	v_lshl_add_u64 v[72:73], v[78:79], 0, v[72:73]
	v_lshl_add_u64 v[72:73], v[72:73], 0, v[148:149]
	v_lshlrev_b32_e32 v80, 16, v70
	v_and_b32_e32 v81, 0xffff0000, v70
	v_lshlrev_b32_e32 v70, 16, v71
	v_and_b32_e32 v71, 0xffff0000, v71
	v_pk_fma_f32 v[66:67], v[66:67], v[90:91], v[70:71]
	v_pk_fma_f32 v[64:65], v[64:65], v[88:89], v[80:81]
	s_nop 0
	v_cvt_pk_bf16_f32 v64, v64, v65
	v_cvt_pk_bf16_f32 v65, v66, v67
	global_store_dwordx2 v[74:75], v[64:65], off
	v_or_b32_e32 v202, 32, v181
	v_or_b32_e32 v204, 0x80, v240
	v_ashrrev_i32_e32 v206, 6, v204
	v_ashrrev_i32_e32 v207, 31, v206
	v_lshlrev_b64 v[206:207], 14, v[206:207]
	v_lshlrev_b32_e32 v208, 1, v204
	v_lshl_add_u64 v[206:207], s[10:11], 0, v[206:207]
	v_and_b32_e32 v203, 16, v208
	v_and_b32_e32 v204, 8, v208
	v_mov_b32_e32 v205, v149
	v_or_b32_e32 v210, 0x90, v240
	v_ashrrev_i32_e32 v220, 6, v210
	v_ashrrev_i32_e32 v221, 31, v220
	v_lshlrev_b64 v[220:221], 14, v[220:221]
	v_lshlrev_b32_e32 v222, 1, v210
	v_lshl_add_u64 v[220:221], s[10:11], 0, v[220:221]
	v_and_b32_e32 v224, 48, v222
	v_and_b32_e32 v210, 8, v222
	v_mov_b32_e32 v211, v149
	v_mov_b32_e32 v227, v149
	v_add_u32_e32 v229, 0x80, v180
	v_ashrrev_i32_e32 v228, 7, v229
	v_lshlrev_b32_e32 v226, 6, v229
	v_lshlrev_b32_e32 v230, 2, v229
	v_ashrrev_i32_e32 v229, 31, v228
	v_and_b32_e32 v232, 0x3c0, v226
	v_and_b32_e32 v233, 32, v230
	v_lshlrev_b64 v[230:231], 19, v[228:229]
	v_or_b32_e32 v234, v233, v232
	v_lshl_add_u64 v[228:229], v[156:157], 0, v[230:231]
	v_or_b32_e32 v226, v234, v181
	v_lshl_add_u64 v[208:209], v[228:229], 0, s[24:25]
	v_lshl_add_u64 v[226:227], v[208:209], 0, v[226:227]
	v_lshl_add_u64 v[226:227], v[226:227], 0, v[148:149]
	global_load_dwordx2 v[194:195], v[226:227], off
	v_mov_b32_e32 v223, v149
	v_bitop3_b32 v222, v232, v233, v202 bitop3:0x36
	v_lshl_add_u64 v[222:223], v[208:209], 0, v[222:223]
	v_lshl_add_u64 v[222:223], v[222:223], 0, v[148:149]
	v_mov_b32_e32 v229, v149
	global_load_dwordx2 v[196:197], v[222:223], off
	v_lshl_add_u64 v[226:227], v[206:207], 0, v[230:231]
	v_or_b32_e32 v228, v234, v203
	v_lshl_add_u64 v[208:209], v[226:227], 0, s[24:25]
	v_lshl_add_u64 v[228:229], v[208:209], 0, v[228:229]
	v_lshl_add_u64 v[228:229], v[228:229], 0, v[204:205]
	v_mov_b32_e32 v207, v149
	global_load_dwordx2 v[198:199], v[228:229], off
	v_lshl_add_u64 v[202:203], v[220:221], 0, v[230:231]
	v_bitop3_b32 v206, v232, v233, v224 bitop3:0x36
	v_lshl_add_u64 v[222:223], v[202:203], 0, s[24:25]
	v_lshl_add_u64 v[206:207], v[222:223], 0, v[206:207]
	v_lshl_add_u64 v[206:207], v[206:207], 0, v[210:211]
	global_load_dwordx2 v[200:201], v[206:207], off
	s_waitcnt vmcnt(0)
; __device__ __forceinline__ unsigned pk_bf16(float lo, float hi) { f32x2 v = {lo, hi}; bf16x2_t b = __builtin_convertvector(v, bf16x2_t); return __builtin_bit_cast(unsigned, b); }
; __device__ __forceinline__ f32x4 unpack4(u32x2 w) { return (f32x4){bf_lo(w.x), bf_hi(w.x), bf_lo(w.y), bf_hi(w.y)}; }
;     __device__ __forceinline__ void operator()(const f32x4 (&acc)[2][2][4][2], const Unit& u, int wr, int wc, int fr, int fq) const {
;     ...
;             for (int m = 0; m < 4; ++m) { const int rr = rowl + ai * HALF + m * 16;
; #pragma unroll
;                 for (int bj = 0; bj < 2; ++bj)
; #pragma unroll
;                     for (int n = 0; n < 2; ++n) { const int c = c0 + bj * HALF + n * 16; char* xp = (char*)xr + blk_off(rr, c, DM / 64);
;                         const f32x4 bs = base_f32 ? *(const f32x4*)(base_f32 + (size_t)rr * DM + c) : unpack4(*(const u32x2*)xp);
;                         const f32x4 o = bs + gv[bj][n] * acc[ai][bj][m][n];
;                         u32x2 w; w.x = pk_bf16(o[0], o[1]); w.y = pk_bf16(o[2], o[3]);
;                         *(u32x2*)xp = w; } }
	v_mov_b32_e32 v64, v194
	v_mov_b32_e32 v65, v195
	v_mov_b32_e32 v67, v149
	v_bitop3_b32 v66, v82, v83, v182 bitop3:0x36
	v_lshl_add_u64 v[66:67], v[78:79], 0, v[66:67]
	v_lshl_add_u64 v[66:67], v[66:67], 0, v[148:149]
	v_lshlrev_b32_e32 v70, 16, v64
	v_and_b32_e32 v71, 0xffff0000, v64
	v_lshlrev_b32_e32 v64, 16, v65
	v_and_b32_e32 v65, 0xffff0000, v65
	v_pk_fma_f32 v[62:63], v[62:63], v[114:115], v[64:65]
	v_pk_fma_f32 v[60:61], v[60:61], v[112:113], v[70:71]
	v_mov_b32_e32 v65, v149
	v_cvt_pk_bf16_f32 v60, v60, v61
	v_cvt_pk_bf16_f32 v61, v62, v63
	global_store_dwordx2 v[72:73], v[60:61], off
	v_mov_b32_e32 v62, v196
	v_mov_b32_e32 v63, v197
	v_lshl_add_u64 v[60:61], v[142:143], 0, v[76:77]
	v_or_b32_e32 v64, v84, v183
	v_lshl_add_u64 v[70:71], v[60:61], 0, s[24:25]
	v_lshl_add_u64 v[64:65], v[70:71], 0, v[64:65]
	v_lshl_add_u64 v[64:65], v[64:65], 0, v[140:141]
	v_lshlrev_b32_e32 v70, 16, v62
	v_and_b32_e32 v71, 0xffff0000, v62
	v_lshlrev_b32_e32 v62, 16, v63
	v_and_b32_e32 v63, 0xffff0000, v63
	v_pk_fma_f32 v[58:59], v[58:59], v[110:111], v[62:63]
	v_pk_fma_f32 v[56:57], v[56:57], v[108:109], v[70:71]
	v_mov_b32_e32 v63, v149
	v_cvt_pk_bf16_f32 v56, v56, v57
	v_cvt_pk_bf16_f32 v57, v58, v59
	global_store_dwordx2 v[66:67], v[56:57], off
	v_mov_b32_e32 v58, v198
	v_mov_b32_e32 v59, v199
	v_lshl_add_u64 v[56:57], v[138:139], 0, v[76:77]
	v_bitop3_b32 v62, v82, v83, v184 bitop3:0x36
	v_lshl_add_u64 v[66:67], v[56:57], 0, s[24:25]
	v_lshl_add_u64 v[62:63], v[66:67], 0, v[62:63]
	v_lshl_add_u64 v[62:63], v[62:63], 0, v[136:137]
	v_lshlrev_b32_e32 v66, 16, v58
	v_and_b32_e32 v67, 0xffff0000, v58
	v_lshlrev_b32_e32 v58, 16, v59
	v_and_b32_e32 v59, 0xffff0000, v59
	v_pk_fma_f32 v[54:55], v[54:55], v[98:99], v[58:59]
	v_pk_fma_f32 v[52:53], v[52:53], v[96:97], v[66:67]
	v_mov_b32_e32 v59, v149
	v_cvt_pk_bf16_f32 v52, v52, v53
	v_cvt_pk_bf16_f32 v53, v54, v55
	global_store_dwordx2 v[64:65], v[52:53], off
	v_mov_b32_e32 v52, v200
	v_mov_b32_e32 v53, v201
	v_add_u32_e32 v54, 0x90, v180
	v_lshrrev_b32_e32 v58, 3, v54
	v_lshlrev_b32_e32 v64, 6, v54
	v_lshlrev_b32_e32 v54, 2, v54
	v_and_or_b32 v58, v58, 10, s71
	v_and_b32_e32 v70, 0x3c0, v64
	v_and_b32_e32 v71, 32, v54
	v_mov_b32_e32 v55, v149
	v_lshlrev_b32_e32 v54, 10, v58
	v_or_b32_e32 v72, v71, v70
	v_or_b32_e32 v58, v72, v181
	v_lshl_add_u64 v[64:65], v[68:69], 0, v[54:55]
	v_lshl_add_u64 v[58:59], v[64:65], 0, v[58:59]
	v_lshl_add_u64 v[58:59], v[58:59], 0, v[148:149]
	v_lshlrev_b32_e32 v66, 16, v52
	v_and_b32_e32 v67, 0xffff0000, v52
	v_lshlrev_b32_e32 v52, 16, v53
	v_and_b32_e32 v53, 0xffff0000, v53
	v_pk_fma_f32 v[50:51], v[50:51], v[90:91], v[52:53]
	v_pk_fma_f32 v[48:49], v[48:49], v[88:89], v[66:67]
	s_nop 0
	v_cvt_pk_bf16_f32 v48, v48, v49
	v_cvt_pk_bf16_f32 v49, v50, v51
	global_store_dwordx2 v[62:63], v[48:49], off
	v_or_b32_e32 v202, 32, v181
	v_or_b32_e32 v204, 0x80, v240
	v_ashrrev_i32_e32 v206, 6, v204
	v_ashrrev_i32_e32 v207, 31, v206
	v_lshlrev_b64 v[206:207], 14, v[206:207]
	v_lshlrev_b32_e32 v208, 1, v204
	v_lshl_add_u64 v[206:207], s[10:11], 0, v[206:207]
	v_and_b32_e32 v203, 16, v208
	v_and_b32_e32 v204, 8, v208
	v_mov_b32_e32 v205, v149
	v_or_b32_e32 v210, 0x90, v240
	v_ashrrev_i32_e32 v220, 6, v210
	v_ashrrev_i32_e32 v221, 31, v220
	v_lshlrev_b64 v[220:221], 14, v[220:221]
	v_lshlrev_b32_e32 v222, 1, v210
	v_lshl_add_u64 v[220:221], s[10:11], 0, v[220:221]
	v_and_b32_e32 v224, 48, v222
	v_and_b32_e32 v210, 8, v222
	v_mov_b32_e32 v211, v149
	v_add_u32_e32 v227, 0x80, v180
	v_ashrrev_i32_e32 v226, 7, v227
	v_ashrrev_i32_e32 v227, 31, v226
	v_lshlrev_b64 v[228:229], 19, v[226:227]
	v_lshl_add_u64 v[226:227], v[156:157], 0, v[228:229]
	v_lshl_add_u64 v[230:231], v[206:207], 0, v[228:229]
	v_lshl_add_u64 v[232:233], v[220:221], 0, v[228:229]
	v_mov_b32_e32 v235, v149
	v_add_u32_e32 v208, 0x90, v180
	v_lshrrev_b32_e32 v234, 3, v208
	v_lshlrev_b32_e32 v222, 6, v208
	v_lshlrev_b32_e32 v208, 2, v208
	v_and_or_b32 v234, v234, 10, s71
	v_and_b32_e32 v206, 0x3c0, v222
	v_and_b32_e32 v207, 32, v208
	v_mov_b32_e32 v209, v149
	v_lshlrev_b32_e32 v208, 10, v234
	v_or_b32_e32 v220, v207, v206
	v_or_b32_e32 v234, v220, v181
	v_lshl_add_u64 v[222:223], v[226:227], 0, v[208:209]
	v_lshl_add_u64 v[234:235], v[222:223], 0, v[234:235]
	v_lshl_add_u64 v[234:235], v[234:235], 0, v[148:149]
	global_load_dwordx2 v[194:195], v[234:235], off
	v_mov_b32_e32 v229, v149
	v_bitop3_b32 v228, v206, v207, v202 bitop3:0x36
	v_lshl_add_u64 v[228:229], v[222:223], 0, v[228:229]
	v_lshl_add_u64 v[228:229], v[228:229], 0, v[148:149]
	v_lshl_add_u64 v[226:227], v[230:231], 0, v[208:209]
	global_load_dwordx2 v[196:197], v[228:229], off
	v_mov_b32_e32 v235, v149
	v_or_b32_e32 v234, v220, v203
	v_lshl_add_u64 v[234:235], v[226:227], 0, v[234:235]
	v_lshl_add_u64 v[234:235], v[234:235], 0, v[204:205]
	v_lshl_add_u64 v[222:223], v[232:233], 0, v[208:209]
	global_load_dwordx2 v[198:199], v[234:235], off
	v_mov_b32_e32 v231, v149
	v_bitop3_b32 v230, v206, v207, v224 bitop3:0x36
	v_lshl_add_u64 v[230:231], v[222:223], 0, v[230:231]
	v_lshl_add_u64 v[230:231], v[230:231], 0, v[210:211]
	global_load_dwordx2 v[200:201], v[230:231], off
	s_waitcnt vmcnt(0)
; __device__ __forceinline__ unsigned pk_bf16(float lo, float hi) { f32x2 v = {lo, hi}; bf16x2_t b = __builtin_convertvector(v, bf16x2_t); return __builtin_bit_cast(unsigned, b); }
; __device__ __forceinline__ f32x4 unpack4(u32x2 w) { return (f32x4){bf_lo(w.x), bf_hi(w.x), bf_lo(w.y), bf_hi(w.y)}; }
;     __device__ __forceinline__ void operator()(const f32x4 (&acc)[2][2][4][2], const Unit& u, int wr, int wc, int fr, int fq) const {
;     ...
;             for (int m = 0; m < 4; ++m) { const int rr = rowl + ai * HALF + m * 16;
; #pragma unroll
;                 for (int bj = 0; bj < 2; ++bj)
; #pragma unroll
;                     for (int n = 0; n < 2; ++n) { const int c = c0 + bj * HALF + n * 16; char* xp = (char*)xr + blk_off(rr, c, DM / 64);
;                         const f32x4 bs = base_f32 ? *(const f32x4*)(base_f32 + (size_t)rr * DM + c) : unpack4(*(const u32x2*)xp);
;                         const f32x4 o = bs + gv[bj][n] * acc[ai][bj][m][n];
;                         u32x2 w; w.x = pk_bf16(o[0], o[1]); w.y = pk_bf16(o[2], o[3]);
;                         *(u32x2*)xp = w; } }
	v_mov_b32_e32 v48, v194
	v_mov_b32_e32 v49, v195
	v_mov_b32_e32 v51, v149
	v_bitop3_b32 v50, v70, v71, v182 bitop3:0x36
	v_lshl_add_u64 v[50:51], v[64:65], 0, v[50:51]
	v_lshl_add_u64 v[50:51], v[50:51], 0, v[148:149]
	v_lshlrev_b32_e32 v52, 16, v48
	v_and_b32_e32 v53, 0xffff0000, v48
	v_lshlrev_b32_e32 v48, 16, v49
	v_and_b32_e32 v49, 0xffff0000, v49
	v_pk_fma_f32 v[46:47], v[46:47], v[114:115], v[48:49]
	v_pk_fma_f32 v[44:45], v[44:45], v[112:113], v[52:53]
	v_lshl_add_u64 v[48:49], v[60:61], 0, v[54:55]
	v_cvt_pk_bf16_f32 v44, v44, v45
	v_cvt_pk_bf16_f32 v45, v46, v47
	global_store_dwordx2 v[58:59], v[44:45], off
	v_mov_b32_e32 v44, v196
	v_mov_b32_e32 v45, v197
	v_mov_b32_e32 v47, v149
	v_or_b32_e32 v46, v72, v183
	v_lshl_add_u64 v[46:47], v[48:49], 0, v[46:47]
	v_lshl_add_u64 v[46:47], v[46:47], 0, v[140:141]
	v_lshlrev_b32_e32 v48, 16, v44
	v_and_b32_e32 v49, 0xffff0000, v44
	v_lshlrev_b32_e32 v44, 16, v45
	v_and_b32_e32 v45, 0xffff0000, v45
	v_pk_fma_f32 v[42:43], v[42:43], v[110:111], v[44:45]
	v_pk_fma_f32 v[40:41], v[40:41], v[108:109], v[48:49]
	v_lshl_add_u64 v[44:45], v[56:57], 0, v[54:55]
	v_cvt_pk_bf16_f32 v40, v40, v41
	v_cvt_pk_bf16_f32 v41, v42, v43
	global_store_dwordx2 v[50:51], v[40:41], off
	v_mov_b32_e32 v40, v198
	v_mov_b32_e32 v41, v199
	v_mov_b32_e32 v43, v149
	v_bitop3_b32 v42, v70, v71, v184 bitop3:0x36
	v_lshl_add_u64 v[42:43], v[44:45], 0, v[42:43]
	v_lshl_add_u64 v[42:43], v[42:43], 0, v[136:137]
	v_lshlrev_b32_e32 v44, 16, v40
	v_and_b32_e32 v45, 0xffff0000, v40
	v_lshlrev_b32_e32 v40, 16, v41
	v_and_b32_e32 v41, 0xffff0000, v41
	v_pk_fma_f32 v[38:39], v[38:39], v[98:99], v[40:41]
	v_pk_fma_f32 v[36:37], v[36:37], v[96:97], v[44:45]
	v_mov_b32_e32 v41, v149
	v_cvt_pk_bf16_f32 v36, v36, v37
	v_cvt_pk_bf16_f32 v37, v38, v39
	global_store_dwordx2 v[46:47], v[36:37], off
	v_mov_b32_e32 v36, v200
	v_mov_b32_e32 v37, v201
	v_add_u32_e32 v38, 0xa0, v180
	v_lshrrev_b32_e32 v40, 3, v38
	v_lshlrev_b32_e32 v44, 6, v38
	v_lshlrev_b32_e32 v38, 2, v38
	v_and_or_b32 v40, v40, 12, s71
	v_and_b32_e32 v48, 0x3c0, v44
	v_and_b32_e32 v49, 32, v38
	v_mov_b32_e32 v39, v149
	v_lshlrev_b32_e32 v38, 10, v40
	v_or_b32_e32 v50, v49, v48
	v_or_b32_e32 v40, v50, v181
	v_lshl_add_u64 v[44:45], v[68:69], 0, v[38:39]
	v_lshl_add_u64 v[40:41], v[44:45], 0, v[40:41]
	v_lshl_add_u64 v[40:41], v[40:41], 0, v[148:149]
	v_lshlrev_b32_e32 v46, 16, v36
	v_and_b32_e32 v47, 0xffff0000, v36
	v_lshlrev_b32_e32 v36, 16, v37
	v_and_b32_e32 v37, 0xffff0000, v37
	v_pk_fma_f32 v[34:35], v[34:35], v[90:91], v[36:37]
	v_pk_fma_f32 v[32:33], v[32:33], v[88:89], v[46:47]
	s_nop 0
	v_cvt_pk_bf16_f32 v32, v32, v33
	v_cvt_pk_bf16_f32 v33, v34, v35
	global_store_dwordx2 v[42:43], v[32:33], off
	v_or_b32_e32 v202, 32, v181
	v_or_b32_e32 v204, 0x80, v240
	v_ashrrev_i32_e32 v206, 6, v204
	v_ashrrev_i32_e32 v207, 31, v206
	v_lshlrev_b64 v[206:207], 14, v[206:207]
	v_lshlrev_b32_e32 v208, 1, v204
	v_lshl_add_u64 v[206:207], s[10:11], 0, v[206:207]
	v_and_b32_e32 v203, 16, v208
	v_and_b32_e32 v204, 8, v208
	v_mov_b32_e32 v205, v149
	v_or_b32_e32 v210, 0x90, v240
	v_ashrrev_i32_e32 v220, 6, v210
	v_ashrrev_i32_e32 v221, 31, v220
	v_lshlrev_b64 v[220:221], 14, v[220:221]
	v_lshlrev_b32_e32 v222, 1, v210
	v_lshl_add_u64 v[220:221], s[10:11], 0, v[220:221]
	v_and_b32_e32 v224, 48, v222
	v_and_b32_e32 v210, 8, v222
	v_mov_b32_e32 v211, v149
	v_add_u32_e32 v227, 0x80, v180
	v_ashrrev_i32_e32 v226, 7, v227
	v_ashrrev_i32_e32 v227, 31, v226
	v_lshlrev_b64 v[228:229], 19, v[226:227]
	v_lshl_add_u64 v[226:227], v[156:157], 0, v[228:229]
	v_lshl_add_u64 v[230:231], v[206:207], 0, v[228:229]
	v_lshl_add_u64 v[232:233], v[220:221], 0, v[228:229]
	v_mov_b32_e32 v235, v149
	v_add_u32_e32 v208, 0xa0, v180
	v_lshrrev_b32_e32 v234, 3, v208
	v_lshlrev_b32_e32 v222, 6, v208
	v_lshlrev_b32_e32 v208, 2, v208
	v_and_or_b32 v234, v234, 12, s71
	v_and_b32_e32 v206, 0x3c0, v222
	v_and_b32_e32 v207, 32, v208
	v_mov_b32_e32 v209, v149
	v_lshlrev_b32_e32 v208, 10, v234
	v_or_b32_e32 v220, v207, v206
	v_or_b32_e32 v234, v220, v181
	v_lshl_add_u64 v[222:223], v[226:227], 0, v[208:209]
	v_lshl_add_u64 v[234:235], v[222:223], 0, v[234:235]
	v_lshl_add_u64 v[234:235], v[234:235], 0, v[148:149]
	global_load_dwordx2 v[194:195], v[234:235], off
	v_mov_b32_e32 v229, v149
	v_bitop3_b32 v228, v206, v207, v202 bitop3:0x36
	v_lshl_add_u64 v[228:229], v[222:223], 0, v[228:229]
	v_lshl_add_u64 v[228:229], v[228:229], 0, v[148:149]
	v_lshl_add_u64 v[226:227], v[230:231], 0, v[208:209]
	global_load_dwordx2 v[196:197], v[228:229], off
	v_mov_b32_e32 v235, v149
	v_or_b32_e32 v234, v220, v203
	v_lshl_add_u64 v[234:235], v[226:227], 0, v[234:235]
	v_lshl_add_u64 v[234:235], v[234:235], 0, v[204:205]
	v_lshl_add_u64 v[222:223], v[232:233], 0, v[208:209]
	global_load_dwordx2 v[198:199], v[234:235], off
	v_mov_b32_e32 v231, v149
	v_bitop3_b32 v230, v206, v207, v224 bitop3:0x36
	v_lshl_add_u64 v[230:231], v[222:223], 0, v[230:231]
	v_lshl_add_u64 v[230:231], v[230:231], 0, v[210:211]
	global_load_dwordx2 v[200:201], v[230:231], off
	s_waitcnt vmcnt(0)
; __device__ __forceinline__ unsigned pk_bf16(float lo, float hi) { f32x2 v = {lo, hi}; bf16x2_t b = __builtin_convertvector(v, bf16x2_t); return __builtin_bit_cast(unsigned, b); }
; __device__ __forceinline__ f32x4 unpack4(u32x2 w) { return (f32x4){bf_lo(w.x), bf_hi(w.x), bf_lo(w.y), bf_hi(w.y)}; }
;     __device__ __forceinline__ void operator()(const f32x4 (&acc)[2][2][4][2], const Unit& u, int wr, int wc, int fr, int fq) const {
;     ...
;             for (int m = 0; m < 4; ++m) { const int rr = rowl + ai * HALF + m * 16;
; #pragma unroll
;                 for (int bj = 0; bj < 2; ++bj)
; #pragma unroll
;                     for (int n = 0; n < 2; ++n) { const int c = c0 + bj * HALF + n * 16; char* xp = (char*)xr + blk_off(rr, c, DM / 64);
;                         const f32x4 bs = base_f32 ? *(const f32x4*)(base_f32 + (size_t)rr * DM + c) : unpack4(*(const u32x2*)xp);
;                         const f32x4 o = bs + gv[bj][n] * acc[ai][bj][m][n];
;                         u32x2 w; w.x = pk_bf16(o[0], o[1]); w.y = pk_bf16(o[2], o[3]);
;                         *(u32x2*)xp = w; } }
	v_mov_b32_e32 v32, v194
	v_mov_b32_e32 v33, v195
	v_mov_b32_e32 v35, v149
	v_bitop3_b32 v34, v48, v49, v182 bitop3:0x36
	v_lshl_add_u64 v[34:35], v[44:45], 0, v[34:35]
	v_lshl_add_u64 v[34:35], v[34:35], 0, v[148:149]
	v_lshlrev_b32_e32 v36, 16, v32
	v_and_b32_e32 v37, 0xffff0000, v32
	v_lshlrev_b32_e32 v32, 16, v33
	v_and_b32_e32 v33, 0xffff0000, v33
	v_pk_fma_f32 v[30:31], v[30:31], v[114:115], v[32:33]
	v_pk_fma_f32 v[28:29], v[28:29], v[112:113], v[36:37]
	v_lshl_add_u64 v[32:33], v[60:61], 0, v[38:39]
	v_cvt_pk_bf16_f32 v28, v28, v29
	v_cvt_pk_bf16_f32 v29, v30, v31
	global_store_dwordx2 v[40:41], v[28:29], off
	v_mov_b32_e32 v28, v196
	v_mov_b32_e32 v29, v197
	v_mov_b32_e32 v31, v149
	v_or_b32_e32 v30, v50, v183
	v_lshl_add_u64 v[30:31], v[32:33], 0, v[30:31]
	v_lshl_add_u64 v[30:31], v[30:31], 0, v[140:141]
	v_lshlrev_b32_e32 v32, 16, v28
	v_and_b32_e32 v33, 0xffff0000, v28
	v_lshlrev_b32_e32 v28, 16, v29
	v_and_b32_e32 v29, 0xffff0000, v29
	v_pk_fma_f32 v[26:27], v[26:27], v[110:111], v[28:29]
	v_pk_fma_f32 v[24:25], v[24:25], v[108:109], v[32:33]
	v_lshl_add_u64 v[28:29], v[56:57], 0, v[38:39]
	v_cvt_pk_bf16_f32 v24, v24, v25
	v_cvt_pk_bf16_f32 v25, v26, v27
	global_store_dwordx2 v[34:35], v[24:25], off
	v_mov_b32_e32 v24, v198
	v_mov_b32_e32 v25, v199
	v_mov_b32_e32 v27, v149
	v_bitop3_b32 v26, v48, v49, v184 bitop3:0x36
	v_lshl_add_u64 v[26:27], v[28:29], 0, v[26:27]
	v_lshl_add_u64 v[26:27], v[26:27], 0, v[136:137]
	v_lshlrev_b32_e32 v28, 16, v24
	v_and_b32_e32 v29, 0xffff0000, v24
	v_lshlrev_b32_e32 v24, 16, v25
	v_and_b32_e32 v25, 0xffff0000, v25
	v_pk_fma_f32 v[22:23], v[22:23], v[98:99], v[24:25]
	v_pk_fma_f32 v[20:21], v[20:21], v[96:97], v[28:29]
	v_mov_b32_e32 v25, v149
	v_cvt_pk_bf16_f32 v20, v20, v21
	v_cvt_pk_bf16_f32 v21, v22, v23
	global_store_dwordx2 v[30:31], v[20:21], off
	v_mov_b32_e32 v20, v200
	v_mov_b32_e32 v21, v201
	v_add_u32_e32 v22, 0xb0, v180
	v_lshrrev_b32_e32 v24, 3, v22
	v_lshlrev_b32_e32 v28, 6, v22
	v_lshlrev_b32_e32 v22, 2, v22
	v_and_or_b32 v24, v24, 14, s71
	v_and_b32_e32 v32, 0x3c0, v28
	v_and_b32_e32 v33, 32, v22
	v_mov_b32_e32 v23, v149
	v_lshlrev_b32_e32 v22, 10, v24
	v_or_b32_e32 v34, v33, v32
	v_or_b32_e32 v24, v34, v181
	v_lshl_add_u64 v[28:29], v[68:69], 0, v[22:23]
	v_lshl_add_u64 v[24:25], v[28:29], 0, v[24:25]
	v_lshl_add_u64 v[24:25], v[24:25], 0, v[148:149]
	v_lshlrev_b32_e32 v30, 16, v20
	v_and_b32_e32 v31, 0xffff0000, v20
	v_lshlrev_b32_e32 v20, 16, v21
	v_and_b32_e32 v21, 0xffff0000, v21
	v_pk_fma_f32 v[18:19], v[18:19], v[90:91], v[20:21]
	v_pk_fma_f32 v[16:17], v[16:17], v[88:89], v[30:31]
	s_nop 0
	v_cvt_pk_bf16_f32 v16, v16, v17
	v_cvt_pk_bf16_f32 v17, v18, v19
	global_store_dwordx2 v[26:27], v[16:17], off
	v_or_b32_e32 v202, 32, v181
	v_or_b32_e32 v204, 0x80, v240
	v_ashrrev_i32_e32 v206, 6, v204
	v_ashrrev_i32_e32 v207, 31, v206
	v_lshlrev_b64 v[206:207], 14, v[206:207]
	v_lshlrev_b32_e32 v208, 1, v204
	v_lshl_add_u64 v[206:207], s[10:11], 0, v[206:207]
	v_and_b32_e32 v203, 16, v208
	v_and_b32_e32 v204, 8, v208
	v_mov_b32_e32 v205, v149
	v_or_b32_e32 v210, 0x90, v240
	v_ashrrev_i32_e32 v220, 6, v210
	v_ashrrev_i32_e32 v221, 31, v220
	v_lshlrev_b64 v[220:221], 14, v[220:221]
	v_lshlrev_b32_e32 v222, 1, v210
	v_lshl_add_u64 v[220:221], s[10:11], 0, v[220:221]
	v_and_b32_e32 v224, 48, v222
	v_and_b32_e32 v210, 8, v222
	v_mov_b32_e32 v211, v149
	v_add_u32_e32 v227, 0x80, v180
	v_ashrrev_i32_e32 v226, 7, v227
	v_ashrrev_i32_e32 v227, 31, v226
	v_lshlrev_b64 v[228:229], 19, v[226:227]
	v_lshl_add_u64 v[226:227], v[156:157], 0, v[228:229]
	v_lshl_add_u64 v[230:231], v[206:207], 0, v[228:229]
	v_lshl_add_u64 v[232:233], v[220:221], 0, v[228:229]
	v_mov_b32_e32 v235, v149
	v_add_u32_e32 v208, 0xb0, v180
	v_lshrrev_b32_e32 v234, 3, v208
	v_lshlrev_b32_e32 v222, 6, v208
	v_lshlrev_b32_e32 v208, 2, v208
	v_and_or_b32 v234, v234, 14, s71
	v_and_b32_e32 v206, 0x3c0, v222
	v_and_b32_e32 v207, 32, v208
	v_mov_b32_e32 v209, v149
	v_lshlrev_b32_e32 v208, 10, v234
	v_or_b32_e32 v220, v207, v206
	v_or_b32_e32 v234, v220, v181
	v_lshl_add_u64 v[222:223], v[226:227], 0, v[208:209]
	v_lshl_add_u64 v[234:235], v[222:223], 0, v[234:235]
	v_lshl_add_u64 v[234:235], v[234:235], 0, v[148:149]
	global_load_dwordx2 v[194:195], v[234:235], off
	v_mov_b32_e32 v229, v149
	v_bitop3_b32 v228, v206, v207, v202 bitop3:0x36
	v_lshl_add_u64 v[228:229], v[222:223], 0, v[228:229]
	v_lshl_add_u64 v[228:229], v[228:229], 0, v[148:149]
	v_or_b32_e32 v226, v220, v203
	global_load_dwordx2 v[196:197], v[228:229], off
	v_lshl_add_u64 v[234:235], v[230:231], 0, v[208:209]
	v_mov_b32_e32 v227, v149
	v_lshl_add_u64 v[234:235], v[234:235], 0, v[226:227]
	v_lshl_add_u64 v[234:235], v[234:235], 0, v[204:205]
	v_bitop3_b32 v226, v206, v207, v224 bitop3:0x36
	global_load_dwordx2 v[198:199], v[234:235], off
	v_lshl_add_u64 v[222:223], v[232:233], 0, v[208:209]
	v_lshl_add_u64 v[222:223], v[222:223], 0, v[226:227]
	v_lshl_add_u64 v[222:223], v[222:223], 0, v[210:211]
	global_load_dwordx2 v[200:201], v[222:223], off
	s_waitcnt vmcnt(0)
; __device__ __forceinline__ unsigned pk_bf16(float lo, float hi) { f32x2 v = {lo, hi}; bf16x2_t b = __builtin_convertvector(v, bf16x2_t); return __builtin_bit_cast(unsigned, b); }
; __device__ __forceinline__ f32x4 unpack4(u32x2 w) { return (f32x4){bf_lo(w.x), bf_hi(w.x), bf_lo(w.y), bf_hi(w.y)}; }
;     __device__ __forceinline__ void operator()(const f32x4 (&acc)[2][2][4][2], const Unit& u, int wr, int wc, int fr, int fq) const {
;     ...
;             for (int m = 0; m < 4; ++m) { const int rr = rowl + ai * HALF + m * 16;
; #pragma unroll
;                 for (int bj = 0; bj < 2; ++bj)
; #pragma unroll
;                     for (int n = 0; n < 2; ++n) { const int c = c0 + bj * HALF + n * 16; char* xp = (char*)xr + blk_off(rr, c, DM / 64);
;                         const f32x4 bs = base_f32 ? *(const f32x4*)(base_f32 + (size_t)rr * DM + c) : unpack4(*(const u32x2*)xp);
;                         const f32x4 o = bs + gv[bj][n] * acc[ai][bj][m][n];
;                         u32x2 w; w.x = pk_bf16(o[0], o[1]); w.y = pk_bf16(o[2], o[3]);
;                         *(u32x2*)xp = w; } }
	v_mov_b32_e32 v16, v194
	v_mov_b32_e32 v17, v195
	v_mov_b32_e32 v19, v149
	v_bitop3_b32 v18, v32, v33, v182 bitop3:0x36
	v_lshl_add_u64 v[18:19], v[28:29], 0, v[18:19]
	v_lshl_add_u64 v[18:19], v[18:19], 0, v[148:149]
	v_or_b32_e32 v148, v34, v183
	v_lshlrev_b32_e32 v20, 16, v16
	v_and_b32_e32 v21, 0xffff0000, v16
	v_lshlrev_b32_e32 v16, 16, v17
	v_and_b32_e32 v17, 0xffff0000, v17
	v_pk_fma_f32 v[14:15], v[14:15], v[114:115], v[16:17]
	v_pk_fma_f32 v[12:13], v[12:13], v[112:113], v[20:21]
	s_nop 0
	v_cvt_pk_bf16_f32 v12, v12, v13
	v_cvt_pk_bf16_f32 v13, v14, v15
	global_store_dwordx2 v[24:25], v[12:13], off
	v_mov_b32_e32 v12, v196
	v_mov_b32_e32 v13, v197
	v_lshl_add_u64 v[14:15], v[60:61], 0, v[22:23]
	v_lshl_add_u64 v[14:15], v[14:15], 0, v[148:149]
	v_lshl_add_u64 v[14:15], v[14:15], 0, v[140:141]
	v_bitop3_b32 v148, v32, v33, v184 bitop3:0x36
	v_lshlrev_b32_e32 v16, 16, v12
	v_and_b32_e32 v17, 0xffff0000, v12
	v_lshlrev_b32_e32 v12, 16, v13
	v_and_b32_e32 v13, 0xffff0000, v13
	v_pk_fma_f32 v[10:11], v[10:11], v[110:111], v[12:13]
	v_pk_fma_f32 v[8:9], v[8:9], v[108:109], v[16:17]
	s_nop 0
	v_cvt_pk_bf16_f32 v8, v8, v9
	v_cvt_pk_bf16_f32 v9, v10, v11
	global_store_dwordx2 v[18:19], v[8:9], off
	v_mov_b32_e32 v8, v198
	v_mov_b32_e32 v9, v199
	v_lshl_add_u64 v[10:11], v[56:57], 0, v[22:23]
	v_lshl_add_u64 v[10:11], v[10:11], 0, v[148:149]
	v_lshl_add_u64 v[10:11], v[10:11], 0, v[136:137]
	v_lshlrev_b32_e32 v12, 16, v8
	v_and_b32_e32 v13, 0xffff0000, v8
	v_lshlrev_b32_e32 v8, 16, v9
	v_and_b32_e32 v9, 0xffff0000, v9
	v_pk_fma_f32 v[6:7], v[6:7], v[98:99], v[8:9]
	v_pk_fma_f32 v[4:5], v[4:5], v[96:97], v[12:13]
	s_nop 0
	v_cvt_pk_bf16_f32 v4, v4, v5
	v_cvt_pk_bf16_f32 v5, v6, v7
	global_store_dwordx2 v[14:15], v[4:5], off
	v_mov_b32_e32 v4, v200
	v_mov_b32_e32 v5, v201
	v_lshlrev_b32_e32 v6, 16, v4
	v_and_b32_e32 v7, 0xffff0000, v4
	v_lshlrev_b32_e32 v4, 16, v5
	v_and_b32_e32 v5, 0xffff0000, v5
	v_pk_fma_f32 v[2:3], v[2:3], v[90:91], v[4:5]
	v_pk_fma_f32 v[0:1], v[0:1], v[88:89], v[6:7]
	s_nop 0
	v_cvt_pk_bf16_f32 v0, v0, v1
	v_cvt_pk_bf16_f32 v1, v2, v3
	global_store_dwordx2 v[10:11], v[0:1], off
	s_cbranch_vccnz .LBB0_1697
	s_andn2_b64 vcc, exec, s[14:15]
	s_cbranch_vccnz .LBB0_1696
	s_barrier
	s_branch .LBB0_1696

; __global__ void __launch_bounds__(512, 2) mk_fwd(Args args) {
;     extern __shared__ __attribute__((aligned(16))) unsigned char lds_raw[];
	.amdhsa_kernel _Z6mk_fwd4Args
		.amdhsa_group_segment_fixed_size 0
		.amdhsa_private_segment_fixed_size 0
		.amdhsa_kernarg_size 456
		.amdhsa_user_sgpr_count 2
		.amdhsa_user_sgpr_dispatch_ptr 0
		.amdhsa_user_sgpr_queue_ptr 0
		.amdhsa_user_sgpr_kernarg_segment_ptr 1
		.amdhsa_user_sgpr_dispatch_id 0
		.amdhsa_user_sgpr_kernarg_preload_length 0
		.amdhsa_user_sgpr_kernarg_preload_offset 0
		.amdhsa_user_sgpr_private_segment_size 0
		.amdhsa_uses_dynamic_stack 0
		.amdhsa_enable_private_segment 0
		.amdhsa_system_sgpr_workgroup_id_x 1
		.amdhsa_system_sgpr_workgroup_id_y 0
		.amdhsa_system_sgpr_workgroup_id_z 0
		.amdhsa_system_sgpr_workgroup_info 0
		.amdhsa_system_vgpr_workitem_id 2
		.amdhsa_next_free_vgpr 243
		.amdhsa_next_free_sgpr 102
		.amdhsa_accum_offset 244
		.amdhsa_reserve_vcc 1
		.amdhsa_float_round_mode_32 0
		.amdhsa_float_round_mode_16_64 0
		.amdhsa_float_denorm_mode_32 3
		.amdhsa_float_denorm_mode_16_64 3
		.amdhsa_dx10_clamp 1
		.amdhsa_ieee_mode 1
		.amdhsa_fp16_overflow 0
		.amdhsa_tg_split 0
		.amdhsa_exception_fp_ieee_invalid_op 0
		.amdhsa_exception_fp_denorm_src 0
		.amdhsa_exception_fp_ieee_div_zero 0
		.amdhsa_exception_fp_ieee_overflow 0
		.amdhsa_exception_fp_ieee_underflow 0
		.amdhsa_exception_fp_ieee_inexact 0
		.amdhsa_exception_int_div_zero 0
	.end_amdhsa_kernel

; __global__ void __launch_bounds__(512, 2) mk_fwd(Args args) {
;     extern __shared__ __attribute__((aligned(16))) unsigned char lds_raw[];
amdhsa.kernels:
  - .agpr_count:     0
    .args:
      - .offset:         0
        .size:           200
        .value_kind:     by_value
      - .offset:         200
        .size:           4
        .value_kind:     hidden_block_count_x
      - .offset:         204
        .size:           4
        .value_kind:     hidden_block_count_y
      - .offset:         208
        .size:           4
        .value_kind:     hidden_block_count_z
      - .offset:         212
        .size:           2
        .value_kind:     hidden_group_size_x
      - .offset:         214
        .size:           2
        .value_kind:     hidden_group_size_y
      - .offset:         216
        .size:           2
        .value_kind:     hidden_group_size_z
      - .offset:         218
        .size:           2
        .value_kind:     hidden_remainder_x
      - .offset:         220
        .size:           2
        .value_kind:     hidden_remainder_y
      - .offset:         222
        .size:           2
        .value_kind:     hidden_remainder_z
      - .offset:         240
        .size:           8
        .value_kind:     hidden_global_offset_x
      - .offset:         248
        .size:           8
        .value_kind:     hidden_global_offset_y
      - .offset:         256
        .size:           8
        .value_kind:     hidden_global_offset_z
      - .offset:         264
        .size:           2
        .value_kind:     hidden_grid_dims
      - .offset:         288
        .size:           8
        .value_kind:     hidden_multigrid_sync_arg
      - .offset:         320
        .size:           4
        .value_kind:     hidden_dynamic_lds_size
    .group_segment_fixed_size: 0
    .kernarg_segment_align: 8
    .kernarg_segment_size: 456
    .language:       OpenCL C
    .language_version:
      - 2
      - 0
    .max_flat_workgroup_size: 512
    .name:           _Z6mk_fwd4Args
    .private_segment_fixed_size: 0
    .sgpr_count:     108
    .sgpr_spill_count: 6
    .symbol:         _Z6mk_fwd4Args.kd
    .uniform_work_group_size: 1
    .uses_dynamic_stack: false
    .vgpr_count:     243
    .vgpr_spill_count: 0
    .wavefront_size: 64
